# v26 + combination of individually-neutral edits: w_in permlane reductions, attention hot-path fall-through layout, SWA window staging de-serialised, EpiResid row-group-0 K-loop prefetch
# speedup vs baseline: 1.0053x; 1.0053x over previous
; __device__ __forceinline__ float bflo(unsigned u) { return __uint_as_float(u << 16); }
;     __device__ __forceinline__ void operator()(const f32x4 (&acc)[2][2][4][2], const Unit& u, int wr, int wc, int fr, int fq) const {
;         const int row0 = u.pm * BM + wr * 64 + fr, col0 = u.pn * BM + wc * 32 + 8 * fq;
; #pragma unroll
;         for (int ai = 0; ai < 2; ++ai)
; #pragma unroll
;             for (int m = 0; m < 4; ++m) {
;                 const int row = row0 + ai * HALF + m * 16;
;                 float rs = 0.f; if (GATED) rs = rsqrtf(row_ssq(ssq_in, 16, 4, row, fq) * (1.f / 1024.f) + EPS);
;                 float sq = 0.f;
; #pragma unroll
;                 for (int bj = 0; bj < 2; ++bj) {
;                     const size_t off = (size_t)row * DM + col0 + bj * HALF;
;                     const u32x4 hh = *(const u32x4*)(HI + off), ll = *(const u32x4*)(LO + off);
;                     float hv[8] = {bflo(hh.x) + bflo(ll.x), bfhi(hh.x) + bfhi(ll.x), bflo(hh.y) + bflo(ll.y), bfhi(hh.y) + bfhi(ll.y),
;                                    bflo(hh.z) + bflo(ll.z), bfhi(hh.z) + bfhi(ll.z), bflo(hh.w) + bflo(ll.w), bfhi(hh.w) + bfhi(ll.w)};
;                     float av[8] = {acc[ai][bj][m][0][0], acc[ai][bj][m][0][1], acc[ai][bj][m][0][2], acc[ai][bj][m][0][3], acc[ai][bj][m][1][0], acc[ai][bj][m][1][1], acc[ai][bj][m][1][2], acc[ai][bj][m][1][3]};
;                     if (GATED) { const u32x4 pp = *(const u32x4*)(PP + off);
;                         const float pv[8] = {bflo(pp.x), bfhi(pp.x), bflo(pp.y), bfhi(pp.y), bflo(pp.z), bfhi(pp.z), bflo(pp.w), bfhi(pp.w)};
; #pragma unroll
;                         for (int e = 0; e < 8; ++e) av[e] = fast_sigmoid(av[e] * rs) * pv[e]; }
;                     else {
; #pragma unroll
;                         for (int e = 0; e < 8; ++e) av[e] *= alpha; }
;                     float lo[8];
; #pragma unroll
;                     for (int e = 0; e < 8; ++e) { hv[e] += av[e]; sq += hv[e] * hv[e]; }
;                     u32x4 wh; wh.x = pk2(hv[0], hv[1]); wh.y = pk2(hv[2], hv[3]); wh.z = pk2(hv[4], hv[5]); wh.w = pk2(hv[6], hv[7]);
;                     lo[0] = hv[0] - bflo(wh.x); lo[1] = hv[1] - bfhi(wh.x); lo[2] = hv[2] - bflo(wh.y); lo[3] = hv[3] - bfhi(wh.y);
;                     lo[4] = hv[4] - bflo(wh.z); lo[5] = hv[5] - bfhi(wh.z); lo[6] = hv[6] - bflo(wh.w); lo[7] = hv[7] - bfhi(wh.w);
.LBB0_244:
	v_and_b32_e32 v158, 64, v241
	v_xor_b32_e32 v214, 16, v241
	v_add_u32_e32 v158, 64, v158
	v_cmp_lt_i32_e32 vcc, v214, v158
	v_lshl_add_u32 v156, s31, 8, v160
	v_lshl_or_b32 v157, s4, 8, v162
	v_cndmask_b32_e32 v214, v241, v214, vcc
	v_lshlrev_b32_e32 v214, 2, v214
	v_xor_b32_e32 v215, 32, v241
	v_cmp_lt_i32_e32 vcc, v215, v158
	v_readlane_b32 s6, v250, 49
	v_readlane_b32 s7, v250, 50
	v_readlane_b32 s10, v253, 35
	v_readlane_b32 s11, v253, 36
	s_nop 1
	v_cndmask_b32_e32 v215, v241, v215, vcc
	v_lshlrev_b32_e32 v215, 2, v215
	v_lshl_add_u32 v213, v156, 10, v157
	v_lshlrev_b32_e32 v213, 1, v213
	s_lshl_b32 s40, s4, 4
	s_lshl_b32 s52, s25, 2
	s_add_i32 s40, s40, s52
	v_lshlrev_b32_e32 v216, 6, v156
	v_add_u32_e32 v216, s40, v216
	v_add_u32_e32 v217, 0x2000, v216
	s_nop 1
	v_add_u32_e32 v211, 0x8000, v213
	global_load_dwordx4 v[164:167], v211, s[38:39]
	global_load_dwordx4 v[168:171], v211, s[6:7]
	global_load_dwordx4 v[172:175], v211, s[38:39] offset:256
	global_load_dwordx4 v[176:179], v211, s[6:7] offset:256
	v_add_u32_e32 v212, 0x10000, v213
	global_load_dwordx4 v[180:183], v212, s[38:39]
	global_load_dwordx4 v[184:187], v212, s[6:7]
	global_load_dwordx4 v[188:191], v212, s[38:39] offset:256
	global_load_dwordx4 v[192:195], v212, s[6:7] offset:256
	v_add_u32_e32 v210, 0x18000, v213
	global_load_dwordx4 v[140:143], v210, s[38:39]
	global_load_dwordx4 v[144:147], v210, s[6:7]
	global_load_dwordx4 v[148:151], v210, s[38:39] offset:256
	global_load_dwordx4 v[152:155], v210, s[6:7] offset:256
	s_waitcnt vmcnt(12)
	v_lshlrev_b32_e32 v156, 16, v226
	v_and_b32_e32 v157, 0xffff0000, v226
	v_lshlrev_b32_e32 v158, 16, v230
	v_and_b32_e32 v159, 0xffff0000, v230
	v_pk_add_f32 v[156:157], v[156:157], v[158:159]
	v_pk_fma_f32 v[156:157], v[126:127], 0.5, v[156:157] op_sel_hi:[1,0,1]
	v_cvt_pk_bf16_f32 v226, v156, v157
	v_pk_mul_f32 v[198:199], v[156:157], v[156:157]
	v_lshlrev_b32_e32 v158, 16, v226
	v_and_b32_e32 v159, 0xffff0000, v226
	v_pk_add_f32 v[196:197], v[156:157], v[158:159] neg_lo:[0,1] neg_hi:[0,1]
	v_cvt_pk_bf16_f32 v230, v196, v197
	v_lshlrev_b32_e32 v156, 16, v227
	v_and_b32_e32 v157, 0xffff0000, v227
	v_lshlrev_b32_e32 v158, 16, v231
	v_and_b32_e32 v159, 0xffff0000, v231
	v_pk_add_f32 v[156:157], v[156:157], v[158:159]
	v_pk_fma_f32 v[156:157], v[128:129], 0.5, v[156:157] op_sel_hi:[1,0,1]
	v_cvt_pk_bf16_f32 v227, v156, v157
	v_pk_fma_f32 v[198:199], v[156:157], v[156:157], v[198:199]
	v_lshlrev_b32_e32 v158, 16, v227
	v_and_b32_e32 v159, 0xffff0000, v227
	v_pk_add_f32 v[196:197], v[156:157], v[158:159] neg_lo:[0,1] neg_hi:[0,1]
	v_cvt_pk_bf16_f32 v231, v196, v197
	v_lshlrev_b32_e32 v156, 16, v228
	v_and_b32_e32 v157, 0xffff0000, v228
	v_lshlrev_b32_e32 v158, 16, v232
	v_and_b32_e32 v159, 0xffff0000, v232
	v_pk_add_f32 v[156:157], v[156:157], v[158:159]
	v_pk_fma_f32 v[156:157], v[122:123], 0.5, v[156:157] op_sel_hi:[1,0,1]
	v_cvt_pk_bf16_f32 v228, v156, v157
	v_pk_fma_f32 v[198:199], v[156:157], v[156:157], v[198:199]
	v_lshlrev_b32_e32 v158, 16, v228
	v_and_b32_e32 v159, 0xffff0000, v228
	v_pk_add_f32 v[196:197], v[156:157], v[158:159] neg_lo:[0,1] neg_hi:[0,1]
	v_cvt_pk_bf16_f32 v232, v196, v197
	v_lshlrev_b32_e32 v156, 16, v229
	v_and_b32_e32 v157, 0xffff0000, v229
	v_lshlrev_b32_e32 v158, 16, v233
	v_and_b32_e32 v159, 0xffff0000, v233
	v_pk_add_f32 v[156:157], v[156:157], v[158:159]
	v_pk_fma_f32 v[156:157], v[124:125], 0.5, v[156:157] op_sel_hi:[1,0,1]
	v_cvt_pk_bf16_f32 v229, v156, v157
	v_pk_fma_f32 v[198:199], v[156:157], v[156:157], v[198:199]
	v_lshlrev_b32_e32 v158, 16, v229
	v_and_b32_e32 v159, 0xffff0000, v229
	v_pk_add_f32 v[196:197], v[156:157], v[158:159] neg_lo:[0,1] neg_hi:[0,1]
	v_cvt_pk_bf16_f32 v233, v196, v197
	global_store_dwordx4 v213, v[226:229], s[10:11]
	global_store_dwordx4 v213, v[230:233], s[6:7]
	v_lshlrev_b32_e32 v156, 16, v234
	v_and_b32_e32 v157, 0xffff0000, v234
	v_lshlrev_b32_e32 v158, 16, v242
	v_and_b32_e32 v159, 0xffff0000, v242
	v_pk_add_f32 v[156:157], v[156:157], v[158:159]
	v_pk_fma_f32 v[156:157], v[118:119], 0.5, v[156:157] op_sel_hi:[1,0,1]
	v_cvt_pk_bf16_f32 v234, v156, v157
	v_pk_fma_f32 v[198:199], v[156:157], v[156:157], v[198:199]
	v_lshlrev_b32_e32 v158, 16, v234
	v_and_b32_e32 v159, 0xffff0000, v234
	v_pk_add_f32 v[196:197], v[156:157], v[158:159] neg_lo:[0,1] neg_hi:[0,1]
	v_cvt_pk_bf16_f32 v242, v196, v197
	v_lshlrev_b32_e32 v156, 16, v235
	v_and_b32_e32 v157, 0xffff0000, v235
	v_lshlrev_b32_e32 v158, 16, v243
	v_and_b32_e32 v159, 0xffff0000, v243
	v_pk_add_f32 v[156:157], v[156:157], v[158:159]
	v_pk_fma_f32 v[156:157], v[120:121], 0.5, v[156:157] op_sel_hi:[1,0,1]
	v_cvt_pk_bf16_f32 v235, v156, v157
	v_pk_fma_f32 v[198:199], v[156:157], v[156:157], v[198:199]
	v_lshlrev_b32_e32 v158, 16, v235
	v_and_b32_e32 v159, 0xffff0000, v235
	v_pk_add_f32 v[196:197], v[156:157], v[158:159] neg_lo:[0,1] neg_hi:[0,1]
	v_cvt_pk_bf16_f32 v243, v196, v197
	v_lshlrev_b32_e32 v156, 16, v236
	v_and_b32_e32 v157, 0xffff0000, v236
	v_lshlrev_b32_e32 v158, 16, v244
	v_and_b32_e32 v159, 0xffff0000, v244
	v_pk_add_f32 v[156:157], v[156:157], v[158:159]
	v_pk_fma_f32 v[156:157], v[114:115], 0.5, v[156:157] op_sel_hi:[1,0,1]
	v_cvt_pk_bf16_f32 v236, v156, v157
	v_pk_fma_f32 v[198:199], v[156:157], v[156:157], v[198:199]
	v_lshlrev_b32_e32 v158, 16, v236
	v_and_b32_e32 v159, 0xffff0000, v236
	v_pk_add_f32 v[196:197], v[156:157], v[158:159] neg_lo:[0,1] neg_hi:[0,1]
	v_cvt_pk_bf16_f32 v244, v196, v197
	v_lshlrev_b32_e32 v156, 16, v237
	v_and_b32_e32 v157, 0xffff0000, v237
	v_lshlrev_b32_e32 v158, 16, v245
	v_and_b32_e32 v159, 0xffff0000, v245
	v_pk_add_f32 v[156:157], v[156:157], v[158:159]
	v_pk_fma_f32 v[156:157], v[116:117], 0.5, v[156:157] op_sel_hi:[1,0,1]
	v_cvt_pk_bf16_f32 v237, v156, v157
	v_pk_fma_f32 v[198:199], v[156:157], v[156:157], v[198:199]
	v_lshlrev_b32_e32 v158, 16, v237
	v_and_b32_e32 v159, 0xffff0000, v237
	v_pk_add_f32 v[196:197], v[156:157], v[158:159] neg_lo:[0,1] neg_hi:[0,1]
	v_cvt_pk_bf16_f32 v245, v196, v197
	global_store_dwordx4 v213, v[234:237], s[10:11] offset:256
	global_store_dwordx4 v213, v[242:245], s[6:7] offset:256
	v_add_f32_e32 v200, v198, v199
	s_waitcnt vmcnt(14)
; __device__ __forceinline__ float bflo(unsigned u) { return __uint_as_float(u << 16); }
;     __device__ __forceinline__ void operator()(const f32x4 (&acc)[2][2][4][2], const Unit& u, int wr, int wc, int fr, int fq) const {
;     ...
;                 const int row = row0 + ai * HALF + m * 16;
;                 float rs = 0.f; if (GATED) rs = rsqrtf(row_ssq(ssq_in, 16, 4, row, fq) * (1.f / 1024.f) + EPS);
;                 float sq = 0.f;
; #pragma unroll
;                 for (int bj = 0; bj < 2; ++bj) {
;                     const size_t off = (size_t)row * DM + col0 + bj * HALF;
;                     const u32x4 hh = *(const u32x4*)(HI + off), ll = *(const u32x4*)(LO + off);
;                     float hv[8] = {bflo(hh.x) + bflo(ll.x), bfhi(hh.x) + bfhi(ll.x), bflo(hh.y) + bflo(ll.y), bfhi(hh.y) + bfhi(ll.y),
;                                    bflo(hh.z) + bflo(ll.z), bfhi(hh.z) + bfhi(ll.z), bflo(hh.w) + bflo(ll.w), bfhi(hh.w) + bfhi(ll.w)};
;                     float av[8] = {acc[ai][bj][m][0][0], acc[ai][bj][m][0][1], acc[ai][bj][m][0][2], acc[ai][bj][m][0][3], acc[ai][bj][m][1][0], acc[ai][bj][m][1][1], acc[ai][bj][m][1][2], acc[ai][bj][m][1][3]};
;                     if (GATED) { const u32x4 pp = *(const u32x4*)(PP + off);
;                         const float pv[8] = {bflo(pp.x), bfhi(pp.x), bflo(pp.y), bfhi(pp.y), bflo(pp.z), bfhi(pp.z), bflo(pp.w), bfhi(pp.w)};
; #pragma unroll
;                         for (int e = 0; e < 8; ++e) av[e] = fast_sigmoid(av[e] * rs) * pv[e]; }
;                     else {
; #pragma unroll
;                         for (int e = 0; e < 8; ++e) av[e] *= alpha; }
;                     float lo[8];
; #pragma unroll
;                     for (int e = 0; e < 8; ++e) { hv[e] += av[e]; sq += hv[e] * hv[e]; }
;                     u32x4 wh; wh.x = pk2(hv[0], hv[1]); wh.y = pk2(hv[2], hv[3]); wh.z = pk2(hv[4], hv[5]); wh.w = pk2(hv[6], hv[7]);
;                     lo[0] = hv[0] - bflo(wh.x); lo[1] = hv[1] - bfhi(wh.x); lo[2] = hv[2] - bflo(wh.y); lo[3] = hv[3] - bfhi(wh.y);
;                     lo[4] = hv[4] - bflo(wh.z); lo[5] = hv[5] - bfhi(wh.z); lo[6] = hv[6] - bflo(wh.w); lo[7] = hv[7] - bfhi(wh.w);
;                     u32x4 wl; wl.x = pk2(lo[0], lo[1]); wl.y = pk2(lo[2], lo[3]); wl.z = pk2(lo[4], lo[5]); wl.w = pk2(lo[6], lo[7]);
;                     *(u32x4*)(HO + off) = wh; *(u32x4*)(LO + off) = wl;
	v_lshlrev_b32_e32 v156, 16, v164
	v_and_b32_e32 v157, 0xffff0000, v164
	v_lshlrev_b32_e32 v158, 16, v168
	v_and_b32_e32 v159, 0xffff0000, v168
	v_pk_add_f32 v[156:157], v[156:157], v[158:159]
	v_pk_fma_f32 v[156:157], v[110:111], 0.5, v[156:157] op_sel_hi:[1,0,1]
	v_cvt_pk_bf16_f32 v164, v156, v157
	v_pk_mul_f32 v[198:199], v[156:157], v[156:157]
	v_lshlrev_b32_e32 v158, 16, v164
	v_and_b32_e32 v159, 0xffff0000, v164
	v_pk_add_f32 v[196:197], v[156:157], v[158:159] neg_lo:[0,1] neg_hi:[0,1]
	v_cvt_pk_bf16_f32 v168, v196, v197
	v_lshlrev_b32_e32 v156, 16, v165
	v_and_b32_e32 v157, 0xffff0000, v165
	v_lshlrev_b32_e32 v158, 16, v169
	v_and_b32_e32 v159, 0xffff0000, v169
	v_pk_add_f32 v[156:157], v[156:157], v[158:159]
	v_pk_fma_f32 v[156:157], v[112:113], 0.5, v[156:157] op_sel_hi:[1,0,1]
	v_cvt_pk_bf16_f32 v165, v156, v157
	v_pk_fma_f32 v[198:199], v[156:157], v[156:157], v[198:199]
	v_lshlrev_b32_e32 v158, 16, v165
	v_and_b32_e32 v159, 0xffff0000, v165
	v_pk_add_f32 v[196:197], v[156:157], v[158:159] neg_lo:[0,1] neg_hi:[0,1]
	v_cvt_pk_bf16_f32 v169, v196, v197
	v_lshlrev_b32_e32 v156, 16, v166
	v_and_b32_e32 v157, 0xffff0000, v166
	v_lshlrev_b32_e32 v158, 16, v170
	v_and_b32_e32 v159, 0xffff0000, v170
	v_pk_add_f32 v[156:157], v[156:157], v[158:159]
	v_pk_fma_f32 v[156:157], v[106:107], 0.5, v[156:157] op_sel_hi:[1,0,1]
	v_cvt_pk_bf16_f32 v166, v156, v157
	v_pk_fma_f32 v[198:199], v[156:157], v[156:157], v[198:199]
	v_lshlrev_b32_e32 v158, 16, v166
	v_and_b32_e32 v159, 0xffff0000, v166
	v_pk_add_f32 v[196:197], v[156:157], v[158:159] neg_lo:[0,1] neg_hi:[0,1]
	v_cvt_pk_bf16_f32 v170, v196, v197
	v_lshlrev_b32_e32 v156, 16, v167
	v_and_b32_e32 v157, 0xffff0000, v167
	v_lshlrev_b32_e32 v158, 16, v171
	v_and_b32_e32 v159, 0xffff0000, v171
	v_pk_add_f32 v[156:157], v[156:157], v[158:159]
	v_pk_fma_f32 v[156:157], v[108:109], 0.5, v[156:157] op_sel_hi:[1,0,1]
	v_cvt_pk_bf16_f32 v167, v156, v157
	v_pk_fma_f32 v[198:199], v[156:157], v[156:157], v[198:199]
	v_lshlrev_b32_e32 v158, 16, v167
	v_and_b32_e32 v159, 0xffff0000, v167
	v_pk_add_f32 v[196:197], v[156:157], v[158:159] neg_lo:[0,1] neg_hi:[0,1]
	v_cvt_pk_bf16_f32 v171, v196, v197
	global_store_dwordx4 v211, v[164:167], s[10:11]
	global_store_dwordx4 v211, v[168:171], s[6:7]
	s_waitcnt vmcnt(14)
	v_lshlrev_b32_e32 v156, 16, v172
	v_and_b32_e32 v157, 0xffff0000, v172
	v_lshlrev_b32_e32 v158, 16, v176
	v_and_b32_e32 v159, 0xffff0000, v176
	v_pk_add_f32 v[156:157], v[156:157], v[158:159]
	v_pk_fma_f32 v[156:157], v[102:103], 0.5, v[156:157] op_sel_hi:[1,0,1]
	v_cvt_pk_bf16_f32 v172, v156, v157
	v_pk_fma_f32 v[198:199], v[156:157], v[156:157], v[198:199]
	v_lshlrev_b32_e32 v158, 16, v172
	v_and_b32_e32 v159, 0xffff0000, v172
	v_pk_add_f32 v[196:197], v[156:157], v[158:159] neg_lo:[0,1] neg_hi:[0,1]
	v_cvt_pk_bf16_f32 v176, v196, v197
	v_lshlrev_b32_e32 v156, 16, v173
	v_and_b32_e32 v157, 0xffff0000, v173
	v_lshlrev_b32_e32 v158, 16, v177
	v_and_b32_e32 v159, 0xffff0000, v177
	v_pk_add_f32 v[156:157], v[156:157], v[158:159]
	v_pk_fma_f32 v[156:157], v[104:105], 0.5, v[156:157] op_sel_hi:[1,0,1]
	v_cvt_pk_bf16_f32 v173, v156, v157
	v_pk_fma_f32 v[198:199], v[156:157], v[156:157], v[198:199]
	v_lshlrev_b32_e32 v158, 16, v173
	v_and_b32_e32 v159, 0xffff0000, v173
	v_pk_add_f32 v[196:197], v[156:157], v[158:159] neg_lo:[0,1] neg_hi:[0,1]
	v_cvt_pk_bf16_f32 v177, v196, v197
	v_lshlrev_b32_e32 v156, 16, v174
	v_and_b32_e32 v157, 0xffff0000, v174
	v_lshlrev_b32_e32 v158, 16, v178
	v_and_b32_e32 v159, 0xffff0000, v178
	v_pk_add_f32 v[156:157], v[156:157], v[158:159]
	v_pk_fma_f32 v[156:157], v[98:99], 0.5, v[156:157] op_sel_hi:[1,0,1]
	v_cvt_pk_bf16_f32 v174, v156, v157
	v_pk_fma_f32 v[198:199], v[156:157], v[156:157], v[198:199]
	v_lshlrev_b32_e32 v158, 16, v174
	v_and_b32_e32 v159, 0xffff0000, v174
	v_pk_add_f32 v[196:197], v[156:157], v[158:159] neg_lo:[0,1] neg_hi:[0,1]
	v_cvt_pk_bf16_f32 v178, v196, v197
	v_lshlrev_b32_e32 v156, 16, v175
	v_and_b32_e32 v157, 0xffff0000, v175
	v_lshlrev_b32_e32 v158, 16, v179
	v_and_b32_e32 v159, 0xffff0000, v179
	v_pk_add_f32 v[156:157], v[156:157], v[158:159]
	v_pk_fma_f32 v[156:157], v[100:101], 0.5, v[156:157] op_sel_hi:[1,0,1]
	v_cvt_pk_bf16_f32 v175, v156, v157
	v_pk_fma_f32 v[198:199], v[156:157], v[156:157], v[198:199]
	v_lshlrev_b32_e32 v158, 16, v175
	v_and_b32_e32 v159, 0xffff0000, v175
	v_pk_add_f32 v[196:197], v[156:157], v[158:159] neg_lo:[0,1] neg_hi:[0,1]
	v_cvt_pk_bf16_f32 v179, v196, v197
	global_store_dwordx4 v211, v[172:175], s[10:11] offset:256
	global_store_dwordx4 v211, v[176:179], s[6:7] offset:256
	v_add_f32_e32 v201, v198, v199
	s_nop 0
	v_add_u32_e32 v211, 0x40000, v213
	global_load_dwordx4 v[164:167], v211, s[38:39]
	global_load_dwordx4 v[168:171], v211, s[6:7]
	global_load_dwordx4 v[172:175], v211, s[38:39] offset:256
	global_load_dwordx4 v[176:179], v211, s[6:7] offset:256
	s_waitcnt vmcnt(18)
; __device__ __forceinline__ float bflo(unsigned u) { return __uint_as_float(u << 16); }
;     __device__ __forceinline__ void operator()(const f32x4 (&acc)[2][2][4][2], const Unit& u, int wr, int wc, int fr, int fq) const {
;     ...
;                 const int row = row0 + ai * HALF + m * 16;
;                 float rs = 0.f; if (GATED) rs = rsqrtf(row_ssq(ssq_in, 16, 4, row, fq) * (1.f / 1024.f) + EPS);
;                 float sq = 0.f;
; #pragma unroll
;                 for (int bj = 0; bj < 2; ++bj) {
;                     const size_t off = (size_t)row * DM + col0 + bj * HALF;
;                     const u32x4 hh = *(const u32x4*)(HI + off), ll = *(const u32x4*)(LO + off);
;                     float hv[8] = {bflo(hh.x) + bflo(ll.x), bfhi(hh.x) + bfhi(ll.x), bflo(hh.y) + bflo(ll.y), bfhi(hh.y) + bfhi(ll.y),
;                                    bflo(hh.z) + bflo(ll.z), bfhi(hh.z) + bfhi(ll.z), bflo(hh.w) + bflo(ll.w), bfhi(hh.w) + bfhi(ll.w)};
;                     float av[8] = {acc[ai][bj][m][0][0], acc[ai][bj][m][0][1], acc[ai][bj][m][0][2], acc[ai][bj][m][0][3], acc[ai][bj][m][1][0], acc[ai][bj][m][1][1], acc[ai][bj][m][1][2], acc[ai][bj][m][1][3]};
;                     if (GATED) { const u32x4 pp = *(const u32x4*)(PP + off);
;                         const float pv[8] = {bflo(pp.x), bfhi(pp.x), bflo(pp.y), bfhi(pp.y), bflo(pp.z), bfhi(pp.z), bflo(pp.w), bfhi(pp.w)};
; #pragma unroll
;                         for (int e = 0; e < 8; ++e) av[e] = fast_sigmoid(av[e] * rs) * pv[e]; }
;                     else {
; #pragma unroll
;                         for (int e = 0; e < 8; ++e) av[e] *= alpha; }
;                     float lo[8];
; #pragma unroll
;                     for (int e = 0; e < 8; ++e) { hv[e] += av[e]; sq += hv[e] * hv[e]; }
;                     u32x4 wh; wh.x = pk2(hv[0], hv[1]); wh.y = pk2(hv[2], hv[3]); wh.z = pk2(hv[4], hv[5]); wh.w = pk2(hv[6], hv[7]);
;                     lo[0] = hv[0] - bflo(wh.x); lo[1] = hv[1] - bfhi(wh.x); lo[2] = hv[2] - bflo(wh.y); lo[3] = hv[3] - bfhi(wh.y);
;                     lo[4] = hv[4] - bflo(wh.z); lo[5] = hv[5] - bfhi(wh.z); lo[6] = hv[6] - bflo(wh.w); lo[7] = hv[7] - bfhi(wh.w);
;                     u32x4 wl; wl.x = pk2(lo[0], lo[1]); wl.y = pk2(lo[2], lo[3]); wl.z = pk2(lo[4], lo[5]); wl.w = pk2(lo[6], lo[7]);
;                     *(u32x4*)(HO + off) = wh; *(u32x4*)(LO + off) = wl;
	v_lshlrev_b32_e32 v156, 16, v180
	v_and_b32_e32 v157, 0xffff0000, v180
	v_lshlrev_b32_e32 v158, 16, v184
	v_and_b32_e32 v159, 0xffff0000, v184
	v_pk_add_f32 v[156:157], v[156:157], v[158:159]
	v_pk_fma_f32 v[156:157], v[94:95], 0.5, v[156:157] op_sel_hi:[1,0,1]
	v_cvt_pk_bf16_f32 v180, v156, v157
	v_pk_mul_f32 v[198:199], v[156:157], v[156:157]
	v_lshlrev_b32_e32 v158, 16, v180
	v_and_b32_e32 v159, 0xffff0000, v180
	v_pk_add_f32 v[196:197], v[156:157], v[158:159] neg_lo:[0,1] neg_hi:[0,1]
	v_cvt_pk_bf16_f32 v184, v196, v197
	v_lshlrev_b32_e32 v156, 16, v181
	v_and_b32_e32 v157, 0xffff0000, v181
	v_lshlrev_b32_e32 v158, 16, v185
	v_and_b32_e32 v159, 0xffff0000, v185
	v_pk_add_f32 v[156:157], v[156:157], v[158:159]
	v_pk_fma_f32 v[156:157], v[96:97], 0.5, v[156:157] op_sel_hi:[1,0,1]
	v_cvt_pk_bf16_f32 v181, v156, v157
	v_pk_fma_f32 v[198:199], v[156:157], v[156:157], v[198:199]
	v_lshlrev_b32_e32 v158, 16, v181
	v_and_b32_e32 v159, 0xffff0000, v181
	v_pk_add_f32 v[196:197], v[156:157], v[158:159] neg_lo:[0,1] neg_hi:[0,1]
	v_cvt_pk_bf16_f32 v185, v196, v197
	v_lshlrev_b32_e32 v156, 16, v182
	v_and_b32_e32 v157, 0xffff0000, v182
	v_lshlrev_b32_e32 v158, 16, v186
	v_and_b32_e32 v159, 0xffff0000, v186
	v_pk_add_f32 v[156:157], v[156:157], v[158:159]
	v_pk_fma_f32 v[156:157], v[90:91], 0.5, v[156:157] op_sel_hi:[1,0,1]
	v_cvt_pk_bf16_f32 v182, v156, v157
	v_pk_fma_f32 v[198:199], v[156:157], v[156:157], v[198:199]
	v_lshlrev_b32_e32 v158, 16, v182
	v_and_b32_e32 v159, 0xffff0000, v182
	v_pk_add_f32 v[196:197], v[156:157], v[158:159] neg_lo:[0,1] neg_hi:[0,1]
	v_cvt_pk_bf16_f32 v186, v196, v197
	v_lshlrev_b32_e32 v156, 16, v183
	v_and_b32_e32 v157, 0xffff0000, v183
	v_lshlrev_b32_e32 v158, 16, v187
	v_and_b32_e32 v159, 0xffff0000, v187
	v_pk_add_f32 v[156:157], v[156:157], v[158:159]
	v_pk_fma_f32 v[156:157], v[92:93], 0.5, v[156:157] op_sel_hi:[1,0,1]
	v_cvt_pk_bf16_f32 v183, v156, v157
	v_pk_fma_f32 v[198:199], v[156:157], v[156:157], v[198:199]
	v_lshlrev_b32_e32 v158, 16, v183
	v_and_b32_e32 v159, 0xffff0000, v183
	v_pk_add_f32 v[196:197], v[156:157], v[158:159] neg_lo:[0,1] neg_hi:[0,1]
	v_cvt_pk_bf16_f32 v187, v196, v197
	global_store_dwordx4 v212, v[180:183], s[10:11]
	global_store_dwordx4 v212, v[184:187], s[6:7]
	s_waitcnt vmcnt(18)
	v_lshlrev_b32_e32 v156, 16, v188
	v_and_b32_e32 v157, 0xffff0000, v188
	v_lshlrev_b32_e32 v158, 16, v192
	v_and_b32_e32 v159, 0xffff0000, v192
	v_pk_add_f32 v[156:157], v[156:157], v[158:159]
	v_pk_fma_f32 v[156:157], v[86:87], 0.5, v[156:157] op_sel_hi:[1,0,1]
	v_cvt_pk_bf16_f32 v188, v156, v157
	v_pk_fma_f32 v[198:199], v[156:157], v[156:157], v[198:199]
	v_lshlrev_b32_e32 v158, 16, v188
	v_and_b32_e32 v159, 0xffff0000, v188
	v_pk_add_f32 v[196:197], v[156:157], v[158:159] neg_lo:[0,1] neg_hi:[0,1]
	v_cvt_pk_bf16_f32 v192, v196, v197
	v_lshlrev_b32_e32 v156, 16, v189
	v_and_b32_e32 v157, 0xffff0000, v189
	v_lshlrev_b32_e32 v158, 16, v193
	v_and_b32_e32 v159, 0xffff0000, v193
	v_pk_add_f32 v[156:157], v[156:157], v[158:159]
	v_pk_fma_f32 v[156:157], v[88:89], 0.5, v[156:157] op_sel_hi:[1,0,1]
	v_cvt_pk_bf16_f32 v189, v156, v157
	v_pk_fma_f32 v[198:199], v[156:157], v[156:157], v[198:199]
	v_lshlrev_b32_e32 v158, 16, v189
	v_and_b32_e32 v159, 0xffff0000, v189
	v_pk_add_f32 v[196:197], v[156:157], v[158:159] neg_lo:[0,1] neg_hi:[0,1]
	v_cvt_pk_bf16_f32 v193, v196, v197
	v_lshlrev_b32_e32 v156, 16, v190
	v_and_b32_e32 v157, 0xffff0000, v190
	v_lshlrev_b32_e32 v158, 16, v194
	v_and_b32_e32 v159, 0xffff0000, v194
	v_pk_add_f32 v[156:157], v[156:157], v[158:159]
	v_pk_fma_f32 v[156:157], v[82:83], 0.5, v[156:157] op_sel_hi:[1,0,1]
	v_cvt_pk_bf16_f32 v190, v156, v157
	v_pk_fma_f32 v[198:199], v[156:157], v[156:157], v[198:199]
	v_lshlrev_b32_e32 v158, 16, v190
	v_and_b32_e32 v159, 0xffff0000, v190
	v_pk_add_f32 v[196:197], v[156:157], v[158:159] neg_lo:[0,1] neg_hi:[0,1]
	v_cvt_pk_bf16_f32 v194, v196, v197
	v_lshlrev_b32_e32 v156, 16, v191
	v_and_b32_e32 v157, 0xffff0000, v191
	v_lshlrev_b32_e32 v158, 16, v195
	v_and_b32_e32 v159, 0xffff0000, v195
	v_pk_add_f32 v[156:157], v[156:157], v[158:159]
	v_pk_fma_f32 v[156:157], v[84:85], 0.5, v[156:157] op_sel_hi:[1,0,1]
	v_cvt_pk_bf16_f32 v191, v156, v157
	v_pk_fma_f32 v[198:199], v[156:157], v[156:157], v[198:199]
	v_lshlrev_b32_e32 v158, 16, v191
	v_and_b32_e32 v159, 0xffff0000, v191
	v_pk_add_f32 v[196:197], v[156:157], v[158:159] neg_lo:[0,1] neg_hi:[0,1]
	v_cvt_pk_bf16_f32 v195, v196, v197
	global_store_dwordx4 v212, v[188:191], s[10:11] offset:256
	global_store_dwordx4 v212, v[192:195], s[6:7] offset:256
	v_add_f32_e32 v202, v198, v199
	s_nop 0
	v_add_u32_e32 v212, 0x48000, v213
	global_load_dwordx4 v[180:183], v212, s[38:39]
	global_load_dwordx4 v[184:187], v212, s[6:7]
	global_load_dwordx4 v[188:191], v212, s[38:39] offset:256
	global_load_dwordx4 v[192:195], v212, s[6:7] offset:256
	s_waitcnt vmcnt(22)
; __device__ __forceinline__ float bflo(unsigned u) { return __uint_as_float(u << 16); }
;     __device__ __forceinline__ void operator()(const f32x4 (&acc)[2][2][4][2], const Unit& u, int wr, int wc, int fr, int fq) const {
;     ...
;                 const int row = row0 + ai * HALF + m * 16;
;                 float rs = 0.f; if (GATED) rs = rsqrtf(row_ssq(ssq_in, 16, 4, row, fq) * (1.f / 1024.f) + EPS);
;                 float sq = 0.f;
; #pragma unroll
;                 for (int bj = 0; bj < 2; ++bj) {
;                     const size_t off = (size_t)row * DM + col0 + bj * HALF;
;                     const u32x4 hh = *(const u32x4*)(HI + off), ll = *(const u32x4*)(LO + off);
;                     float hv[8] = {bflo(hh.x) + bflo(ll.x), bfhi(hh.x) + bfhi(ll.x), bflo(hh.y) + bflo(ll.y), bfhi(hh.y) + bfhi(ll.y),
;                                    bflo(hh.z) + bflo(ll.z), bfhi(hh.z) + bfhi(ll.z), bflo(hh.w) + bflo(ll.w), bfhi(hh.w) + bfhi(ll.w)};
;                     float av[8] = {acc[ai][bj][m][0][0], acc[ai][bj][m][0][1], acc[ai][bj][m][0][2], acc[ai][bj][m][0][3], acc[ai][bj][m][1][0], acc[ai][bj][m][1][1], acc[ai][bj][m][1][2], acc[ai][bj][m][1][3]};
;                     if (GATED) { const u32x4 pp = *(const u32x4*)(PP + off);
;                         const float pv[8] = {bflo(pp.x), bfhi(pp.x), bflo(pp.y), bfhi(pp.y), bflo(pp.z), bfhi(pp.z), bflo(pp.w), bfhi(pp.w)};
; #pragma unroll
;                         for (int e = 0; e < 8; ++e) av[e] = fast_sigmoid(av[e] * rs) * pv[e]; }
;                     else {
; #pragma unroll
;                         for (int e = 0; e < 8; ++e) av[e] *= alpha; }
;                     float lo[8];
; #pragma unroll
;                     for (int e = 0; e < 8; ++e) { hv[e] += av[e]; sq += hv[e] * hv[e]; }
;                     u32x4 wh; wh.x = pk2(hv[0], hv[1]); wh.y = pk2(hv[2], hv[3]); wh.z = pk2(hv[4], hv[5]); wh.w = pk2(hv[6], hv[7]);
;                     lo[0] = hv[0] - bflo(wh.x); lo[1] = hv[1] - bfhi(wh.x); lo[2] = hv[2] - bflo(wh.y); lo[3] = hv[3] - bfhi(wh.y);
;                     lo[4] = hv[4] - bflo(wh.z); lo[5] = hv[5] - bfhi(wh.z); lo[6] = hv[6] - bflo(wh.w); lo[7] = hv[7] - bfhi(wh.w);
;                     u32x4 wl; wl.x = pk2(lo[0], lo[1]); wl.y = pk2(lo[2], lo[3]); wl.z = pk2(lo[4], lo[5]); wl.w = pk2(lo[6], lo[7]);
;                     *(u32x4*)(HO + off) = wh; *(u32x4*)(LO + off) = wl;
	v_lshlrev_b32_e32 v156, 16, v140
	v_and_b32_e32 v157, 0xffff0000, v140
	v_lshlrev_b32_e32 v158, 16, v144
	v_and_b32_e32 v159, 0xffff0000, v144
	v_pk_add_f32 v[156:157], v[156:157], v[158:159]
	v_pk_fma_f32 v[156:157], v[78:79], 0.5, v[156:157] op_sel_hi:[1,0,1]
	v_cvt_pk_bf16_f32 v140, v156, v157
	v_pk_mul_f32 v[198:199], v[156:157], v[156:157]
	v_lshlrev_b32_e32 v158, 16, v140
	v_and_b32_e32 v159, 0xffff0000, v140
	v_pk_add_f32 v[196:197], v[156:157], v[158:159] neg_lo:[0,1] neg_hi:[0,1]
	v_cvt_pk_bf16_f32 v144, v196, v197
	v_lshlrev_b32_e32 v156, 16, v141
	v_and_b32_e32 v157, 0xffff0000, v141
	v_lshlrev_b32_e32 v158, 16, v145
	v_and_b32_e32 v159, 0xffff0000, v145
	v_pk_add_f32 v[156:157], v[156:157], v[158:159]
	v_pk_fma_f32 v[156:157], v[80:81], 0.5, v[156:157] op_sel_hi:[1,0,1]
	v_cvt_pk_bf16_f32 v141, v156, v157
	v_pk_fma_f32 v[198:199], v[156:157], v[156:157], v[198:199]
	v_lshlrev_b32_e32 v158, 16, v141
	v_and_b32_e32 v159, 0xffff0000, v141
	v_pk_add_f32 v[196:197], v[156:157], v[158:159] neg_lo:[0,1] neg_hi:[0,1]
	v_cvt_pk_bf16_f32 v145, v196, v197
	v_lshlrev_b32_e32 v156, 16, v142
	v_and_b32_e32 v157, 0xffff0000, v142
	v_lshlrev_b32_e32 v158, 16, v146
	v_and_b32_e32 v159, 0xffff0000, v146
	v_pk_add_f32 v[156:157], v[156:157], v[158:159]
	v_pk_fma_f32 v[156:157], v[74:75], 0.5, v[156:157] op_sel_hi:[1,0,1]
	v_cvt_pk_bf16_f32 v142, v156, v157
	v_pk_fma_f32 v[198:199], v[156:157], v[156:157], v[198:199]
	v_lshlrev_b32_e32 v158, 16, v142
	v_and_b32_e32 v159, 0xffff0000, v142
	v_pk_add_f32 v[196:197], v[156:157], v[158:159] neg_lo:[0,1] neg_hi:[0,1]
	v_cvt_pk_bf16_f32 v146, v196, v197
	v_lshlrev_b32_e32 v156, 16, v143
	v_and_b32_e32 v157, 0xffff0000, v143
	v_lshlrev_b32_e32 v158, 16, v147
	v_and_b32_e32 v159, 0xffff0000, v147
	v_pk_add_f32 v[156:157], v[156:157], v[158:159]
	v_pk_fma_f32 v[156:157], v[76:77], 0.5, v[156:157] op_sel_hi:[1,0,1]
	v_cvt_pk_bf16_f32 v143, v156, v157
	v_pk_fma_f32 v[198:199], v[156:157], v[156:157], v[198:199]
	v_lshlrev_b32_e32 v158, 16, v143
	v_and_b32_e32 v159, 0xffff0000, v143
	v_pk_add_f32 v[196:197], v[156:157], v[158:159] neg_lo:[0,1] neg_hi:[0,1]
	v_cvt_pk_bf16_f32 v147, v196, v197
	global_store_dwordx4 v210, v[140:143], s[10:11]
	global_store_dwordx4 v210, v[144:147], s[6:7]
	s_waitcnt vmcnt(22)
	v_lshlrev_b32_e32 v156, 16, v148
	v_and_b32_e32 v157, 0xffff0000, v148
	v_lshlrev_b32_e32 v158, 16, v152
	v_and_b32_e32 v159, 0xffff0000, v152
	v_pk_add_f32 v[156:157], v[156:157], v[158:159]
	v_pk_fma_f32 v[156:157], v[70:71], 0.5, v[156:157] op_sel_hi:[1,0,1]
	v_cvt_pk_bf16_f32 v148, v156, v157
	v_pk_fma_f32 v[198:199], v[156:157], v[156:157], v[198:199]
	v_lshlrev_b32_e32 v158, 16, v148
	v_and_b32_e32 v159, 0xffff0000, v148
	v_pk_add_f32 v[196:197], v[156:157], v[158:159] neg_lo:[0,1] neg_hi:[0,1]
	v_cvt_pk_bf16_f32 v152, v196, v197
	v_lshlrev_b32_e32 v156, 16, v149
	v_and_b32_e32 v157, 0xffff0000, v149
	v_lshlrev_b32_e32 v158, 16, v153
	v_and_b32_e32 v159, 0xffff0000, v153
	v_pk_add_f32 v[156:157], v[156:157], v[158:159]
	v_pk_fma_f32 v[156:157], v[72:73], 0.5, v[156:157] op_sel_hi:[1,0,1]
	v_cvt_pk_bf16_f32 v149, v156, v157
	v_pk_fma_f32 v[198:199], v[156:157], v[156:157], v[198:199]
	v_lshlrev_b32_e32 v158, 16, v149
	v_and_b32_e32 v159, 0xffff0000, v149
	v_pk_add_f32 v[196:197], v[156:157], v[158:159] neg_lo:[0,1] neg_hi:[0,1]
	v_cvt_pk_bf16_f32 v153, v196, v197
	v_lshlrev_b32_e32 v156, 16, v150
	v_and_b32_e32 v157, 0xffff0000, v150
	v_lshlrev_b32_e32 v158, 16, v154
	v_and_b32_e32 v159, 0xffff0000, v154
	v_pk_add_f32 v[156:157], v[156:157], v[158:159]
	v_pk_fma_f32 v[156:157], v[66:67], 0.5, v[156:157] op_sel_hi:[1,0,1]
	v_cvt_pk_bf16_f32 v150, v156, v157
	v_pk_fma_f32 v[198:199], v[156:157], v[156:157], v[198:199]
	v_lshlrev_b32_e32 v158, 16, v150
	v_and_b32_e32 v159, 0xffff0000, v150
	v_pk_add_f32 v[196:197], v[156:157], v[158:159] neg_lo:[0,1] neg_hi:[0,1]
	v_cvt_pk_bf16_f32 v154, v196, v197
	v_lshlrev_b32_e32 v156, 16, v151
	v_and_b32_e32 v157, 0xffff0000, v151
	v_lshlrev_b32_e32 v158, 16, v155
	v_and_b32_e32 v159, 0xffff0000, v155
	v_pk_add_f32 v[156:157], v[156:157], v[158:159]
	v_pk_fma_f32 v[156:157], v[68:69], 0.5, v[156:157] op_sel_hi:[1,0,1]
	v_cvt_pk_bf16_f32 v151, v156, v157
	v_pk_fma_f32 v[198:199], v[156:157], v[156:157], v[198:199]
	v_lshlrev_b32_e32 v158, 16, v151
	v_and_b32_e32 v159, 0xffff0000, v151
	v_pk_add_f32 v[196:197], v[156:157], v[158:159] neg_lo:[0,1] neg_hi:[0,1]
	v_cvt_pk_bf16_f32 v155, v196, v197
	global_store_dwordx4 v210, v[148:151], s[10:11] offset:256
	global_store_dwordx4 v210, v[152:155], s[6:7] offset:256
	v_add_f32_e32 v203, v198, v199
	s_nop 0
	v_add_u32_e32 v210, 0x50000, v213
	global_load_dwordx4 v[140:143], v210, s[38:39]
	global_load_dwordx4 v[144:147], v210, s[6:7]
	global_load_dwordx4 v[148:151], v210, s[38:39] offset:256
	global_load_dwordx4 v[152:155], v210, s[6:7] offset:256
	s_waitcnt vmcnt(18)
; __device__ __forceinline__ unsigned pk2(float lo, float hi) { f32x2_t v = {lo, hi}; bf16x2_t b = __builtin_convertvector(v, bf16x2_t); return __builtin_bit_cast(unsigned, b); }
; __device__ __forceinline__ float bflo(unsigned u) { return __uint_as_float(u << 16); }
;     __device__ __forceinline__ void operator()(const f32x4 (&acc)[2][2][4][2], const Unit& u, int wr, int wc, int fr, int fq) const {
;     ...
;                 for (int bj = 0; bj < 2; ++bj) {
;                     const size_t off = (size_t)row * DM + col0 + bj * HALF;
;                     const u32x4 hh = *(const u32x4*)(HI + off), ll = *(const u32x4*)(LO + off);
;                     float hv[8] = {bflo(hh.x) + bflo(ll.x), bfhi(hh.x) + bfhi(ll.x), bflo(hh.y) + bflo(ll.y), bfhi(hh.y) + bfhi(ll.y),
;                                    bflo(hh.z) + bflo(ll.z), bfhi(hh.z) + bfhi(ll.z), bflo(hh.w) + bflo(ll.w), bfhi(hh.w) + bfhi(ll.w)};
;                     float av[8] = {acc[ai][bj][m][0][0], acc[ai][bj][m][0][1], acc[ai][bj][m][0][2], acc[ai][bj][m][0][3], acc[ai][bj][m][1][0], acc[ai][bj][m][1][1], acc[ai][bj][m][1][2], acc[ai][bj][m][1][3]};
;                     if (GATED) { const u32x4 pp = *(const u32x4*)(PP + off);
;                         const float pv[8] = {bflo(pp.x), bfhi(pp.x), bflo(pp.y), bfhi(pp.y), bflo(pp.z), bfhi(pp.z), bflo(pp.w), bfhi(pp.w)};
; #pragma unroll
;                         for (int e = 0; e < 8; ++e) av[e] = fast_sigmoid(av[e] * rs) * pv[e]; }
;                     else {
; #pragma unroll
;                         for (int e = 0; e < 8; ++e) av[e] *= alpha; }
;                     float lo[8];
; #pragma unroll
;                     for (int e = 0; e < 8; ++e) { hv[e] += av[e]; sq += hv[e] * hv[e]; }
;                     u32x4 wh; wh.x = pk2(hv[0], hv[1]); wh.y = pk2(hv[2], hv[3]); wh.z = pk2(hv[4], hv[5]); wh.w = pk2(hv[6], hv[7]);
;                     lo[0] = hv[0] - bflo(wh.x); lo[1] = hv[1] - bfhi(wh.x); lo[2] = hv[2] - bflo(wh.y); lo[3] = hv[3] - bfhi(wh.y);
;                     lo[4] = hv[4] - bflo(wh.z); lo[5] = hv[5] - bfhi(wh.z); lo[6] = hv[6] - bflo(wh.w); lo[7] = hv[7] - bfhi(wh.w);
;                     u32x4 wl; wl.x = pk2(lo[0], lo[1]); wl.y = pk2(lo[2], lo[3]); wl.z = pk2(lo[4], lo[5]); wl.w = pk2(lo[6], lo[7]);
;                     *(u32x4*)(HO + off) = wh; *(u32x4*)(LO + off) = wl;
;                 }
	v_lshlrev_b32_e32 v156, 16, v164
	v_and_b32_e32 v157, 0xffff0000, v164
	v_lshlrev_b32_e32 v158, 16, v168
	v_and_b32_e32 v159, 0xffff0000, v168
	v_pk_add_f32 v[156:157], v[156:157], v[158:159]
	v_pk_fma_f32 v[156:157], v[62:63], 0.5, v[156:157] op_sel_hi:[1,0,1]
	v_cvt_pk_bf16_f32 v164, v156, v157
	v_pk_mul_f32 v[198:199], v[156:157], v[156:157]
	v_lshlrev_b32_e32 v158, 16, v164
	v_and_b32_e32 v159, 0xffff0000, v164
	v_pk_add_f32 v[196:197], v[156:157], v[158:159] neg_lo:[0,1] neg_hi:[0,1]
	v_cvt_pk_bf16_f32 v168, v196, v197
	v_lshlrev_b32_e32 v156, 16, v165
	v_and_b32_e32 v157, 0xffff0000, v165
	v_lshlrev_b32_e32 v158, 16, v169
	v_and_b32_e32 v159, 0xffff0000, v169
	v_pk_add_f32 v[156:157], v[156:157], v[158:159]
	v_pk_fma_f32 v[156:157], v[64:65], 0.5, v[156:157] op_sel_hi:[1,0,1]
	v_cvt_pk_bf16_f32 v165, v156, v157
	v_pk_fma_f32 v[198:199], v[156:157], v[156:157], v[198:199]
	v_lshlrev_b32_e32 v158, 16, v165
	v_and_b32_e32 v159, 0xffff0000, v165
	v_pk_add_f32 v[196:197], v[156:157], v[158:159] neg_lo:[0,1] neg_hi:[0,1]
	v_cvt_pk_bf16_f32 v169, v196, v197
	v_lshlrev_b32_e32 v156, 16, v166
	v_and_b32_e32 v157, 0xffff0000, v166
	v_lshlrev_b32_e32 v158, 16, v170
	v_and_b32_e32 v159, 0xffff0000, v170
	v_pk_add_f32 v[156:157], v[156:157], v[158:159]
	v_pk_fma_f32 v[156:157], v[58:59], 0.5, v[156:157] op_sel_hi:[1,0,1]
	v_cvt_pk_bf16_f32 v166, v156, v157
	v_pk_fma_f32 v[198:199], v[156:157], v[156:157], v[198:199]
	v_lshlrev_b32_e32 v158, 16, v166
	v_and_b32_e32 v159, 0xffff0000, v166
	v_pk_add_f32 v[196:197], v[156:157], v[158:159] neg_lo:[0,1] neg_hi:[0,1]
	v_cvt_pk_bf16_f32 v170, v196, v197
	v_lshlrev_b32_e32 v156, 16, v167
	v_and_b32_e32 v157, 0xffff0000, v167
	v_lshlrev_b32_e32 v158, 16, v171
	v_and_b32_e32 v159, 0xffff0000, v171
	v_pk_add_f32 v[156:157], v[156:157], v[158:159]
	v_pk_fma_f32 v[156:157], v[60:61], 0.5, v[156:157] op_sel_hi:[1,0,1]
	v_cvt_pk_bf16_f32 v167, v156, v157
	v_pk_fma_f32 v[198:199], v[156:157], v[156:157], v[198:199]
	v_lshlrev_b32_e32 v158, 16, v167
	v_and_b32_e32 v159, 0xffff0000, v167
	v_pk_add_f32 v[196:197], v[156:157], v[158:159] neg_lo:[0,1] neg_hi:[0,1]
	v_cvt_pk_bf16_f32 v171, v196, v197
	global_store_dwordx4 v211, v[164:167], s[10:11]
	global_store_dwordx4 v211, v[168:171], s[6:7]
	s_waitcnt vmcnt(18)
	v_lshlrev_b32_e32 v156, 16, v172
	v_and_b32_e32 v157, 0xffff0000, v172
	v_lshlrev_b32_e32 v158, 16, v176
	v_and_b32_e32 v159, 0xffff0000, v176
	v_pk_add_f32 v[156:157], v[156:157], v[158:159]
	v_pk_fma_f32 v[156:157], v[54:55], 0.5, v[156:157] op_sel_hi:[1,0,1]
	v_cvt_pk_bf16_f32 v172, v156, v157
	v_pk_fma_f32 v[198:199], v[156:157], v[156:157], v[198:199]
	v_lshlrev_b32_e32 v158, 16, v172
	v_and_b32_e32 v159, 0xffff0000, v172
	v_pk_add_f32 v[196:197], v[156:157], v[158:159] neg_lo:[0,1] neg_hi:[0,1]
	v_cvt_pk_bf16_f32 v176, v196, v197
	v_lshlrev_b32_e32 v156, 16, v173
	v_and_b32_e32 v157, 0xffff0000, v173
	v_lshlrev_b32_e32 v158, 16, v177
	v_and_b32_e32 v159, 0xffff0000, v177
	v_pk_add_f32 v[156:157], v[156:157], v[158:159]
	v_pk_fma_f32 v[156:157], v[56:57], 0.5, v[156:157] op_sel_hi:[1,0,1]
	v_cvt_pk_bf16_f32 v173, v156, v157
	v_pk_fma_f32 v[198:199], v[156:157], v[156:157], v[198:199]
	v_lshlrev_b32_e32 v158, 16, v173
	v_and_b32_e32 v159, 0xffff0000, v173
	v_pk_add_f32 v[196:197], v[156:157], v[158:159] neg_lo:[0,1] neg_hi:[0,1]
	v_cvt_pk_bf16_f32 v177, v196, v197
	v_lshlrev_b32_e32 v156, 16, v174
	v_and_b32_e32 v157, 0xffff0000, v174
	v_lshlrev_b32_e32 v158, 16, v178
	v_and_b32_e32 v159, 0xffff0000, v178
	v_pk_add_f32 v[156:157], v[156:157], v[158:159]
	v_pk_fma_f32 v[156:157], v[50:51], 0.5, v[156:157] op_sel_hi:[1,0,1]
	v_cvt_pk_bf16_f32 v174, v156, v157
	v_pk_fma_f32 v[198:199], v[156:157], v[156:157], v[198:199]
	v_lshlrev_b32_e32 v158, 16, v174
	v_and_b32_e32 v159, 0xffff0000, v174
	v_pk_add_f32 v[196:197], v[156:157], v[158:159] neg_lo:[0,1] neg_hi:[0,1]
	v_cvt_pk_bf16_f32 v178, v196, v197
	v_lshlrev_b32_e32 v156, 16, v175
	v_and_b32_e32 v157, 0xffff0000, v175
	v_lshlrev_b32_e32 v158, 16, v179
	v_and_b32_e32 v159, 0xffff0000, v179
	v_pk_add_f32 v[156:157], v[156:157], v[158:159]
	v_pk_fma_f32 v[156:157], v[52:53], 0.5, v[156:157] op_sel_hi:[1,0,1]
	v_cvt_pk_bf16_f32 v175, v156, v157
	v_pk_fma_f32 v[198:199], v[156:157], v[156:157], v[198:199]
	v_lshlrev_b32_e32 v158, 16, v175
	v_and_b32_e32 v159, 0xffff0000, v175
	v_pk_add_f32 v[196:197], v[156:157], v[158:159] neg_lo:[0,1] neg_hi:[0,1]
	v_cvt_pk_bf16_f32 v179, v196, v197
	global_store_dwordx4 v211, v[172:175], s[10:11] offset:256
	global_store_dwordx4 v211, v[176:179], s[6:7] offset:256
	v_add_f32_e32 v206, v198, v199
	s_nop 0
	v_add_u32_e32 v211, 0x58000, v213
	global_load_dwordx4 v[164:167], v211, s[38:39]
	global_load_dwordx4 v[168:171], v211, s[6:7]
	global_load_dwordx4 v[172:175], v211, s[38:39] offset:256
	global_load_dwordx4 v[176:179], v211, s[6:7] offset:256
	s_waitcnt vmcnt(18)
; __device__ __forceinline__ unsigned pk2(float lo, float hi) { f32x2_t v = {lo, hi}; bf16x2_t b = __builtin_convertvector(v, bf16x2_t); return __builtin_bit_cast(unsigned, b); }
; __device__ __forceinline__ float bflo(unsigned u) { return __uint_as_float(u << 16); }
;     __device__ __forceinline__ void operator()(const f32x4 (&acc)[2][2][4][2], const Unit& u, int wr, int wc, int fr, int fq) const {
;     ...
;                 for (int bj = 0; bj < 2; ++bj) {
;                     const size_t off = (size_t)row * DM + col0 + bj * HALF;
;                     const u32x4 hh = *(const u32x4*)(HI + off), ll = *(const u32x4*)(LO + off);
;                     float hv[8] = {bflo(hh.x) + bflo(ll.x), bfhi(hh.x) + bfhi(ll.x), bflo(hh.y) + bflo(ll.y), bfhi(hh.y) + bfhi(ll.y),
;                                    bflo(hh.z) + bflo(ll.z), bfhi(hh.z) + bfhi(ll.z), bflo(hh.w) + bflo(ll.w), bfhi(hh.w) + bfhi(ll.w)};
;                     float av[8] = {acc[ai][bj][m][0][0], acc[ai][bj][m][0][1], acc[ai][bj][m][0][2], acc[ai][bj][m][0][3], acc[ai][bj][m][1][0], acc[ai][bj][m][1][1], acc[ai][bj][m][1][2], acc[ai][bj][m][1][3]};
;                     if (GATED) { const u32x4 pp = *(const u32x4*)(PP + off);
;                         const float pv[8] = {bflo(pp.x), bfhi(pp.x), bflo(pp.y), bfhi(pp.y), bflo(pp.z), bfhi(pp.z), bflo(pp.w), bfhi(pp.w)};
; #pragma unroll
;                         for (int e = 0; e < 8; ++e) av[e] = fast_sigmoid(av[e] * rs) * pv[e]; }
;                     else {
; #pragma unroll
;                         for (int e = 0; e < 8; ++e) av[e] *= alpha; }
;                     float lo[8];
; #pragma unroll
;                     for (int e = 0; e < 8; ++e) { hv[e] += av[e]; sq += hv[e] * hv[e]; }
;                     u32x4 wh; wh.x = pk2(hv[0], hv[1]); wh.y = pk2(hv[2], hv[3]); wh.z = pk2(hv[4], hv[5]); wh.w = pk2(hv[6], hv[7]);
;                     lo[0] = hv[0] - bflo(wh.x); lo[1] = hv[1] - bfhi(wh.x); lo[2] = hv[2] - bflo(wh.y); lo[3] = hv[3] - bfhi(wh.y);
;                     lo[4] = hv[4] - bflo(wh.z); lo[5] = hv[5] - bfhi(wh.z); lo[6] = hv[6] - bflo(wh.w); lo[7] = hv[7] - bfhi(wh.w);
;                     u32x4 wl; wl.x = pk2(lo[0], lo[1]); wl.y = pk2(lo[2], lo[3]); wl.z = pk2(lo[4], lo[5]); wl.w = pk2(lo[6], lo[7]);
;                     *(u32x4*)(HO + off) = wh; *(u32x4*)(LO + off) = wl;
;                 }
	v_lshlrev_b32_e32 v156, 16, v180
	v_and_b32_e32 v157, 0xffff0000, v180
	v_lshlrev_b32_e32 v158, 16, v184
	v_and_b32_e32 v159, 0xffff0000, v184
	v_pk_add_f32 v[156:157], v[156:157], v[158:159]
	v_pk_fma_f32 v[156:157], v[46:47], 0.5, v[156:157] op_sel_hi:[1,0,1]
	v_cvt_pk_bf16_f32 v180, v156, v157
	v_pk_mul_f32 v[198:199], v[156:157], v[156:157]
	v_lshlrev_b32_e32 v158, 16, v180
	v_and_b32_e32 v159, 0xffff0000, v180
	v_pk_add_f32 v[196:197], v[156:157], v[158:159] neg_lo:[0,1] neg_hi:[0,1]
	v_cvt_pk_bf16_f32 v184, v196, v197
	v_lshlrev_b32_e32 v156, 16, v181
	v_and_b32_e32 v157, 0xffff0000, v181
	v_lshlrev_b32_e32 v158, 16, v185
	v_and_b32_e32 v159, 0xffff0000, v185
	v_pk_add_f32 v[156:157], v[156:157], v[158:159]
	v_pk_fma_f32 v[156:157], v[48:49], 0.5, v[156:157] op_sel_hi:[1,0,1]
	v_cvt_pk_bf16_f32 v181, v156, v157
	v_pk_fma_f32 v[198:199], v[156:157], v[156:157], v[198:199]
	v_lshlrev_b32_e32 v158, 16, v181
	v_and_b32_e32 v159, 0xffff0000, v181
	v_pk_add_f32 v[196:197], v[156:157], v[158:159] neg_lo:[0,1] neg_hi:[0,1]
	v_cvt_pk_bf16_f32 v185, v196, v197
	v_lshlrev_b32_e32 v156, 16, v182
	v_and_b32_e32 v157, 0xffff0000, v182
	v_lshlrev_b32_e32 v158, 16, v186
	v_and_b32_e32 v159, 0xffff0000, v186
	v_pk_add_f32 v[156:157], v[156:157], v[158:159]
	v_pk_fma_f32 v[156:157], v[42:43], 0.5, v[156:157] op_sel_hi:[1,0,1]
	v_cvt_pk_bf16_f32 v182, v156, v157
	v_pk_fma_f32 v[198:199], v[156:157], v[156:157], v[198:199]
	v_lshlrev_b32_e32 v158, 16, v182
	v_and_b32_e32 v159, 0xffff0000, v182
	v_pk_add_f32 v[196:197], v[156:157], v[158:159] neg_lo:[0,1] neg_hi:[0,1]
	v_cvt_pk_bf16_f32 v186, v196, v197
	v_lshlrev_b32_e32 v156, 16, v183
	v_and_b32_e32 v157, 0xffff0000, v183
	v_lshlrev_b32_e32 v158, 16, v187
	v_and_b32_e32 v159, 0xffff0000, v187
	v_pk_add_f32 v[156:157], v[156:157], v[158:159]
	v_pk_fma_f32 v[156:157], v[44:45], 0.5, v[156:157] op_sel_hi:[1,0,1]
	v_cvt_pk_bf16_f32 v183, v156, v157
	v_pk_fma_f32 v[198:199], v[156:157], v[156:157], v[198:199]
	v_lshlrev_b32_e32 v158, 16, v183
	v_and_b32_e32 v159, 0xffff0000, v183
	v_pk_add_f32 v[196:197], v[156:157], v[158:159] neg_lo:[0,1] neg_hi:[0,1]
	v_cvt_pk_bf16_f32 v187, v196, v197
	global_store_dwordx4 v212, v[180:183], s[10:11]
	global_store_dwordx4 v212, v[184:187], s[6:7]
	s_waitcnt vmcnt(18)
	v_lshlrev_b32_e32 v156, 16, v188
	v_and_b32_e32 v157, 0xffff0000, v188
	v_lshlrev_b32_e32 v158, 16, v192
	v_and_b32_e32 v159, 0xffff0000, v192
	v_pk_add_f32 v[156:157], v[156:157], v[158:159]
	v_pk_fma_f32 v[156:157], v[38:39], 0.5, v[156:157] op_sel_hi:[1,0,1]
	v_cvt_pk_bf16_f32 v188, v156, v157
	v_pk_fma_f32 v[198:199], v[156:157], v[156:157], v[198:199]
	v_lshlrev_b32_e32 v158, 16, v188
	v_and_b32_e32 v159, 0xffff0000, v188
	v_pk_add_f32 v[196:197], v[156:157], v[158:159] neg_lo:[0,1] neg_hi:[0,1]
	v_cvt_pk_bf16_f32 v192, v196, v197
	v_lshlrev_b32_e32 v156, 16, v189
	v_and_b32_e32 v157, 0xffff0000, v189
	v_lshlrev_b32_e32 v158, 16, v193
	v_and_b32_e32 v159, 0xffff0000, v193
	v_pk_add_f32 v[156:157], v[156:157], v[158:159]
	v_pk_fma_f32 v[156:157], v[40:41], 0.5, v[156:157] op_sel_hi:[1,0,1]
	v_cvt_pk_bf16_f32 v189, v156, v157
	v_pk_fma_f32 v[198:199], v[156:157], v[156:157], v[198:199]
	v_lshlrev_b32_e32 v158, 16, v189
	v_and_b32_e32 v159, 0xffff0000, v189
	v_pk_add_f32 v[196:197], v[156:157], v[158:159] neg_lo:[0,1] neg_hi:[0,1]
	v_cvt_pk_bf16_f32 v193, v196, v197
	v_lshlrev_b32_e32 v156, 16, v190
	v_and_b32_e32 v157, 0xffff0000, v190
	v_lshlrev_b32_e32 v158, 16, v194
	v_and_b32_e32 v159, 0xffff0000, v194
	v_pk_add_f32 v[156:157], v[156:157], v[158:159]
	v_pk_fma_f32 v[156:157], v[34:35], 0.5, v[156:157] op_sel_hi:[1,0,1]
	v_cvt_pk_bf16_f32 v190, v156, v157
	v_pk_fma_f32 v[198:199], v[156:157], v[156:157], v[198:199]
	v_lshlrev_b32_e32 v158, 16, v190
	v_and_b32_e32 v159, 0xffff0000, v190
	v_pk_add_f32 v[196:197], v[156:157], v[158:159] neg_lo:[0,1] neg_hi:[0,1]
	v_cvt_pk_bf16_f32 v194, v196, v197
	v_lshlrev_b32_e32 v156, 16, v191
	v_and_b32_e32 v157, 0xffff0000, v191
	v_lshlrev_b32_e32 v158, 16, v195
	v_and_b32_e32 v159, 0xffff0000, v195
	v_pk_add_f32 v[156:157], v[156:157], v[158:159]
	v_pk_fma_f32 v[156:157], v[36:37], 0.5, v[156:157] op_sel_hi:[1,0,1]
	v_cvt_pk_bf16_f32 v191, v156, v157
	v_pk_fma_f32 v[198:199], v[156:157], v[156:157], v[198:199]
	v_lshlrev_b32_e32 v158, 16, v191
	v_and_b32_e32 v159, 0xffff0000, v191
	v_pk_add_f32 v[196:197], v[156:157], v[158:159] neg_lo:[0,1] neg_hi:[0,1]
	v_cvt_pk_bf16_f32 v195, v196, v197
	global_store_dwordx4 v212, v[188:191], s[10:11] offset:256
	global_store_dwordx4 v212, v[192:195], s[6:7] offset:256
	v_add_f32_e32 v207, v198, v199
	s_waitcnt vmcnt(14)
; __device__ __forceinline__ unsigned pk2(float lo, float hi) { f32x2_t v = {lo, hi}; bf16x2_t b = __builtin_convertvector(v, bf16x2_t); return __builtin_bit_cast(unsigned, b); }
; __device__ __forceinline__ float bflo(unsigned u) { return __uint_as_float(u << 16); }
;     __device__ __forceinline__ void operator()(const f32x4 (&acc)[2][2][4][2], const Unit& u, int wr, int wc, int fr, int fq) const {
;     ...
;                 for (int bj = 0; bj < 2; ++bj) {
;                     const size_t off = (size_t)row * DM + col0 + bj * HALF;
;                     const u32x4 hh = *(const u32x4*)(HI + off), ll = *(const u32x4*)(LO + off);
;                     float hv[8] = {bflo(hh.x) + bflo(ll.x), bfhi(hh.x) + bfhi(ll.x), bflo(hh.y) + bflo(ll.y), bfhi(hh.y) + bfhi(ll.y),
;                                    bflo(hh.z) + bflo(ll.z), bfhi(hh.z) + bfhi(ll.z), bflo(hh.w) + bflo(ll.w), bfhi(hh.w) + bfhi(ll.w)};
;                     float av[8] = {acc[ai][bj][m][0][0], acc[ai][bj][m][0][1], acc[ai][bj][m][0][2], acc[ai][bj][m][0][3], acc[ai][bj][m][1][0], acc[ai][bj][m][1][1], acc[ai][bj][m][1][2], acc[ai][bj][m][1][3]};
;                     if (GATED) { const u32x4 pp = *(const u32x4*)(PP + off);
;                         const float pv[8] = {bflo(pp.x), bfhi(pp.x), bflo(pp.y), bfhi(pp.y), bflo(pp.z), bfhi(pp.z), bflo(pp.w), bfhi(pp.w)};
; #pragma unroll
;                         for (int e = 0; e < 8; ++e) av[e] = fast_sigmoid(av[e] * rs) * pv[e]; }
;                     else {
; #pragma unroll
;                         for (int e = 0; e < 8; ++e) av[e] *= alpha; }
;                     float lo[8];
; #pragma unroll
;                     for (int e = 0; e < 8; ++e) { hv[e] += av[e]; sq += hv[e] * hv[e]; }
;                     u32x4 wh; wh.x = pk2(hv[0], hv[1]); wh.y = pk2(hv[2], hv[3]); wh.z = pk2(hv[4], hv[5]); wh.w = pk2(hv[6], hv[7]);
;                     lo[0] = hv[0] - bflo(wh.x); lo[1] = hv[1] - bfhi(wh.x); lo[2] = hv[2] - bflo(wh.y); lo[3] = hv[3] - bfhi(wh.y);
;                     lo[4] = hv[4] - bflo(wh.z); lo[5] = hv[5] - bfhi(wh.z); lo[6] = hv[6] - bflo(wh.w); lo[7] = hv[7] - bfhi(wh.w);
;                     u32x4 wl; wl.x = pk2(lo[0], lo[1]); wl.y = pk2(lo[2], lo[3]); wl.z = pk2(lo[4], lo[5]); wl.w = pk2(lo[6], lo[7]);
;                     *(u32x4*)(HO + off) = wh; *(u32x4*)(LO + off) = wl;
;                 }
	v_lshlrev_b32_e32 v156, 16, v140
	v_and_b32_e32 v157, 0xffff0000, v140
	v_lshlrev_b32_e32 v158, 16, v144
	v_and_b32_e32 v159, 0xffff0000, v144
	v_pk_add_f32 v[156:157], v[156:157], v[158:159]
	v_pk_fma_f32 v[156:157], v[30:31], 0.5, v[156:157] op_sel_hi:[1,0,1]
	v_cvt_pk_bf16_f32 v140, v156, v157
	v_pk_mul_f32 v[198:199], v[156:157], v[156:157]
	v_lshlrev_b32_e32 v158, 16, v140
	v_and_b32_e32 v159, 0xffff0000, v140
	v_pk_add_f32 v[196:197], v[156:157], v[158:159] neg_lo:[0,1] neg_hi:[0,1]
	v_cvt_pk_bf16_f32 v144, v196, v197
	v_lshlrev_b32_e32 v156, 16, v141
	v_and_b32_e32 v157, 0xffff0000, v141
	v_lshlrev_b32_e32 v158, 16, v145
	v_and_b32_e32 v159, 0xffff0000, v145
	v_pk_add_f32 v[156:157], v[156:157], v[158:159]
	v_pk_fma_f32 v[156:157], v[32:33], 0.5, v[156:157] op_sel_hi:[1,0,1]
	v_cvt_pk_bf16_f32 v141, v156, v157
	v_pk_fma_f32 v[198:199], v[156:157], v[156:157], v[198:199]
	v_lshlrev_b32_e32 v158, 16, v141
	v_and_b32_e32 v159, 0xffff0000, v141
	v_pk_add_f32 v[196:197], v[156:157], v[158:159] neg_lo:[0,1] neg_hi:[0,1]
	v_cvt_pk_bf16_f32 v145, v196, v197
	v_lshlrev_b32_e32 v156, 16, v142
	v_and_b32_e32 v157, 0xffff0000, v142
	v_lshlrev_b32_e32 v158, 16, v146
	v_and_b32_e32 v159, 0xffff0000, v146
	v_pk_add_f32 v[156:157], v[156:157], v[158:159]
	v_pk_fma_f32 v[156:157], v[26:27], 0.5, v[156:157] op_sel_hi:[1,0,1]
	v_cvt_pk_bf16_f32 v142, v156, v157
	v_pk_fma_f32 v[198:199], v[156:157], v[156:157], v[198:199]
	v_lshlrev_b32_e32 v158, 16, v142
	v_and_b32_e32 v159, 0xffff0000, v142
	v_pk_add_f32 v[196:197], v[156:157], v[158:159] neg_lo:[0,1] neg_hi:[0,1]
	v_cvt_pk_bf16_f32 v146, v196, v197
	v_lshlrev_b32_e32 v156, 16, v143
	v_and_b32_e32 v157, 0xffff0000, v143
	v_lshlrev_b32_e32 v158, 16, v147
	v_and_b32_e32 v159, 0xffff0000, v147
	v_pk_add_f32 v[156:157], v[156:157], v[158:159]
	v_pk_fma_f32 v[156:157], v[28:29], 0.5, v[156:157] op_sel_hi:[1,0,1]
	v_cvt_pk_bf16_f32 v143, v156, v157
	v_pk_fma_f32 v[198:199], v[156:157], v[156:157], v[198:199]
	v_lshlrev_b32_e32 v158, 16, v143
	v_and_b32_e32 v159, 0xffff0000, v143
	v_pk_add_f32 v[196:197], v[156:157], v[158:159] neg_lo:[0,1] neg_hi:[0,1]
	v_cvt_pk_bf16_f32 v147, v196, v197
	global_store_dwordx4 v210, v[140:143], s[10:11]
	global_store_dwordx4 v210, v[144:147], s[6:7]
	s_waitcnt vmcnt(14)
	v_lshlrev_b32_e32 v156, 16, v148
	v_and_b32_e32 v157, 0xffff0000, v148
	v_lshlrev_b32_e32 v158, 16, v152
	v_and_b32_e32 v159, 0xffff0000, v152
	v_pk_add_f32 v[156:157], v[156:157], v[158:159]
	v_pk_fma_f32 v[156:157], v[22:23], 0.5, v[156:157] op_sel_hi:[1,0,1]
	v_cvt_pk_bf16_f32 v148, v156, v157
	v_pk_fma_f32 v[198:199], v[156:157], v[156:157], v[198:199]
	v_lshlrev_b32_e32 v158, 16, v148
	v_and_b32_e32 v159, 0xffff0000, v148
	v_pk_add_f32 v[196:197], v[156:157], v[158:159] neg_lo:[0,1] neg_hi:[0,1]
	v_cvt_pk_bf16_f32 v152, v196, v197
	v_lshlrev_b32_e32 v156, 16, v149
	v_and_b32_e32 v157, 0xffff0000, v149
	v_lshlrev_b32_e32 v158, 16, v153
	v_and_b32_e32 v159, 0xffff0000, v153
	v_pk_add_f32 v[156:157], v[156:157], v[158:159]
	v_pk_fma_f32 v[156:157], v[24:25], 0.5, v[156:157] op_sel_hi:[1,0,1]
	v_cvt_pk_bf16_f32 v149, v156, v157
	v_pk_fma_f32 v[198:199], v[156:157], v[156:157], v[198:199]
	v_lshlrev_b32_e32 v158, 16, v149
	v_and_b32_e32 v159, 0xffff0000, v149
	v_pk_add_f32 v[196:197], v[156:157], v[158:159] neg_lo:[0,1] neg_hi:[0,1]
	v_cvt_pk_bf16_f32 v153, v196, v197
	v_lshlrev_b32_e32 v156, 16, v150
	v_and_b32_e32 v157, 0xffff0000, v150
	v_lshlrev_b32_e32 v158, 16, v154
	v_and_b32_e32 v159, 0xffff0000, v154
	v_pk_add_f32 v[156:157], v[156:157], v[158:159]
	v_pk_fma_f32 v[156:157], v[18:19], 0.5, v[156:157] op_sel_hi:[1,0,1]
	v_cvt_pk_bf16_f32 v150, v156, v157
	v_pk_fma_f32 v[198:199], v[156:157], v[156:157], v[198:199]
	v_lshlrev_b32_e32 v158, 16, v150
	v_and_b32_e32 v159, 0xffff0000, v150
	v_pk_add_f32 v[196:197], v[156:157], v[158:159] neg_lo:[0,1] neg_hi:[0,1]
	v_cvt_pk_bf16_f32 v154, v196, v197
	v_lshlrev_b32_e32 v156, 16, v151
	v_and_b32_e32 v157, 0xffff0000, v151
	v_lshlrev_b32_e32 v158, 16, v155
	v_and_b32_e32 v159, 0xffff0000, v155
	v_pk_add_f32 v[156:157], v[156:157], v[158:159]
	v_pk_fma_f32 v[156:157], v[20:21], 0.5, v[156:157] op_sel_hi:[1,0,1]
	v_cvt_pk_bf16_f32 v151, v156, v157
	v_pk_fma_f32 v[198:199], v[156:157], v[156:157], v[198:199]
	v_lshlrev_b32_e32 v158, 16, v151
	v_and_b32_e32 v159, 0xffff0000, v151
	v_pk_add_f32 v[196:197], v[156:157], v[158:159] neg_lo:[0,1] neg_hi:[0,1]
	v_cvt_pk_bf16_f32 v155, v196, v197
	global_store_dwordx4 v210, v[148:151], s[10:11] offset:256
	global_store_dwordx4 v210, v[152:155], s[6:7] offset:256
	v_add_f32_e32 v208, v198, v199
	s_waitcnt vmcnt(10)
; __device__ __forceinline__ float bflo(unsigned u) { return __uint_as_float(u << 16); }
;     __device__ __forceinline__ void operator()(const f32x4 (&acc)[2][2][4][2], const Unit& u, int wr, int wc, int fr, int fq) const {
;     ...
;                 for (int bj = 0; bj < 2; ++bj) {
;                     const size_t off = (size_t)row * DM + col0 + bj * HALF;
;                     const u32x4 hh = *(const u32x4*)(HI + off), ll = *(const u32x4*)(LO + off);
;                     float hv[8] = {bflo(hh.x) + bflo(ll.x), bfhi(hh.x) + bfhi(ll.x), bflo(hh.y) + bflo(ll.y), bfhi(hh.y) + bfhi(ll.y),
;                                    bflo(hh.z) + bflo(ll.z), bfhi(hh.z) + bfhi(ll.z), bflo(hh.w) + bflo(ll.w), bfhi(hh.w) + bfhi(ll.w)};
;                     float av[8] = {acc[ai][bj][m][0][0], acc[ai][bj][m][0][1], acc[ai][bj][m][0][2], acc[ai][bj][m][0][3], acc[ai][bj][m][1][0], acc[ai][bj][m][1][1], acc[ai][bj][m][1][2], acc[ai][bj][m][1][3]};
;                     if (GATED) { const u32x4 pp = *(const u32x4*)(PP + off);
;                         const float pv[8] = {bflo(pp.x), bfhi(pp.x), bflo(pp.y), bfhi(pp.y), bflo(pp.z), bfhi(pp.z), bflo(pp.w), bfhi(pp.w)};
; #pragma unroll
;                         for (int e = 0; e < 8; ++e) av[e] = fast_sigmoid(av[e] * rs) * pv[e]; }
;                     else {
; #pragma unroll
;                         for (int e = 0; e < 8; ++e) av[e] *= alpha; }
;                     float lo[8];
; #pragma unroll
;                     for (int e = 0; e < 8; ++e) { hv[e] += av[e]; sq += hv[e] * hv[e]; }
;                     u32x4 wh; wh.x = pk2(hv[0], hv[1]); wh.y = pk2(hv[2], hv[3]); wh.z = pk2(hv[4], hv[5]); wh.w = pk2(hv[6], hv[7]);
;                     lo[0] = hv[0] - bflo(wh.x); lo[1] = hv[1] - bfhi(wh.x); lo[2] = hv[2] - bflo(wh.y); lo[3] = hv[3] - bfhi(wh.y);
;                     lo[4] = hv[4] - bflo(wh.z); lo[5] = hv[5] - bfhi(wh.z); lo[6] = hv[6] - bflo(wh.w); lo[7] = hv[7] - bfhi(wh.w);
;                     u32x4 wl; wl.x = pk2(lo[0], lo[1]); wl.y = pk2(lo[2], lo[3]); wl.z = pk2(lo[4], lo[5]); wl.w = pk2(lo[6], lo[7]);
;                     *(u32x4*)(HO + off) = wh; *(u32x4*)(LO + off) = wl;
;                 }
;                 sq += __shfl_xor(sq, 16); sq += __shfl_xor(sq, 32);
;                 if (fq == 0) ssq_out[(size_t)row * 16 + 4 * u.pn + wc] = sq;
	v_lshlrev_b32_e32 v156, 16, v164
	v_and_b32_e32 v157, 0xffff0000, v164
	v_lshlrev_b32_e32 v158, 16, v168
	v_and_b32_e32 v159, 0xffff0000, v168
	v_pk_add_f32 v[156:157], v[156:157], v[158:159]
	v_pk_fma_f32 v[156:157], v[14:15], 0.5, v[156:157] op_sel_hi:[1,0,1]
	v_cvt_pk_bf16_f32 v164, v156, v157
	v_pk_mul_f32 v[198:199], v[156:157], v[156:157]
	v_lshlrev_b32_e32 v158, 16, v164
	v_and_b32_e32 v159, 0xffff0000, v164
	v_pk_add_f32 v[196:197], v[156:157], v[158:159] neg_lo:[0,1] neg_hi:[0,1]
	v_cvt_pk_bf16_f32 v168, v196, v197
	v_lshlrev_b32_e32 v156, 16, v165
	v_and_b32_e32 v157, 0xffff0000, v165
	v_lshlrev_b32_e32 v158, 16, v169
	v_and_b32_e32 v159, 0xffff0000, v169
	v_pk_add_f32 v[156:157], v[156:157], v[158:159]
	v_pk_fma_f32 v[156:157], v[16:17], 0.5, v[156:157] op_sel_hi:[1,0,1]
	v_cvt_pk_bf16_f32 v165, v156, v157
	v_pk_fma_f32 v[198:199], v[156:157], v[156:157], v[198:199]
	v_lshlrev_b32_e32 v158, 16, v165
	v_and_b32_e32 v159, 0xffff0000, v165
	v_pk_add_f32 v[196:197], v[156:157], v[158:159] neg_lo:[0,1] neg_hi:[0,1]
	v_cvt_pk_bf16_f32 v169, v196, v197
	v_lshlrev_b32_e32 v156, 16, v166
	v_and_b32_e32 v157, 0xffff0000, v166
	v_lshlrev_b32_e32 v158, 16, v170
	v_and_b32_e32 v159, 0xffff0000, v170
	v_pk_add_f32 v[156:157], v[156:157], v[158:159]
	v_pk_fma_f32 v[156:157], v[10:11], 0.5, v[156:157] op_sel_hi:[1,0,1]
	v_cvt_pk_bf16_f32 v166, v156, v157
	v_pk_fma_f32 v[198:199], v[156:157], v[156:157], v[198:199]
	v_lshlrev_b32_e32 v158, 16, v166
	v_and_b32_e32 v159, 0xffff0000, v166
	v_pk_add_f32 v[196:197], v[156:157], v[158:159] neg_lo:[0,1] neg_hi:[0,1]
	v_cvt_pk_bf16_f32 v170, v196, v197
	v_lshlrev_b32_e32 v156, 16, v167
	v_and_b32_e32 v157, 0xffff0000, v167
	v_lshlrev_b32_e32 v158, 16, v171
	v_and_b32_e32 v159, 0xffff0000, v171
	v_pk_add_f32 v[156:157], v[156:157], v[158:159]
	v_pk_fma_f32 v[156:157], v[12:13], 0.5, v[156:157] op_sel_hi:[1,0,1]
	v_cvt_pk_bf16_f32 v167, v156, v157
	v_pk_fma_f32 v[198:199], v[156:157], v[156:157], v[198:199]
	v_lshlrev_b32_e32 v158, 16, v167
	v_and_b32_e32 v159, 0xffff0000, v167
	v_pk_add_f32 v[196:197], v[156:157], v[158:159] neg_lo:[0,1] neg_hi:[0,1]
	v_cvt_pk_bf16_f32 v171, v196, v197
	global_store_dwordx4 v211, v[164:167], s[10:11]
	global_store_dwordx4 v211, v[168:171], s[6:7]
	s_waitcnt vmcnt(10)
	v_lshlrev_b32_e32 v156, 16, v172
	v_and_b32_e32 v157, 0xffff0000, v172
	v_lshlrev_b32_e32 v158, 16, v176
	v_and_b32_e32 v159, 0xffff0000, v176
	v_pk_add_f32 v[156:157], v[156:157], v[158:159]
	v_pk_fma_f32 v[156:157], v[6:7], 0.5, v[156:157] op_sel_hi:[1,0,1]
	v_cvt_pk_bf16_f32 v172, v156, v157
	v_pk_fma_f32 v[198:199], v[156:157], v[156:157], v[198:199]
	v_lshlrev_b32_e32 v158, 16, v172
	v_and_b32_e32 v159, 0xffff0000, v172
	v_pk_add_f32 v[196:197], v[156:157], v[158:159] neg_lo:[0,1] neg_hi:[0,1]
	v_cvt_pk_bf16_f32 v176, v196, v197
	v_lshlrev_b32_e32 v156, 16, v173
	v_and_b32_e32 v157, 0xffff0000, v173
	v_lshlrev_b32_e32 v158, 16, v177
	v_and_b32_e32 v159, 0xffff0000, v177
	v_pk_add_f32 v[156:157], v[156:157], v[158:159]
	v_pk_fma_f32 v[156:157], v[8:9], 0.5, v[156:157] op_sel_hi:[1,0,1]
	v_cvt_pk_bf16_f32 v173, v156, v157
	v_pk_fma_f32 v[198:199], v[156:157], v[156:157], v[198:199]
	v_lshlrev_b32_e32 v158, 16, v173
	v_and_b32_e32 v159, 0xffff0000, v173
	v_pk_add_f32 v[196:197], v[156:157], v[158:159] neg_lo:[0,1] neg_hi:[0,1]
	v_cvt_pk_bf16_f32 v177, v196, v197
	v_lshlrev_b32_e32 v156, 16, v174
	v_and_b32_e32 v157, 0xffff0000, v174
	v_lshlrev_b32_e32 v158, 16, v178
	v_and_b32_e32 v159, 0xffff0000, v178
	v_pk_add_f32 v[156:157], v[156:157], v[158:159]
	v_pk_fma_f32 v[156:157], v[2:3], 0.5, v[156:157] op_sel_hi:[1,0,1]
	v_cvt_pk_bf16_f32 v174, v156, v157
	v_pk_fma_f32 v[198:199], v[156:157], v[156:157], v[198:199]
	v_lshlrev_b32_e32 v158, 16, v174
	v_and_b32_e32 v159, 0xffff0000, v174
	v_pk_add_f32 v[196:197], v[156:157], v[158:159] neg_lo:[0,1] neg_hi:[0,1]
	v_cvt_pk_bf16_f32 v178, v196, v197
	v_lshlrev_b32_e32 v156, 16, v175
	v_and_b32_e32 v157, 0xffff0000, v175
	v_lshlrev_b32_e32 v158, 16, v179
	v_and_b32_e32 v159, 0xffff0000, v179
	v_pk_add_f32 v[156:157], v[156:157], v[158:159]
	v_pk_fma_f32 v[156:157], v[4:5], 0.5, v[156:157] op_sel_hi:[1,0,1]
	v_cvt_pk_bf16_f32 v175, v156, v157
	v_pk_fma_f32 v[198:199], v[156:157], v[156:157], v[198:199]
	v_lshlrev_b32_e32 v158, 16, v175
	v_and_b32_e32 v159, 0xffff0000, v175
	v_pk_add_f32 v[196:197], v[156:157], v[158:159] neg_lo:[0,1] neg_hi:[0,1]
	v_cvt_pk_bf16_f32 v179, v196, v197
	global_store_dwordx4 v211, v[172:175], s[10:11] offset:256
	global_store_dwordx4 v211, v[176:179], s[6:7] offset:256
	v_add_f32_e32 v209, v198, v199
	v_mov_b32_e32 v140, v200
	s_nop 1
	v_permlane16_swap_b32_e32 v200, v140
	v_mov_b32_e32 v141, v201
	s_nop 1
	v_permlane16_swap_b32_e32 v201, v141
	v_mov_b32_e32 v142, v202
	s_nop 1
	v_permlane16_swap_b32_e32 v202, v142
	v_mov_b32_e32 v143, v203
	s_nop 1
	v_permlane16_swap_b32_e32 v203, v143
	v_mov_b32_e32 v144, v206
	s_nop 1
	v_permlane16_swap_b32_e32 v206, v144
	v_mov_b32_e32 v145, v207
	s_nop 1
	v_permlane16_swap_b32_e32 v207, v145
	v_mov_b32_e32 v146, v208
	s_nop 1
	v_permlane16_swap_b32_e32 v208, v146
	v_mov_b32_e32 v147, v209
	s_nop 1
	v_permlane16_swap_b32_e32 v209, v147
	v_readlane_b32 s52, v250, 35
	v_readlane_b32 s53, v250, 36
	s_waitcnt lgkmcnt(0)
	v_add_f32_e32 v200, v200, v140
	v_add_f32_e32 v201, v201, v141
	v_add_f32_e32 v202, v202, v142
	v_add_f32_e32 v203, v203, v143
	v_add_f32_e32 v206, v206, v144
	v_add_f32_e32 v207, v207, v145
	v_add_f32_e32 v208, v208, v146
	v_add_f32_e32 v209, v209, v147
	v_mov_b32_e32 v140, v200
	s_nop 1
	v_permlane32_swap_b32_e32 v200, v140
	v_mov_b32_e32 v141, v201
	s_nop 1
	v_permlane32_swap_b32_e32 v201, v141
	v_mov_b32_e32 v142, v202
	s_nop 1
	v_permlane32_swap_b32_e32 v202, v142
	v_mov_b32_e32 v143, v203
	s_nop 1
	v_permlane32_swap_b32_e32 v203, v143
	v_mov_b32_e32 v144, v206
	s_nop 1
	v_permlane32_swap_b32_e32 v206, v144
	v_mov_b32_e32 v145, v207
	s_nop 1
	v_permlane32_swap_b32_e32 v207, v145
	v_mov_b32_e32 v146, v208
	s_nop 1
	v_permlane32_swap_b32_e32 v208, v146
	v_mov_b32_e32 v147, v209
	s_nop 1
	v_permlane32_swap_b32_e32 v209, v147
	s_waitcnt lgkmcnt(0)
	v_add_f32_e32 v200, v200, v140
	v_add_f32_e32 v201, v201, v141
	v_add_f32_e32 v202, v202, v142
	v_add_f32_e32 v203, v203, v143
	v_add_f32_e32 v206, v206, v144
	v_add_f32_e32 v207, v207, v145
	v_add_f32_e32 v208, v208, v146
	v_add_f32_e32 v209, v209, v147
	s_and_saveexec_b64 s[12:13], s[44:45]
	s_cbranch_execz .Lepir_f1d_skip
	global_store_dword v216, v200, s[52:53]
	global_store_dword v216, v201, s[52:53] offset:1024
	global_store_dword v216, v202, s[52:53] offset:2048
	global_store_dword v216, v203, s[52:53] offset:3072
	global_store_dword v217, v206, s[52:53]
	global_store_dword v217, v207, s[52:53] offset:1024
	global_store_dword v217, v208, s[52:53] offset:2048
	global_store_dword v217, v209, s[52:53] offset:3072

; __device__ __forceinline__ float bflo(unsigned u) { return __uint_as_float(u << 16); }
;     __device__ __forceinline__ void operator()(const f32x4 (&acc)[2][2][4][2], const Unit& u, int wr, int wc, int fr, int fq) const {
;         const int row0 = u.pm * BM + wr * 64 + fr, col0 = u.pn * BM + wc * 32 + 8 * fq;
; #pragma unroll
;         for (int ai = 0; ai < 2; ++ai)
; #pragma unroll
;             for (int m = 0; m < 4; ++m) {
;                 const int row = row0 + ai * HALF + m * 16;
;                 float rs = 0.f; if (GATED) rs = rsqrtf(row_ssq(ssq_in, 16, 4, row, fq) * (1.f / 1024.f) + EPS);
;                 float sq = 0.f;
; #pragma unroll
;                 for (int bj = 0; bj < 2; ++bj) {
;                     const size_t off = (size_t)row * DM + col0 + bj * HALF;
;                     const u32x4 hh = *(const u32x4*)(HI + off), ll = *(const u32x4*)(LO + off);
;                     float hv[8] = {bflo(hh.x) + bflo(ll.x), bfhi(hh.x) + bfhi(ll.x), bflo(hh.y) + bflo(ll.y), bfhi(hh.y) + bfhi(ll.y),
;                                    bflo(hh.z) + bflo(ll.z), bfhi(hh.z) + bfhi(ll.z), bflo(hh.w) + bflo(ll.w), bfhi(hh.w) + bfhi(ll.w)};
;                     float av[8] = {acc[ai][bj][m][0][0], acc[ai][bj][m][0][1], acc[ai][bj][m][0][2], acc[ai][bj][m][0][3], acc[ai][bj][m][1][0], acc[ai][bj][m][1][1], acc[ai][bj][m][1][2], acc[ai][bj][m][1][3]};
;                     if (GATED) { const u32x4 pp = *(const u32x4*)(PP + off);
;                         const float pv[8] = {bflo(pp.x), bfhi(pp.x), bflo(pp.y), bfhi(pp.y), bflo(pp.z), bfhi(pp.z), bflo(pp.w), bfhi(pp.w)};
; #pragma unroll
;                         for (int e = 0; e < 8; ++e) av[e] = fast_sigmoid(av[e] * rs) * pv[e]; }
;                     else {
; #pragma unroll
;                         for (int e = 0; e < 8; ++e) av[e] *= alpha; }
;                     float lo[8];
; #pragma unroll
;                     for (int e = 0; e < 8; ++e) { hv[e] += av[e]; sq += hv[e] * hv[e]; }
;                     u32x4 wh; wh.x = pk2(hv[0], hv[1]); wh.y = pk2(hv[2], hv[3]); wh.z = pk2(hv[4], hv[5]); wh.w = pk2(hv[6], hv[7]);
;                     lo[0] = hv[0] - bflo(wh.x); lo[1] = hv[1] - bfhi(wh.x); lo[2] = hv[2] - bflo(wh.y); lo[3] = hv[3] - bfhi(wh.y);
;                     lo[4] = hv[4] - bflo(wh.z); lo[5] = hv[5] - bfhi(wh.z); lo[6] = hv[6] - bflo(wh.w); lo[7] = hv[7] - bfhi(wh.w);
.LBB0_1071:
	v_and_b32_e32 v158, 64, v241
	v_xor_b32_e32 v214, 16, v241
	v_add_u32_e32 v158, 64, v158
	v_cmp_lt_i32_e32 vcc, v214, v158
	v_lshl_add_u32 v156, s40, 8, v160
	v_lshl_or_b32 v157, s4, 8, v162
	v_cndmask_b32_e32 v214, v241, v214, vcc
	v_lshlrev_b32_e32 v214, 2, v214
	v_xor_b32_e32 v215, 32, v241
	v_cmp_lt_i32_e32 vcc, v215, v158
	v_readlane_b32 s10, v254, 18
	v_readlane_b32 s11, v254, 19
	s_nop 1
	v_cndmask_b32_e32 v215, v241, v215, vcc
	v_lshlrev_b32_e32 v215, 2, v215
	v_lshl_add_u32 v213, v156, 10, v157
	v_lshlrev_b32_e32 v213, 1, v213
	s_lshl_b32 s40, s4, 4
	s_lshl_b32 s0, s48, 2
	s_add_i32 s40, s40, s0
	v_lshlrev_b32_e32 v216, 6, v156
	v_add_u32_e32 v216, s40, v216
	v_add_u32_e32 v217, 0x2000, v216
	v_readlane_b32 s30, v251, 4
	v_readlane_b32 s31, v251, 5
	s_nop 1
	v_add_u32_e32 v211, 0x8000, v213
	global_load_dwordx4 v[164:167], v211, s[10:11]
	global_load_dwordx4 v[168:171], v211, s[14:15]
	global_load_dwordx4 v[172:175], v211, s[10:11] offset:256
	global_load_dwordx4 v[176:179], v211, s[14:15] offset:256
	v_add_u32_e32 v212, 0x10000, v213
	global_load_dwordx4 v[180:183], v212, s[10:11]
	global_load_dwordx4 v[184:187], v212, s[14:15]
	global_load_dwordx4 v[188:191], v212, s[10:11] offset:256
	global_load_dwordx4 v[192:195], v212, s[14:15] offset:256
	v_add_u32_e32 v210, 0x18000, v213
	global_load_dwordx4 v[140:143], v210, s[10:11]
	global_load_dwordx4 v[144:147], v210, s[14:15]
	global_load_dwordx4 v[148:151], v210, s[10:11] offset:256
	global_load_dwordx4 v[152:155], v210, s[14:15] offset:256
	s_waitcnt vmcnt(12)
	v_lshlrev_b32_e32 v156, 16, v226
	v_and_b32_e32 v157, 0xffff0000, v226
	v_lshlrev_b32_e32 v158, 16, v230
	v_and_b32_e32 v159, 0xffff0000, v230
	v_pk_add_f32 v[156:157], v[156:157], v[158:159]
	v_pk_add_f32 v[156:157], v[126:127], v[156:157]
	v_cvt_pk_bf16_f32 v226, v156, v157
	v_pk_mul_f32 v[198:199], v[156:157], v[156:157]
	v_lshlrev_b32_e32 v158, 16, v226
	v_and_b32_e32 v159, 0xffff0000, v226
	v_pk_add_f32 v[196:197], v[156:157], v[158:159] neg_lo:[0,1] neg_hi:[0,1]
	v_cvt_pk_bf16_f32 v230, v196, v197
	v_lshlrev_b32_e32 v156, 16, v227
	v_and_b32_e32 v157, 0xffff0000, v227
	v_lshlrev_b32_e32 v158, 16, v231
	v_and_b32_e32 v159, 0xffff0000, v231
	v_pk_add_f32 v[156:157], v[156:157], v[158:159]
	v_pk_add_f32 v[156:157], v[128:129], v[156:157]
	v_cvt_pk_bf16_f32 v227, v156, v157
	v_pk_fma_f32 v[198:199], v[156:157], v[156:157], v[198:199]
	v_lshlrev_b32_e32 v158, 16, v227
	v_and_b32_e32 v159, 0xffff0000, v227
	v_pk_add_f32 v[196:197], v[156:157], v[158:159] neg_lo:[0,1] neg_hi:[0,1]
	v_cvt_pk_bf16_f32 v231, v196, v197
	v_lshlrev_b32_e32 v156, 16, v228
	v_and_b32_e32 v157, 0xffff0000, v228
	v_lshlrev_b32_e32 v158, 16, v232
	v_and_b32_e32 v159, 0xffff0000, v232
	v_pk_add_f32 v[156:157], v[156:157], v[158:159]
	v_pk_add_f32 v[156:157], v[122:123], v[156:157]
	v_cvt_pk_bf16_f32 v228, v156, v157
	v_pk_fma_f32 v[198:199], v[156:157], v[156:157], v[198:199]
	v_lshlrev_b32_e32 v158, 16, v228
	v_and_b32_e32 v159, 0xffff0000, v228
	v_pk_add_f32 v[196:197], v[156:157], v[158:159] neg_lo:[0,1] neg_hi:[0,1]
	v_cvt_pk_bf16_f32 v232, v196, v197
	v_lshlrev_b32_e32 v156, 16, v229
	v_and_b32_e32 v157, 0xffff0000, v229
	v_lshlrev_b32_e32 v158, 16, v233
	v_and_b32_e32 v159, 0xffff0000, v233
	v_pk_add_f32 v[156:157], v[156:157], v[158:159]
	v_pk_add_f32 v[156:157], v[124:125], v[156:157]
	v_cvt_pk_bf16_f32 v229, v156, v157
	v_pk_fma_f32 v[198:199], v[156:157], v[156:157], v[198:199]
	v_lshlrev_b32_e32 v158, 16, v229
	v_and_b32_e32 v159, 0xffff0000, v229
	v_pk_add_f32 v[196:197], v[156:157], v[158:159] neg_lo:[0,1] neg_hi:[0,1]
	v_cvt_pk_bf16_f32 v233, v196, v197
	global_store_dwordx4 v213, v[226:229], s[10:11]
	global_store_dwordx4 v213, v[230:233], s[14:15]
	v_lshlrev_b32_e32 v156, 16, v234
	v_and_b32_e32 v157, 0xffff0000, v234
	v_lshlrev_b32_e32 v158, 16, v242
	v_and_b32_e32 v159, 0xffff0000, v242
	v_pk_add_f32 v[156:157], v[156:157], v[158:159]
	v_pk_add_f32 v[156:157], v[118:119], v[156:157]
	v_cvt_pk_bf16_f32 v234, v156, v157
	v_pk_fma_f32 v[198:199], v[156:157], v[156:157], v[198:199]
	v_lshlrev_b32_e32 v158, 16, v234
	v_and_b32_e32 v159, 0xffff0000, v234
	v_pk_add_f32 v[196:197], v[156:157], v[158:159] neg_lo:[0,1] neg_hi:[0,1]
	v_cvt_pk_bf16_f32 v242, v196, v197
	v_lshlrev_b32_e32 v156, 16, v235
	v_and_b32_e32 v157, 0xffff0000, v235
	v_lshlrev_b32_e32 v158, 16, v243
	v_and_b32_e32 v159, 0xffff0000, v243
	v_pk_add_f32 v[156:157], v[156:157], v[158:159]
	v_pk_add_f32 v[156:157], v[120:121], v[156:157]
	v_cvt_pk_bf16_f32 v235, v156, v157
	v_pk_fma_f32 v[198:199], v[156:157], v[156:157], v[198:199]
	v_lshlrev_b32_e32 v158, 16, v235
	v_and_b32_e32 v159, 0xffff0000, v235
	v_pk_add_f32 v[196:197], v[156:157], v[158:159] neg_lo:[0,1] neg_hi:[0,1]
	v_cvt_pk_bf16_f32 v243, v196, v197
	v_lshlrev_b32_e32 v156, 16, v236
	v_and_b32_e32 v157, 0xffff0000, v236
	v_lshlrev_b32_e32 v158, 16, v244
	v_and_b32_e32 v159, 0xffff0000, v244
	v_pk_add_f32 v[156:157], v[156:157], v[158:159]
	v_pk_add_f32 v[156:157], v[114:115], v[156:157]
	v_cvt_pk_bf16_f32 v236, v156, v157
	v_pk_fma_f32 v[198:199], v[156:157], v[156:157], v[198:199]
	v_lshlrev_b32_e32 v158, 16, v236
	v_and_b32_e32 v159, 0xffff0000, v236
	v_pk_add_f32 v[196:197], v[156:157], v[158:159] neg_lo:[0,1] neg_hi:[0,1]
	v_cvt_pk_bf16_f32 v244, v196, v197
	v_lshlrev_b32_e32 v156, 16, v237
	v_and_b32_e32 v157, 0xffff0000, v237
	v_lshlrev_b32_e32 v158, 16, v245
	v_and_b32_e32 v159, 0xffff0000, v245
	v_pk_add_f32 v[156:157], v[156:157], v[158:159]
	v_pk_add_f32 v[156:157], v[116:117], v[156:157]
	v_cvt_pk_bf16_f32 v237, v156, v157
	v_pk_fma_f32 v[198:199], v[156:157], v[156:157], v[198:199]
	v_lshlrev_b32_e32 v158, 16, v237
	v_and_b32_e32 v159, 0xffff0000, v237
	v_pk_add_f32 v[196:197], v[156:157], v[158:159] neg_lo:[0,1] neg_hi:[0,1]
	v_cvt_pk_bf16_f32 v245, v196, v197
	global_store_dwordx4 v213, v[234:237], s[10:11] offset:256
	global_store_dwordx4 v213, v[242:245], s[14:15] offset:256
	v_add_f32_e32 v200, v198, v199
	s_waitcnt vmcnt(14)
; __device__ __forceinline__ unsigned pk2(float lo, float hi) { f32x2_t v = {lo, hi}; bf16x2_t b = __builtin_convertvector(v, bf16x2_t); return __builtin_bit_cast(unsigned, b); }
; __device__ __forceinline__ float bflo(unsigned u) { return __uint_as_float(u << 16); }
;     __device__ __forceinline__ void operator()(const f32x4 (&acc)[2][2][4][2], const Unit& u, int wr, int wc, int fr, int fq) const {
;     ...
;                 for (int bj = 0; bj < 2; ++bj) {
;                     const size_t off = (size_t)row * DM + col0 + bj * HALF;
;                     const u32x4 hh = *(const u32x4*)(HI + off), ll = *(const u32x4*)(LO + off);
;                     float hv[8] = {bflo(hh.x) + bflo(ll.x), bfhi(hh.x) + bfhi(ll.x), bflo(hh.y) + bflo(ll.y), bfhi(hh.y) + bfhi(ll.y),
;                                    bflo(hh.z) + bflo(ll.z), bfhi(hh.z) + bfhi(ll.z), bflo(hh.w) + bflo(ll.w), bfhi(hh.w) + bfhi(ll.w)};
;                     float av[8] = {acc[ai][bj][m][0][0], acc[ai][bj][m][0][1], acc[ai][bj][m][0][2], acc[ai][bj][m][0][3], acc[ai][bj][m][1][0], acc[ai][bj][m][1][1], acc[ai][bj][m][1][2], acc[ai][bj][m][1][3]};
;                     if (GATED) { const u32x4 pp = *(const u32x4*)(PP + off);
;                         const float pv[8] = {bflo(pp.x), bfhi(pp.x), bflo(pp.y), bfhi(pp.y), bflo(pp.z), bfhi(pp.z), bflo(pp.w), bfhi(pp.w)};
; #pragma unroll
;                         for (int e = 0; e < 8; ++e) av[e] = fast_sigmoid(av[e] * rs) * pv[e]; }
;                     else {
; #pragma unroll
;                         for (int e = 0; e < 8; ++e) av[e] *= alpha; }
;                     float lo[8];
; #pragma unroll
;                     for (int e = 0; e < 8; ++e) { hv[e] += av[e]; sq += hv[e] * hv[e]; }
;                     u32x4 wh; wh.x = pk2(hv[0], hv[1]); wh.y = pk2(hv[2], hv[3]); wh.z = pk2(hv[4], hv[5]); wh.w = pk2(hv[6], hv[7]);
;                     lo[0] = hv[0] - bflo(wh.x); lo[1] = hv[1] - bfhi(wh.x); lo[2] = hv[2] - bflo(wh.y); lo[3] = hv[3] - bfhi(wh.y);
;                     lo[4] = hv[4] - bflo(wh.z); lo[5] = hv[5] - bfhi(wh.z); lo[6] = hv[6] - bflo(wh.w); lo[7] = hv[7] - bfhi(wh.w);
;                     u32x4 wl; wl.x = pk2(lo[0], lo[1]); wl.y = pk2(lo[2], lo[3]); wl.z = pk2(lo[4], lo[5]); wl.w = pk2(lo[6], lo[7]);
;                     *(u32x4*)(HO + off) = wh; *(u32x4*)(LO + off) = wl;
;                 }
	v_lshlrev_b32_e32 v156, 16, v164
	v_and_b32_e32 v157, 0xffff0000, v164
	v_lshlrev_b32_e32 v158, 16, v168
	v_and_b32_e32 v159, 0xffff0000, v168
	v_pk_add_f32 v[156:157], v[156:157], v[158:159]
	v_pk_add_f32 v[156:157], v[110:111], v[156:157]
	v_cvt_pk_bf16_f32 v164, v156, v157
	v_pk_mul_f32 v[198:199], v[156:157], v[156:157]
	v_lshlrev_b32_e32 v158, 16, v164
	v_and_b32_e32 v159, 0xffff0000, v164
	v_pk_add_f32 v[196:197], v[156:157], v[158:159] neg_lo:[0,1] neg_hi:[0,1]
	v_cvt_pk_bf16_f32 v168, v196, v197
	v_lshlrev_b32_e32 v156, 16, v165
	v_and_b32_e32 v157, 0xffff0000, v165
	v_lshlrev_b32_e32 v158, 16, v169
	v_and_b32_e32 v159, 0xffff0000, v169
	v_pk_add_f32 v[156:157], v[156:157], v[158:159]
	v_pk_add_f32 v[156:157], v[112:113], v[156:157]
	v_cvt_pk_bf16_f32 v165, v156, v157
	v_pk_fma_f32 v[198:199], v[156:157], v[156:157], v[198:199]
	v_lshlrev_b32_e32 v158, 16, v165
	v_and_b32_e32 v159, 0xffff0000, v165
	v_pk_add_f32 v[196:197], v[156:157], v[158:159] neg_lo:[0,1] neg_hi:[0,1]
	v_cvt_pk_bf16_f32 v169, v196, v197
	v_lshlrev_b32_e32 v156, 16, v166
	v_and_b32_e32 v157, 0xffff0000, v166
	v_lshlrev_b32_e32 v158, 16, v170
	v_and_b32_e32 v159, 0xffff0000, v170
	v_pk_add_f32 v[156:157], v[156:157], v[158:159]
	v_pk_add_f32 v[156:157], v[106:107], v[156:157]
	v_cvt_pk_bf16_f32 v166, v156, v157
	v_pk_fma_f32 v[198:199], v[156:157], v[156:157], v[198:199]
	v_lshlrev_b32_e32 v158, 16, v166
	v_and_b32_e32 v159, 0xffff0000, v166
	v_pk_add_f32 v[196:197], v[156:157], v[158:159] neg_lo:[0,1] neg_hi:[0,1]
	v_cvt_pk_bf16_f32 v170, v196, v197
	v_lshlrev_b32_e32 v156, 16, v167
	v_and_b32_e32 v157, 0xffff0000, v167
	v_lshlrev_b32_e32 v158, 16, v171
	v_and_b32_e32 v159, 0xffff0000, v171
	v_pk_add_f32 v[156:157], v[156:157], v[158:159]
	v_pk_add_f32 v[156:157], v[108:109], v[156:157]
	v_cvt_pk_bf16_f32 v167, v156, v157
	v_pk_fma_f32 v[198:199], v[156:157], v[156:157], v[198:199]
	v_lshlrev_b32_e32 v158, 16, v167
	v_and_b32_e32 v159, 0xffff0000, v167
	v_pk_add_f32 v[196:197], v[156:157], v[158:159] neg_lo:[0,1] neg_hi:[0,1]
	v_cvt_pk_bf16_f32 v171, v196, v197
	global_store_dwordx4 v211, v[164:167], s[10:11]
	global_store_dwordx4 v211, v[168:171], s[14:15]
	s_waitcnt vmcnt(14)
	v_lshlrev_b32_e32 v156, 16, v172
	v_and_b32_e32 v157, 0xffff0000, v172
	v_lshlrev_b32_e32 v158, 16, v176
	v_and_b32_e32 v159, 0xffff0000, v176
	v_pk_add_f32 v[156:157], v[156:157], v[158:159]
	v_pk_add_f32 v[156:157], v[102:103], v[156:157]
	v_cvt_pk_bf16_f32 v172, v156, v157
	v_pk_fma_f32 v[198:199], v[156:157], v[156:157], v[198:199]
	v_lshlrev_b32_e32 v158, 16, v172
	v_and_b32_e32 v159, 0xffff0000, v172
	v_pk_add_f32 v[196:197], v[156:157], v[158:159] neg_lo:[0,1] neg_hi:[0,1]
	v_cvt_pk_bf16_f32 v176, v196, v197
	v_lshlrev_b32_e32 v156, 16, v173
	v_and_b32_e32 v157, 0xffff0000, v173
	v_lshlrev_b32_e32 v158, 16, v177
	v_and_b32_e32 v159, 0xffff0000, v177
	v_pk_add_f32 v[156:157], v[156:157], v[158:159]
	v_pk_add_f32 v[156:157], v[104:105], v[156:157]
	v_cvt_pk_bf16_f32 v173, v156, v157
	v_pk_fma_f32 v[198:199], v[156:157], v[156:157], v[198:199]
	v_lshlrev_b32_e32 v158, 16, v173
	v_and_b32_e32 v159, 0xffff0000, v173
	v_pk_add_f32 v[196:197], v[156:157], v[158:159] neg_lo:[0,1] neg_hi:[0,1]
	v_cvt_pk_bf16_f32 v177, v196, v197
	v_lshlrev_b32_e32 v156, 16, v174
	v_and_b32_e32 v157, 0xffff0000, v174
	v_lshlrev_b32_e32 v158, 16, v178
	v_and_b32_e32 v159, 0xffff0000, v178
	v_pk_add_f32 v[156:157], v[156:157], v[158:159]
	v_pk_add_f32 v[156:157], v[98:99], v[156:157]
	v_cvt_pk_bf16_f32 v174, v156, v157
	v_pk_fma_f32 v[198:199], v[156:157], v[156:157], v[198:199]
	v_lshlrev_b32_e32 v158, 16, v174
	v_and_b32_e32 v159, 0xffff0000, v174
	v_pk_add_f32 v[196:197], v[156:157], v[158:159] neg_lo:[0,1] neg_hi:[0,1]
	v_cvt_pk_bf16_f32 v178, v196, v197
	v_lshlrev_b32_e32 v156, 16, v175
	v_and_b32_e32 v157, 0xffff0000, v175
	v_lshlrev_b32_e32 v158, 16, v179
	v_and_b32_e32 v159, 0xffff0000, v179
	v_pk_add_f32 v[156:157], v[156:157], v[158:159]
	v_pk_add_f32 v[156:157], v[100:101], v[156:157]
	v_cvt_pk_bf16_f32 v175, v156, v157
	v_pk_fma_f32 v[198:199], v[156:157], v[156:157], v[198:199]
	v_lshlrev_b32_e32 v158, 16, v175
	v_and_b32_e32 v159, 0xffff0000, v175
	v_pk_add_f32 v[196:197], v[156:157], v[158:159] neg_lo:[0,1] neg_hi:[0,1]
	v_cvt_pk_bf16_f32 v179, v196, v197
	global_store_dwordx4 v211, v[172:175], s[10:11] offset:256
	global_store_dwordx4 v211, v[176:179], s[14:15] offset:256
	v_add_f32_e32 v201, v198, v199
	s_nop 0
	v_add_u32_e32 v211, 0x40000, v213
	global_load_dwordx4 v[164:167], v211, s[10:11]
	global_load_dwordx4 v[168:171], v211, s[14:15]
	global_load_dwordx4 v[172:175], v211, s[10:11] offset:256
	global_load_dwordx4 v[176:179], v211, s[14:15] offset:256
	s_waitcnt vmcnt(18)
; __device__ __forceinline__ unsigned pk2(float lo, float hi) { f32x2_t v = {lo, hi}; bf16x2_t b = __builtin_convertvector(v, bf16x2_t); return __builtin_bit_cast(unsigned, b); }
; __device__ __forceinline__ float bflo(unsigned u) { return __uint_as_float(u << 16); }
;     __device__ __forceinline__ void operator()(const f32x4 (&acc)[2][2][4][2], const Unit& u, int wr, int wc, int fr, int fq) const {
;     ...
;                 for (int bj = 0; bj < 2; ++bj) {
;                     const size_t off = (size_t)row * DM + col0 + bj * HALF;
;                     const u32x4 hh = *(const u32x4*)(HI + off), ll = *(const u32x4*)(LO + off);
;                     float hv[8] = {bflo(hh.x) + bflo(ll.x), bfhi(hh.x) + bfhi(ll.x), bflo(hh.y) + bflo(ll.y), bfhi(hh.y) + bfhi(ll.y),
;                                    bflo(hh.z) + bflo(ll.z), bfhi(hh.z) + bfhi(ll.z), bflo(hh.w) + bflo(ll.w), bfhi(hh.w) + bfhi(ll.w)};
;                     float av[8] = {acc[ai][bj][m][0][0], acc[ai][bj][m][0][1], acc[ai][bj][m][0][2], acc[ai][bj][m][0][3], acc[ai][bj][m][1][0], acc[ai][bj][m][1][1], acc[ai][bj][m][1][2], acc[ai][bj][m][1][3]};
;                     if (GATED) { const u32x4 pp = *(const u32x4*)(PP + off);
;                         const float pv[8] = {bflo(pp.x), bfhi(pp.x), bflo(pp.y), bfhi(pp.y), bflo(pp.z), bfhi(pp.z), bflo(pp.w), bfhi(pp.w)};
; #pragma unroll
;                         for (int e = 0; e < 8; ++e) av[e] = fast_sigmoid(av[e] * rs) * pv[e]; }
;                     else {
; #pragma unroll
;                         for (int e = 0; e < 8; ++e) av[e] *= alpha; }
;                     float lo[8];
; #pragma unroll
;                     for (int e = 0; e < 8; ++e) { hv[e] += av[e]; sq += hv[e] * hv[e]; }
;                     u32x4 wh; wh.x = pk2(hv[0], hv[1]); wh.y = pk2(hv[2], hv[3]); wh.z = pk2(hv[4], hv[5]); wh.w = pk2(hv[6], hv[7]);
;                     lo[0] = hv[0] - bflo(wh.x); lo[1] = hv[1] - bfhi(wh.x); lo[2] = hv[2] - bflo(wh.y); lo[3] = hv[3] - bfhi(wh.y);
;                     lo[4] = hv[4] - bflo(wh.z); lo[5] = hv[5] - bfhi(wh.z); lo[6] = hv[6] - bflo(wh.w); lo[7] = hv[7] - bfhi(wh.w);
;                     u32x4 wl; wl.x = pk2(lo[0], lo[1]); wl.y = pk2(lo[2], lo[3]); wl.z = pk2(lo[4], lo[5]); wl.w = pk2(lo[6], lo[7]);
;                     *(u32x4*)(HO + off) = wh; *(u32x4*)(LO + off) = wl;
;                 }
	v_lshlrev_b32_e32 v156, 16, v180
	v_and_b32_e32 v157, 0xffff0000, v180
	v_lshlrev_b32_e32 v158, 16, v184
	v_and_b32_e32 v159, 0xffff0000, v184
	v_pk_add_f32 v[156:157], v[156:157], v[158:159]
	v_pk_add_f32 v[156:157], v[94:95], v[156:157]
	v_cvt_pk_bf16_f32 v180, v156, v157
	v_pk_mul_f32 v[198:199], v[156:157], v[156:157]
	v_lshlrev_b32_e32 v158, 16, v180
	v_and_b32_e32 v159, 0xffff0000, v180
	v_pk_add_f32 v[196:197], v[156:157], v[158:159] neg_lo:[0,1] neg_hi:[0,1]
	v_cvt_pk_bf16_f32 v184, v196, v197
	v_lshlrev_b32_e32 v156, 16, v181
	v_and_b32_e32 v157, 0xffff0000, v181
	v_lshlrev_b32_e32 v158, 16, v185
	v_and_b32_e32 v159, 0xffff0000, v185
	v_pk_add_f32 v[156:157], v[156:157], v[158:159]
	v_pk_add_f32 v[156:157], v[96:97], v[156:157]
	v_cvt_pk_bf16_f32 v181, v156, v157
	v_pk_fma_f32 v[198:199], v[156:157], v[156:157], v[198:199]
	v_lshlrev_b32_e32 v158, 16, v181
	v_and_b32_e32 v159, 0xffff0000, v181
	v_pk_add_f32 v[196:197], v[156:157], v[158:159] neg_lo:[0,1] neg_hi:[0,1]
	v_cvt_pk_bf16_f32 v185, v196, v197
	v_lshlrev_b32_e32 v156, 16, v182
	v_and_b32_e32 v157, 0xffff0000, v182
	v_lshlrev_b32_e32 v158, 16, v186
	v_and_b32_e32 v159, 0xffff0000, v186
	v_pk_add_f32 v[156:157], v[156:157], v[158:159]
	v_pk_add_f32 v[156:157], v[90:91], v[156:157]
	v_cvt_pk_bf16_f32 v182, v156, v157
	v_pk_fma_f32 v[198:199], v[156:157], v[156:157], v[198:199]
	v_lshlrev_b32_e32 v158, 16, v182
	v_and_b32_e32 v159, 0xffff0000, v182
	v_pk_add_f32 v[196:197], v[156:157], v[158:159] neg_lo:[0,1] neg_hi:[0,1]
	v_cvt_pk_bf16_f32 v186, v196, v197
	v_lshlrev_b32_e32 v156, 16, v183
	v_and_b32_e32 v157, 0xffff0000, v183
	v_lshlrev_b32_e32 v158, 16, v187
	v_and_b32_e32 v159, 0xffff0000, v187
	v_pk_add_f32 v[156:157], v[156:157], v[158:159]
	v_pk_add_f32 v[156:157], v[92:93], v[156:157]
	v_cvt_pk_bf16_f32 v183, v156, v157
	v_pk_fma_f32 v[198:199], v[156:157], v[156:157], v[198:199]
	v_lshlrev_b32_e32 v158, 16, v183
	v_and_b32_e32 v159, 0xffff0000, v183
	v_pk_add_f32 v[196:197], v[156:157], v[158:159] neg_lo:[0,1] neg_hi:[0,1]
	v_cvt_pk_bf16_f32 v187, v196, v197
	global_store_dwordx4 v212, v[180:183], s[10:11]
	global_store_dwordx4 v212, v[184:187], s[14:15]
	s_waitcnt vmcnt(18)
	v_lshlrev_b32_e32 v156, 16, v188
	v_and_b32_e32 v157, 0xffff0000, v188
	v_lshlrev_b32_e32 v158, 16, v192
	v_and_b32_e32 v159, 0xffff0000, v192
	v_pk_add_f32 v[156:157], v[156:157], v[158:159]
	v_pk_add_f32 v[156:157], v[86:87], v[156:157]
	v_cvt_pk_bf16_f32 v188, v156, v157
	v_pk_fma_f32 v[198:199], v[156:157], v[156:157], v[198:199]
	v_lshlrev_b32_e32 v158, 16, v188
	v_and_b32_e32 v159, 0xffff0000, v188
	v_pk_add_f32 v[196:197], v[156:157], v[158:159] neg_lo:[0,1] neg_hi:[0,1]
	v_cvt_pk_bf16_f32 v192, v196, v197
	v_lshlrev_b32_e32 v156, 16, v189
	v_and_b32_e32 v157, 0xffff0000, v189
	v_lshlrev_b32_e32 v158, 16, v193
	v_and_b32_e32 v159, 0xffff0000, v193
	v_pk_add_f32 v[156:157], v[156:157], v[158:159]
	v_pk_add_f32 v[156:157], v[88:89], v[156:157]
	v_cvt_pk_bf16_f32 v189, v156, v157
	v_pk_fma_f32 v[198:199], v[156:157], v[156:157], v[198:199]
	v_lshlrev_b32_e32 v158, 16, v189
	v_and_b32_e32 v159, 0xffff0000, v189
	v_pk_add_f32 v[196:197], v[156:157], v[158:159] neg_lo:[0,1] neg_hi:[0,1]
	v_cvt_pk_bf16_f32 v193, v196, v197
	v_lshlrev_b32_e32 v156, 16, v190
	v_and_b32_e32 v157, 0xffff0000, v190
	v_lshlrev_b32_e32 v158, 16, v194
	v_and_b32_e32 v159, 0xffff0000, v194
	v_pk_add_f32 v[156:157], v[156:157], v[158:159]
	v_pk_add_f32 v[156:157], v[82:83], v[156:157]
	v_cvt_pk_bf16_f32 v190, v156, v157
	v_pk_fma_f32 v[198:199], v[156:157], v[156:157], v[198:199]
	v_lshlrev_b32_e32 v158, 16, v190
	v_and_b32_e32 v159, 0xffff0000, v190
	v_pk_add_f32 v[196:197], v[156:157], v[158:159] neg_lo:[0,1] neg_hi:[0,1]
	v_cvt_pk_bf16_f32 v194, v196, v197
	v_lshlrev_b32_e32 v156, 16, v191
	v_and_b32_e32 v157, 0xffff0000, v191
	v_lshlrev_b32_e32 v158, 16, v195
	v_and_b32_e32 v159, 0xffff0000, v195
	v_pk_add_f32 v[156:157], v[156:157], v[158:159]
	v_pk_add_f32 v[156:157], v[84:85], v[156:157]
	v_cvt_pk_bf16_f32 v191, v156, v157
	v_pk_fma_f32 v[198:199], v[156:157], v[156:157], v[198:199]
	v_lshlrev_b32_e32 v158, 16, v191
	v_and_b32_e32 v159, 0xffff0000, v191
	v_pk_add_f32 v[196:197], v[156:157], v[158:159] neg_lo:[0,1] neg_hi:[0,1]
	v_cvt_pk_bf16_f32 v195, v196, v197
	global_store_dwordx4 v212, v[188:191], s[10:11] offset:256
	global_store_dwordx4 v212, v[192:195], s[14:15] offset:256
	v_add_f32_e32 v202, v198, v199
	s_nop 0
	v_add_u32_e32 v212, 0x48000, v213
	global_load_dwordx4 v[180:183], v212, s[10:11]
	global_load_dwordx4 v[184:187], v212, s[14:15]
	global_load_dwordx4 v[188:191], v212, s[10:11] offset:256
	global_load_dwordx4 v[192:195], v212, s[14:15] offset:256
	s_waitcnt vmcnt(22)
; __device__ __forceinline__ unsigned pk2(float lo, float hi) { f32x2_t v = {lo, hi}; bf16x2_t b = __builtin_convertvector(v, bf16x2_t); return __builtin_bit_cast(unsigned, b); }
; __device__ __forceinline__ float bflo(unsigned u) { return __uint_as_float(u << 16); }
;     __device__ __forceinline__ void operator()(const f32x4 (&acc)[2][2][4][2], const Unit& u, int wr, int wc, int fr, int fq) const {
;     ...
;                 for (int bj = 0; bj < 2; ++bj) {
;                     const size_t off = (size_t)row * DM + col0 + bj * HALF;
;                     const u32x4 hh = *(const u32x4*)(HI + off), ll = *(const u32x4*)(LO + off);
;                     float hv[8] = {bflo(hh.x) + bflo(ll.x), bfhi(hh.x) + bfhi(ll.x), bflo(hh.y) + bflo(ll.y), bfhi(hh.y) + bfhi(ll.y),
;                                    bflo(hh.z) + bflo(ll.z), bfhi(hh.z) + bfhi(ll.z), bflo(hh.w) + bflo(ll.w), bfhi(hh.w) + bfhi(ll.w)};
;                     float av[8] = {acc[ai][bj][m][0][0], acc[ai][bj][m][0][1], acc[ai][bj][m][0][2], acc[ai][bj][m][0][3], acc[ai][bj][m][1][0], acc[ai][bj][m][1][1], acc[ai][bj][m][1][2], acc[ai][bj][m][1][3]};
;                     if (GATED) { const u32x4 pp = *(const u32x4*)(PP + off);
;                         const float pv[8] = {bflo(pp.x), bfhi(pp.x), bflo(pp.y), bfhi(pp.y), bflo(pp.z), bfhi(pp.z), bflo(pp.w), bfhi(pp.w)};
; #pragma unroll
;                         for (int e = 0; e < 8; ++e) av[e] = fast_sigmoid(av[e] * rs) * pv[e]; }
;                     else {
; #pragma unroll
;                         for (int e = 0; e < 8; ++e) av[e] *= alpha; }
;                     float lo[8];
; #pragma unroll
;                     for (int e = 0; e < 8; ++e) { hv[e] += av[e]; sq += hv[e] * hv[e]; }
;                     u32x4 wh; wh.x = pk2(hv[0], hv[1]); wh.y = pk2(hv[2], hv[3]); wh.z = pk2(hv[4], hv[5]); wh.w = pk2(hv[6], hv[7]);
;                     lo[0] = hv[0] - bflo(wh.x); lo[1] = hv[1] - bfhi(wh.x); lo[2] = hv[2] - bflo(wh.y); lo[3] = hv[3] - bfhi(wh.y);
;                     lo[4] = hv[4] - bflo(wh.z); lo[5] = hv[5] - bfhi(wh.z); lo[6] = hv[6] - bflo(wh.w); lo[7] = hv[7] - bfhi(wh.w);
;                     u32x4 wl; wl.x = pk2(lo[0], lo[1]); wl.y = pk2(lo[2], lo[3]); wl.z = pk2(lo[4], lo[5]); wl.w = pk2(lo[6], lo[7]);
;                     *(u32x4*)(HO + off) = wh; *(u32x4*)(LO + off) = wl;
;                 }
	v_lshlrev_b32_e32 v156, 16, v140
	v_and_b32_e32 v157, 0xffff0000, v140
	v_lshlrev_b32_e32 v158, 16, v144
	v_and_b32_e32 v159, 0xffff0000, v144
	v_pk_add_f32 v[156:157], v[156:157], v[158:159]
	v_pk_add_f32 v[156:157], v[78:79], v[156:157]
	v_cvt_pk_bf16_f32 v140, v156, v157
	v_pk_mul_f32 v[198:199], v[156:157], v[156:157]
	v_lshlrev_b32_e32 v158, 16, v140
	v_and_b32_e32 v159, 0xffff0000, v140
	v_pk_add_f32 v[196:197], v[156:157], v[158:159] neg_lo:[0,1] neg_hi:[0,1]
	v_cvt_pk_bf16_f32 v144, v196, v197
	v_lshlrev_b32_e32 v156, 16, v141
	v_and_b32_e32 v157, 0xffff0000, v141
	v_lshlrev_b32_e32 v158, 16, v145
	v_and_b32_e32 v159, 0xffff0000, v145
	v_pk_add_f32 v[156:157], v[156:157], v[158:159]
	v_pk_add_f32 v[156:157], v[80:81], v[156:157]
	v_cvt_pk_bf16_f32 v141, v156, v157
	v_pk_fma_f32 v[198:199], v[156:157], v[156:157], v[198:199]
	v_lshlrev_b32_e32 v158, 16, v141
	v_and_b32_e32 v159, 0xffff0000, v141
	v_pk_add_f32 v[196:197], v[156:157], v[158:159] neg_lo:[0,1] neg_hi:[0,1]
	v_cvt_pk_bf16_f32 v145, v196, v197
	v_lshlrev_b32_e32 v156, 16, v142
	v_and_b32_e32 v157, 0xffff0000, v142
	v_lshlrev_b32_e32 v158, 16, v146
	v_and_b32_e32 v159, 0xffff0000, v146
	v_pk_add_f32 v[156:157], v[156:157], v[158:159]
	v_pk_add_f32 v[156:157], v[74:75], v[156:157]
	v_cvt_pk_bf16_f32 v142, v156, v157
	v_pk_fma_f32 v[198:199], v[156:157], v[156:157], v[198:199]
	v_lshlrev_b32_e32 v158, 16, v142
	v_and_b32_e32 v159, 0xffff0000, v142
	v_pk_add_f32 v[196:197], v[156:157], v[158:159] neg_lo:[0,1] neg_hi:[0,1]
	v_cvt_pk_bf16_f32 v146, v196, v197
	v_lshlrev_b32_e32 v156, 16, v143
	v_and_b32_e32 v157, 0xffff0000, v143
	v_lshlrev_b32_e32 v158, 16, v147
	v_and_b32_e32 v159, 0xffff0000, v147
	v_pk_add_f32 v[156:157], v[156:157], v[158:159]
	v_pk_add_f32 v[156:157], v[76:77], v[156:157]
	v_cvt_pk_bf16_f32 v143, v156, v157
	v_pk_fma_f32 v[198:199], v[156:157], v[156:157], v[198:199]
	v_lshlrev_b32_e32 v158, 16, v143
	v_and_b32_e32 v159, 0xffff0000, v143
	v_pk_add_f32 v[196:197], v[156:157], v[158:159] neg_lo:[0,1] neg_hi:[0,1]
	v_cvt_pk_bf16_f32 v147, v196, v197
	global_store_dwordx4 v210, v[140:143], s[10:11]
	global_store_dwordx4 v210, v[144:147], s[14:15]
	s_waitcnt vmcnt(22)
	v_lshlrev_b32_e32 v156, 16, v148
	v_and_b32_e32 v157, 0xffff0000, v148
	v_lshlrev_b32_e32 v158, 16, v152
	v_and_b32_e32 v159, 0xffff0000, v152
	v_pk_add_f32 v[156:157], v[156:157], v[158:159]
	v_pk_add_f32 v[156:157], v[70:71], v[156:157]
	v_cvt_pk_bf16_f32 v148, v156, v157
	v_pk_fma_f32 v[198:199], v[156:157], v[156:157], v[198:199]
	v_lshlrev_b32_e32 v158, 16, v148
	v_and_b32_e32 v159, 0xffff0000, v148
	v_pk_add_f32 v[196:197], v[156:157], v[158:159] neg_lo:[0,1] neg_hi:[0,1]
	v_cvt_pk_bf16_f32 v152, v196, v197
	v_lshlrev_b32_e32 v156, 16, v149
	v_and_b32_e32 v157, 0xffff0000, v149
	v_lshlrev_b32_e32 v158, 16, v153
	v_and_b32_e32 v159, 0xffff0000, v153
	v_pk_add_f32 v[156:157], v[156:157], v[158:159]
	v_pk_add_f32 v[156:157], v[72:73], v[156:157]
	v_cvt_pk_bf16_f32 v149, v156, v157
	v_pk_fma_f32 v[198:199], v[156:157], v[156:157], v[198:199]
	v_lshlrev_b32_e32 v158, 16, v149
	v_and_b32_e32 v159, 0xffff0000, v149
	v_pk_add_f32 v[196:197], v[156:157], v[158:159] neg_lo:[0,1] neg_hi:[0,1]
	v_cvt_pk_bf16_f32 v153, v196, v197
	v_lshlrev_b32_e32 v156, 16, v150
	v_and_b32_e32 v157, 0xffff0000, v150
	v_lshlrev_b32_e32 v158, 16, v154
	v_and_b32_e32 v159, 0xffff0000, v154
	v_pk_add_f32 v[156:157], v[156:157], v[158:159]
	v_pk_add_f32 v[156:157], v[66:67], v[156:157]
	v_cvt_pk_bf16_f32 v150, v156, v157
	v_pk_fma_f32 v[198:199], v[156:157], v[156:157], v[198:199]
	v_lshlrev_b32_e32 v158, 16, v150
	v_and_b32_e32 v159, 0xffff0000, v150
	v_pk_add_f32 v[196:197], v[156:157], v[158:159] neg_lo:[0,1] neg_hi:[0,1]
	v_cvt_pk_bf16_f32 v154, v196, v197
	v_lshlrev_b32_e32 v156, 16, v151
	v_and_b32_e32 v157, 0xffff0000, v151
	v_lshlrev_b32_e32 v158, 16, v155
	v_and_b32_e32 v159, 0xffff0000, v155
	v_pk_add_f32 v[156:157], v[156:157], v[158:159]
	v_pk_add_f32 v[156:157], v[68:69], v[156:157]
	v_cvt_pk_bf16_f32 v151, v156, v157
	v_pk_fma_f32 v[198:199], v[156:157], v[156:157], v[198:199]
	v_lshlrev_b32_e32 v158, 16, v151
	v_and_b32_e32 v159, 0xffff0000, v151
	v_pk_add_f32 v[196:197], v[156:157], v[158:159] neg_lo:[0,1] neg_hi:[0,1]
	v_cvt_pk_bf16_f32 v155, v196, v197
	global_store_dwordx4 v210, v[148:151], s[10:11] offset:256
	global_store_dwordx4 v210, v[152:155], s[14:15] offset:256
	v_add_f32_e32 v203, v198, v199
	s_nop 0
	v_add_u32_e32 v210, 0x50000, v213
	global_load_dwordx4 v[140:143], v210, s[10:11]
	global_load_dwordx4 v[144:147], v210, s[14:15]
	global_load_dwordx4 v[148:151], v210, s[10:11] offset:256
	global_load_dwordx4 v[152:155], v210, s[14:15] offset:256
	s_waitcnt vmcnt(18)
; __device__ __forceinline__ unsigned pk2(float lo, float hi) { f32x2_t v = {lo, hi}; bf16x2_t b = __builtin_convertvector(v, bf16x2_t); return __builtin_bit_cast(unsigned, b); }
; __device__ __forceinline__ float bflo(unsigned u) { return __uint_as_float(u << 16); }
;     __device__ __forceinline__ void operator()(const f32x4 (&acc)[2][2][4][2], const Unit& u, int wr, int wc, int fr, int fq) const {
;     ...
;                 for (int bj = 0; bj < 2; ++bj) {
;                     const size_t off = (size_t)row * DM + col0 + bj * HALF;
;                     const u32x4 hh = *(const u32x4*)(HI + off), ll = *(const u32x4*)(LO + off);
;                     float hv[8] = {bflo(hh.x) + bflo(ll.x), bfhi(hh.x) + bfhi(ll.x), bflo(hh.y) + bflo(ll.y), bfhi(hh.y) + bfhi(ll.y),
;                                    bflo(hh.z) + bflo(ll.z), bfhi(hh.z) + bfhi(ll.z), bflo(hh.w) + bflo(ll.w), bfhi(hh.w) + bfhi(ll.w)};
;                     float av[8] = {acc[ai][bj][m][0][0], acc[ai][bj][m][0][1], acc[ai][bj][m][0][2], acc[ai][bj][m][0][3], acc[ai][bj][m][1][0], acc[ai][bj][m][1][1], acc[ai][bj][m][1][2], acc[ai][bj][m][1][3]};
;                     if (GATED) { const u32x4 pp = *(const u32x4*)(PP + off);
;                         const float pv[8] = {bflo(pp.x), bfhi(pp.x), bflo(pp.y), bfhi(pp.y), bflo(pp.z), bfhi(pp.z), bflo(pp.w), bfhi(pp.w)};
; #pragma unroll
;                         for (int e = 0; e < 8; ++e) av[e] = fast_sigmoid(av[e] * rs) * pv[e]; }
;                     else {
; #pragma unroll
;                         for (int e = 0; e < 8; ++e) av[e] *= alpha; }
;                     float lo[8];
; #pragma unroll
;                     for (int e = 0; e < 8; ++e) { hv[e] += av[e]; sq += hv[e] * hv[e]; }
;                     u32x4 wh; wh.x = pk2(hv[0], hv[1]); wh.y = pk2(hv[2], hv[3]); wh.z = pk2(hv[4], hv[5]); wh.w = pk2(hv[6], hv[7]);
;                     lo[0] = hv[0] - bflo(wh.x); lo[1] = hv[1] - bfhi(wh.x); lo[2] = hv[2] - bflo(wh.y); lo[3] = hv[3] - bfhi(wh.y);
;                     lo[4] = hv[4] - bflo(wh.z); lo[5] = hv[5] - bfhi(wh.z); lo[6] = hv[6] - bflo(wh.w); lo[7] = hv[7] - bfhi(wh.w);
;                     u32x4 wl; wl.x = pk2(lo[0], lo[1]); wl.y = pk2(lo[2], lo[3]); wl.z = pk2(lo[4], lo[5]); wl.w = pk2(lo[6], lo[7]);
;                     *(u32x4*)(HO + off) = wh; *(u32x4*)(LO + off) = wl;
;                 }
	v_lshlrev_b32_e32 v156, 16, v164
	v_and_b32_e32 v157, 0xffff0000, v164
	v_lshlrev_b32_e32 v158, 16, v168
	v_and_b32_e32 v159, 0xffff0000, v168
	v_pk_add_f32 v[156:157], v[156:157], v[158:159]
	v_pk_add_f32 v[156:157], v[62:63], v[156:157]
	v_cvt_pk_bf16_f32 v164, v156, v157
	v_pk_mul_f32 v[198:199], v[156:157], v[156:157]
	v_lshlrev_b32_e32 v158, 16, v164
	v_and_b32_e32 v159, 0xffff0000, v164
	v_pk_add_f32 v[196:197], v[156:157], v[158:159] neg_lo:[0,1] neg_hi:[0,1]
	v_cvt_pk_bf16_f32 v168, v196, v197
	v_lshlrev_b32_e32 v156, 16, v165
	v_and_b32_e32 v157, 0xffff0000, v165
	v_lshlrev_b32_e32 v158, 16, v169
	v_and_b32_e32 v159, 0xffff0000, v169
	v_pk_add_f32 v[156:157], v[156:157], v[158:159]
	v_pk_add_f32 v[156:157], v[64:65], v[156:157]
	v_cvt_pk_bf16_f32 v165, v156, v157
	v_pk_fma_f32 v[198:199], v[156:157], v[156:157], v[198:199]
	v_lshlrev_b32_e32 v158, 16, v165
	v_and_b32_e32 v159, 0xffff0000, v165
	v_pk_add_f32 v[196:197], v[156:157], v[158:159] neg_lo:[0,1] neg_hi:[0,1]
	v_cvt_pk_bf16_f32 v169, v196, v197
	v_lshlrev_b32_e32 v156, 16, v166
	v_and_b32_e32 v157, 0xffff0000, v166
	v_lshlrev_b32_e32 v158, 16, v170
	v_and_b32_e32 v159, 0xffff0000, v170
	v_pk_add_f32 v[156:157], v[156:157], v[158:159]
	v_pk_add_f32 v[156:157], v[58:59], v[156:157]
	v_cvt_pk_bf16_f32 v166, v156, v157
	v_pk_fma_f32 v[198:199], v[156:157], v[156:157], v[198:199]
	v_lshlrev_b32_e32 v158, 16, v166
	v_and_b32_e32 v159, 0xffff0000, v166
	v_pk_add_f32 v[196:197], v[156:157], v[158:159] neg_lo:[0,1] neg_hi:[0,1]
	v_cvt_pk_bf16_f32 v170, v196, v197
	v_lshlrev_b32_e32 v156, 16, v167
	v_and_b32_e32 v157, 0xffff0000, v167
	v_lshlrev_b32_e32 v158, 16, v171
	v_and_b32_e32 v159, 0xffff0000, v171
	v_pk_add_f32 v[156:157], v[156:157], v[158:159]
	v_pk_add_f32 v[156:157], v[60:61], v[156:157]
	v_cvt_pk_bf16_f32 v167, v156, v157
	v_pk_fma_f32 v[198:199], v[156:157], v[156:157], v[198:199]
	v_lshlrev_b32_e32 v158, 16, v167
	v_and_b32_e32 v159, 0xffff0000, v167
	v_pk_add_f32 v[196:197], v[156:157], v[158:159] neg_lo:[0,1] neg_hi:[0,1]
	v_cvt_pk_bf16_f32 v171, v196, v197
	global_store_dwordx4 v211, v[164:167], s[10:11]
	global_store_dwordx4 v211, v[168:171], s[14:15]
	s_waitcnt vmcnt(18)
	v_lshlrev_b32_e32 v156, 16, v172
	v_and_b32_e32 v157, 0xffff0000, v172
	v_lshlrev_b32_e32 v158, 16, v176
	v_and_b32_e32 v159, 0xffff0000, v176
	v_pk_add_f32 v[156:157], v[156:157], v[158:159]
	v_pk_add_f32 v[156:157], v[54:55], v[156:157]
	v_cvt_pk_bf16_f32 v172, v156, v157
	v_pk_fma_f32 v[198:199], v[156:157], v[156:157], v[198:199]
	v_lshlrev_b32_e32 v158, 16, v172
	v_and_b32_e32 v159, 0xffff0000, v172
	v_pk_add_f32 v[196:197], v[156:157], v[158:159] neg_lo:[0,1] neg_hi:[0,1]
	v_cvt_pk_bf16_f32 v176, v196, v197
	v_lshlrev_b32_e32 v156, 16, v173
	v_and_b32_e32 v157, 0xffff0000, v173
	v_lshlrev_b32_e32 v158, 16, v177
	v_and_b32_e32 v159, 0xffff0000, v177
	v_pk_add_f32 v[156:157], v[156:157], v[158:159]
	v_pk_add_f32 v[156:157], v[56:57], v[156:157]
	v_cvt_pk_bf16_f32 v173, v156, v157
	v_pk_fma_f32 v[198:199], v[156:157], v[156:157], v[198:199]
	v_lshlrev_b32_e32 v158, 16, v173
	v_and_b32_e32 v159, 0xffff0000, v173
	v_pk_add_f32 v[196:197], v[156:157], v[158:159] neg_lo:[0,1] neg_hi:[0,1]
	v_cvt_pk_bf16_f32 v177, v196, v197
	v_lshlrev_b32_e32 v156, 16, v174
	v_and_b32_e32 v157, 0xffff0000, v174
	v_lshlrev_b32_e32 v158, 16, v178
	v_and_b32_e32 v159, 0xffff0000, v178
	v_pk_add_f32 v[156:157], v[156:157], v[158:159]
	v_pk_add_f32 v[156:157], v[50:51], v[156:157]
	v_cvt_pk_bf16_f32 v174, v156, v157
	v_pk_fma_f32 v[198:199], v[156:157], v[156:157], v[198:199]
	v_lshlrev_b32_e32 v158, 16, v174
	v_and_b32_e32 v159, 0xffff0000, v174
	v_pk_add_f32 v[196:197], v[156:157], v[158:159] neg_lo:[0,1] neg_hi:[0,1]
	v_cvt_pk_bf16_f32 v178, v196, v197
	v_lshlrev_b32_e32 v156, 16, v175
	v_and_b32_e32 v157, 0xffff0000, v175
	v_lshlrev_b32_e32 v158, 16, v179
	v_and_b32_e32 v159, 0xffff0000, v179
	v_pk_add_f32 v[156:157], v[156:157], v[158:159]
	v_pk_add_f32 v[156:157], v[52:53], v[156:157]
	v_cvt_pk_bf16_f32 v175, v156, v157
	v_pk_fma_f32 v[198:199], v[156:157], v[156:157], v[198:199]
	v_lshlrev_b32_e32 v158, 16, v175
	v_and_b32_e32 v159, 0xffff0000, v175
	v_pk_add_f32 v[196:197], v[156:157], v[158:159] neg_lo:[0,1] neg_hi:[0,1]
	v_cvt_pk_bf16_f32 v179, v196, v197
	global_store_dwordx4 v211, v[172:175], s[10:11] offset:256
	global_store_dwordx4 v211, v[176:179], s[14:15] offset:256
	v_add_f32_e32 v206, v198, v199
	s_nop 0
	v_add_u32_e32 v211, 0x58000, v213
	global_load_dwordx4 v[164:167], v211, s[10:11]
	global_load_dwordx4 v[168:171], v211, s[14:15]
	global_load_dwordx4 v[172:175], v211, s[10:11] offset:256
	global_load_dwordx4 v[176:179], v211, s[14:15] offset:256
	s_waitcnt vmcnt(18)
; __device__ __forceinline__ unsigned pk2(float lo, float hi) { f32x2_t v = {lo, hi}; bf16x2_t b = __builtin_convertvector(v, bf16x2_t); return __builtin_bit_cast(unsigned, b); }
; __device__ __forceinline__ float bflo(unsigned u) { return __uint_as_float(u << 16); }
;     __device__ __forceinline__ void operator()(const f32x4 (&acc)[2][2][4][2], const Unit& u, int wr, int wc, int fr, int fq) const {
;     ...
;                 for (int bj = 0; bj < 2; ++bj) {
;                     const size_t off = (size_t)row * DM + col0 + bj * HALF;
;                     const u32x4 hh = *(const u32x4*)(HI + off), ll = *(const u32x4*)(LO + off);
;                     float hv[8] = {bflo(hh.x) + bflo(ll.x), bfhi(hh.x) + bfhi(ll.x), bflo(hh.y) + bflo(ll.y), bfhi(hh.y) + bfhi(ll.y),
;                                    bflo(hh.z) + bflo(ll.z), bfhi(hh.z) + bfhi(ll.z), bflo(hh.w) + bflo(ll.w), bfhi(hh.w) + bfhi(ll.w)};
;                     float av[8] = {acc[ai][bj][m][0][0], acc[ai][bj][m][0][1], acc[ai][bj][m][0][2], acc[ai][bj][m][0][3], acc[ai][bj][m][1][0], acc[ai][bj][m][1][1], acc[ai][bj][m][1][2], acc[ai][bj][m][1][3]};
;                     if (GATED) { const u32x4 pp = *(const u32x4*)(PP + off);
;                         const float pv[8] = {bflo(pp.x), bfhi(pp.x), bflo(pp.y), bfhi(pp.y), bflo(pp.z), bfhi(pp.z), bflo(pp.w), bfhi(pp.w)};
; #pragma unroll
;                         for (int e = 0; e < 8; ++e) av[e] = fast_sigmoid(av[e] * rs) * pv[e]; }
;                     else {
; #pragma unroll
;                         for (int e = 0; e < 8; ++e) av[e] *= alpha; }
;                     float lo[8];
; #pragma unroll
;                     for (int e = 0; e < 8; ++e) { hv[e] += av[e]; sq += hv[e] * hv[e]; }
;                     u32x4 wh; wh.x = pk2(hv[0], hv[1]); wh.y = pk2(hv[2], hv[3]); wh.z = pk2(hv[4], hv[5]); wh.w = pk2(hv[6], hv[7]);
;                     lo[0] = hv[0] - bflo(wh.x); lo[1] = hv[1] - bfhi(wh.x); lo[2] = hv[2] - bflo(wh.y); lo[3] = hv[3] - bfhi(wh.y);
;                     lo[4] = hv[4] - bflo(wh.z); lo[5] = hv[5] - bfhi(wh.z); lo[6] = hv[6] - bflo(wh.w); lo[7] = hv[7] - bfhi(wh.w);
;                     u32x4 wl; wl.x = pk2(lo[0], lo[1]); wl.y = pk2(lo[2], lo[3]); wl.z = pk2(lo[4], lo[5]); wl.w = pk2(lo[6], lo[7]);
;                     *(u32x4*)(HO + off) = wh; *(u32x4*)(LO + off) = wl;
;                 }
	v_lshlrev_b32_e32 v156, 16, v180
	v_and_b32_e32 v157, 0xffff0000, v180
	v_lshlrev_b32_e32 v158, 16, v184
	v_and_b32_e32 v159, 0xffff0000, v184
	v_pk_add_f32 v[156:157], v[156:157], v[158:159]
	v_pk_add_f32 v[156:157], v[46:47], v[156:157]
	v_cvt_pk_bf16_f32 v180, v156, v157
	v_pk_mul_f32 v[198:199], v[156:157], v[156:157]
	v_lshlrev_b32_e32 v158, 16, v180
	v_and_b32_e32 v159, 0xffff0000, v180
	v_pk_add_f32 v[196:197], v[156:157], v[158:159] neg_lo:[0,1] neg_hi:[0,1]
	v_cvt_pk_bf16_f32 v184, v196, v197
	v_lshlrev_b32_e32 v156, 16, v181
	v_and_b32_e32 v157, 0xffff0000, v181
	v_lshlrev_b32_e32 v158, 16, v185
	v_and_b32_e32 v159, 0xffff0000, v185
	v_pk_add_f32 v[156:157], v[156:157], v[158:159]
	v_pk_add_f32 v[156:157], v[48:49], v[156:157]
	v_cvt_pk_bf16_f32 v181, v156, v157
	v_pk_fma_f32 v[198:199], v[156:157], v[156:157], v[198:199]
	v_lshlrev_b32_e32 v158, 16, v181
	v_and_b32_e32 v159, 0xffff0000, v181
	v_pk_add_f32 v[196:197], v[156:157], v[158:159] neg_lo:[0,1] neg_hi:[0,1]
	v_cvt_pk_bf16_f32 v185, v196, v197
	v_lshlrev_b32_e32 v156, 16, v182
	v_and_b32_e32 v157, 0xffff0000, v182
	v_lshlrev_b32_e32 v158, 16, v186
	v_and_b32_e32 v159, 0xffff0000, v186
	v_pk_add_f32 v[156:157], v[156:157], v[158:159]
	v_pk_add_f32 v[156:157], v[42:43], v[156:157]
	v_cvt_pk_bf16_f32 v182, v156, v157
	v_pk_fma_f32 v[198:199], v[156:157], v[156:157], v[198:199]
	v_lshlrev_b32_e32 v158, 16, v182
	v_and_b32_e32 v159, 0xffff0000, v182
	v_pk_add_f32 v[196:197], v[156:157], v[158:159] neg_lo:[0,1] neg_hi:[0,1]
	v_cvt_pk_bf16_f32 v186, v196, v197
	v_lshlrev_b32_e32 v156, 16, v183
	v_and_b32_e32 v157, 0xffff0000, v183
	v_lshlrev_b32_e32 v158, 16, v187
	v_and_b32_e32 v159, 0xffff0000, v187
	v_pk_add_f32 v[156:157], v[156:157], v[158:159]
	v_pk_add_f32 v[156:157], v[44:45], v[156:157]
	v_cvt_pk_bf16_f32 v183, v156, v157
	v_pk_fma_f32 v[198:199], v[156:157], v[156:157], v[198:199]
	v_lshlrev_b32_e32 v158, 16, v183
	v_and_b32_e32 v159, 0xffff0000, v183
	v_pk_add_f32 v[196:197], v[156:157], v[158:159] neg_lo:[0,1] neg_hi:[0,1]
	v_cvt_pk_bf16_f32 v187, v196, v197
	global_store_dwordx4 v212, v[180:183], s[10:11]
	global_store_dwordx4 v212, v[184:187], s[14:15]
	s_waitcnt vmcnt(18)
	v_lshlrev_b32_e32 v156, 16, v188
	v_and_b32_e32 v157, 0xffff0000, v188
	v_lshlrev_b32_e32 v158, 16, v192
	v_and_b32_e32 v159, 0xffff0000, v192
	v_pk_add_f32 v[156:157], v[156:157], v[158:159]
	v_pk_add_f32 v[156:157], v[38:39], v[156:157]
	v_cvt_pk_bf16_f32 v188, v156, v157
	v_pk_fma_f32 v[198:199], v[156:157], v[156:157], v[198:199]
	v_lshlrev_b32_e32 v158, 16, v188
	v_and_b32_e32 v159, 0xffff0000, v188
	v_pk_add_f32 v[196:197], v[156:157], v[158:159] neg_lo:[0,1] neg_hi:[0,1]
	v_cvt_pk_bf16_f32 v192, v196, v197
	v_lshlrev_b32_e32 v156, 16, v189
	v_and_b32_e32 v157, 0xffff0000, v189
	v_lshlrev_b32_e32 v158, 16, v193
	v_and_b32_e32 v159, 0xffff0000, v193
	v_pk_add_f32 v[156:157], v[156:157], v[158:159]
	v_pk_add_f32 v[156:157], v[40:41], v[156:157]
	v_cvt_pk_bf16_f32 v189, v156, v157
	v_pk_fma_f32 v[198:199], v[156:157], v[156:157], v[198:199]
	v_lshlrev_b32_e32 v158, 16, v189
	v_and_b32_e32 v159, 0xffff0000, v189
	v_pk_add_f32 v[196:197], v[156:157], v[158:159] neg_lo:[0,1] neg_hi:[0,1]
	v_cvt_pk_bf16_f32 v193, v196, v197
	v_lshlrev_b32_e32 v156, 16, v190
	v_and_b32_e32 v157, 0xffff0000, v190
	v_lshlrev_b32_e32 v158, 16, v194
	v_and_b32_e32 v159, 0xffff0000, v194
	v_pk_add_f32 v[156:157], v[156:157], v[158:159]
	v_pk_add_f32 v[156:157], v[34:35], v[156:157]
	v_cvt_pk_bf16_f32 v190, v156, v157
	v_pk_fma_f32 v[198:199], v[156:157], v[156:157], v[198:199]
	v_lshlrev_b32_e32 v158, 16, v190
	v_and_b32_e32 v159, 0xffff0000, v190
	v_pk_add_f32 v[196:197], v[156:157], v[158:159] neg_lo:[0,1] neg_hi:[0,1]
	v_cvt_pk_bf16_f32 v194, v196, v197
	v_lshlrev_b32_e32 v156, 16, v191
	v_and_b32_e32 v157, 0xffff0000, v191
	v_lshlrev_b32_e32 v158, 16, v195
	v_and_b32_e32 v159, 0xffff0000, v195
	v_pk_add_f32 v[156:157], v[156:157], v[158:159]
	v_pk_add_f32 v[156:157], v[36:37], v[156:157]
	v_cvt_pk_bf16_f32 v191, v156, v157
	v_pk_fma_f32 v[198:199], v[156:157], v[156:157], v[198:199]
	v_lshlrev_b32_e32 v158, 16, v191
	v_and_b32_e32 v159, 0xffff0000, v191
	v_pk_add_f32 v[196:197], v[156:157], v[158:159] neg_lo:[0,1] neg_hi:[0,1]
	v_cvt_pk_bf16_f32 v195, v196, v197
	global_store_dwordx4 v212, v[188:191], s[10:11] offset:256
	global_store_dwordx4 v212, v[192:195], s[14:15] offset:256
	v_add_f32_e32 v207, v198, v199
	s_waitcnt vmcnt(14)
	v_lshlrev_b32_e32 v156, 16, v140
	v_and_b32_e32 v157, 0xffff0000, v140
	v_lshlrev_b32_e32 v158, 16, v144
	v_and_b32_e32 v159, 0xffff0000, v144
	v_pk_add_f32 v[156:157], v[156:157], v[158:159]
	v_pk_add_f32 v[156:157], v[30:31], v[156:157]
	v_cvt_pk_bf16_f32 v140, v156, v157
	v_pk_mul_f32 v[198:199], v[156:157], v[156:157]
	v_lshlrev_b32_e32 v158, 16, v140
	v_and_b32_e32 v159, 0xffff0000, v140
	v_pk_add_f32 v[196:197], v[156:157], v[158:159] neg_lo:[0,1] neg_hi:[0,1]
	v_cvt_pk_bf16_f32 v144, v196, v197
	v_lshlrev_b32_e32 v156, 16, v141
	v_and_b32_e32 v157, 0xffff0000, v141
	v_lshlrev_b32_e32 v158, 16, v145
	v_and_b32_e32 v159, 0xffff0000, v145
	v_pk_add_f32 v[156:157], v[156:157], v[158:159]
	v_pk_add_f32 v[156:157], v[32:33], v[156:157]
	v_cvt_pk_bf16_f32 v141, v156, v157
	v_pk_fma_f32 v[198:199], v[156:157], v[156:157], v[198:199]
	v_lshlrev_b32_e32 v158, 16, v141
	v_and_b32_e32 v159, 0xffff0000, v141
	v_pk_add_f32 v[196:197], v[156:157], v[158:159] neg_lo:[0,1] neg_hi:[0,1]
	v_cvt_pk_bf16_f32 v145, v196, v197
	v_lshlrev_b32_e32 v156, 16, v142
	v_and_b32_e32 v157, 0xffff0000, v142
	v_lshlrev_b32_e32 v158, 16, v146
	v_and_b32_e32 v159, 0xffff0000, v146
	v_pk_add_f32 v[156:157], v[156:157], v[158:159]
	v_pk_add_f32 v[156:157], v[26:27], v[156:157]
	v_cvt_pk_bf16_f32 v142, v156, v157
	v_pk_fma_f32 v[198:199], v[156:157], v[156:157], v[198:199]
	v_lshlrev_b32_e32 v158, 16, v142
	v_and_b32_e32 v159, 0xffff0000, v142
	v_pk_add_f32 v[196:197], v[156:157], v[158:159] neg_lo:[0,1] neg_hi:[0,1]
	v_cvt_pk_bf16_f32 v146, v196, v197
	v_lshlrev_b32_e32 v156, 16, v143
	v_and_b32_e32 v157, 0xffff0000, v143
	v_lshlrev_b32_e32 v158, 16, v147
	v_and_b32_e32 v159, 0xffff0000, v147
	v_pk_add_f32 v[156:157], v[156:157], v[158:159]
	v_pk_add_f32 v[156:157], v[28:29], v[156:157]
	v_cvt_pk_bf16_f32 v143, v156, v157
	v_pk_fma_f32 v[198:199], v[156:157], v[156:157], v[198:199]
	v_lshlrev_b32_e32 v158, 16, v143
	v_and_b32_e32 v159, 0xffff0000, v143
	v_pk_add_f32 v[196:197], v[156:157], v[158:159] neg_lo:[0,1] neg_hi:[0,1]
	v_cvt_pk_bf16_f32 v147, v196, v197
	global_store_dwordx4 v210, v[140:143], s[10:11]
	global_store_dwordx4 v210, v[144:147], s[14:15]
	s_waitcnt vmcnt(14)
; __device__ __forceinline__ unsigned pk2(float lo, float hi) { f32x2_t v = {lo, hi}; bf16x2_t b = __builtin_convertvector(v, bf16x2_t); return __builtin_bit_cast(unsigned, b); }
; __device__ __forceinline__ float bflo(unsigned u) { return __uint_as_float(u << 16); }
;     __device__ __forceinline__ void operator()(const f32x4 (&acc)[2][2][4][2], const Unit& u, int wr, int wc, int fr, int fq) const {
;     ...
;                 for (int bj = 0; bj < 2; ++bj) {
;                     const size_t off = (size_t)row * DM + col0 + bj * HALF;
;                     const u32x4 hh = *(const u32x4*)(HI + off), ll = *(const u32x4*)(LO + off);
;                     float hv[8] = {bflo(hh.x) + bflo(ll.x), bfhi(hh.x) + bfhi(ll.x), bflo(hh.y) + bflo(ll.y), bfhi(hh.y) + bfhi(ll.y),
;                                    bflo(hh.z) + bflo(ll.z), bfhi(hh.z) + bfhi(ll.z), bflo(hh.w) + bflo(ll.w), bfhi(hh.w) + bfhi(ll.w)};
;                     float av[8] = {acc[ai][bj][m][0][0], acc[ai][bj][m][0][1], acc[ai][bj][m][0][2], acc[ai][bj][m][0][3], acc[ai][bj][m][1][0], acc[ai][bj][m][1][1], acc[ai][bj][m][1][2], acc[ai][bj][m][1][3]};
;                     if (GATED) { const u32x4 pp = *(const u32x4*)(PP + off);
;                         const float pv[8] = {bflo(pp.x), bfhi(pp.x), bflo(pp.y), bfhi(pp.y), bflo(pp.z), bfhi(pp.z), bflo(pp.w), bfhi(pp.w)};
; #pragma unroll
;                         for (int e = 0; e < 8; ++e) av[e] = fast_sigmoid(av[e] * rs) * pv[e]; }
;                     else {
; #pragma unroll
;                         for (int e = 0; e < 8; ++e) av[e] *= alpha; }
;                     float lo[8];
; #pragma unroll
;                     for (int e = 0; e < 8; ++e) { hv[e] += av[e]; sq += hv[e] * hv[e]; }
;                     u32x4 wh; wh.x = pk2(hv[0], hv[1]); wh.y = pk2(hv[2], hv[3]); wh.z = pk2(hv[4], hv[5]); wh.w = pk2(hv[6], hv[7]);
;                     lo[0] = hv[0] - bflo(wh.x); lo[1] = hv[1] - bfhi(wh.x); lo[2] = hv[2] - bflo(wh.y); lo[3] = hv[3] - bfhi(wh.y);
;                     lo[4] = hv[4] - bflo(wh.z); lo[5] = hv[5] - bfhi(wh.z); lo[6] = hv[6] - bflo(wh.w); lo[7] = hv[7] - bfhi(wh.w);
;                     u32x4 wl; wl.x = pk2(lo[0], lo[1]); wl.y = pk2(lo[2], lo[3]); wl.z = pk2(lo[4], lo[5]); wl.w = pk2(lo[6], lo[7]);
;                     *(u32x4*)(HO + off) = wh; *(u32x4*)(LO + off) = wl;
;                 }
	v_lshlrev_b32_e32 v156, 16, v148
	v_and_b32_e32 v157, 0xffff0000, v148
	v_lshlrev_b32_e32 v158, 16, v152
	v_and_b32_e32 v159, 0xffff0000, v152
	v_pk_add_f32 v[156:157], v[156:157], v[158:159]
	v_pk_add_f32 v[156:157], v[22:23], v[156:157]
	v_cvt_pk_bf16_f32 v148, v156, v157
	v_pk_fma_f32 v[198:199], v[156:157], v[156:157], v[198:199]
	v_lshlrev_b32_e32 v158, 16, v148
	v_and_b32_e32 v159, 0xffff0000, v148
	v_pk_add_f32 v[196:197], v[156:157], v[158:159] neg_lo:[0,1] neg_hi:[0,1]
	v_cvt_pk_bf16_f32 v152, v196, v197
	v_lshlrev_b32_e32 v156, 16, v149
	v_and_b32_e32 v157, 0xffff0000, v149
	v_lshlrev_b32_e32 v158, 16, v153
	v_and_b32_e32 v159, 0xffff0000, v153
	v_pk_add_f32 v[156:157], v[156:157], v[158:159]
	v_pk_add_f32 v[156:157], v[24:25], v[156:157]
	v_cvt_pk_bf16_f32 v149, v156, v157
	v_pk_fma_f32 v[198:199], v[156:157], v[156:157], v[198:199]
	v_lshlrev_b32_e32 v158, 16, v149
	v_and_b32_e32 v159, 0xffff0000, v149
	v_pk_add_f32 v[196:197], v[156:157], v[158:159] neg_lo:[0,1] neg_hi:[0,1]
	v_cvt_pk_bf16_f32 v153, v196, v197
	v_lshlrev_b32_e32 v156, 16, v150
	v_and_b32_e32 v157, 0xffff0000, v150
	v_lshlrev_b32_e32 v158, 16, v154
	v_and_b32_e32 v159, 0xffff0000, v154
	v_pk_add_f32 v[156:157], v[156:157], v[158:159]
	v_pk_add_f32 v[156:157], v[18:19], v[156:157]
	v_cvt_pk_bf16_f32 v150, v156, v157
	v_pk_fma_f32 v[198:199], v[156:157], v[156:157], v[198:199]
	v_lshlrev_b32_e32 v158, 16, v150
	v_and_b32_e32 v159, 0xffff0000, v150
	v_pk_add_f32 v[196:197], v[156:157], v[158:159] neg_lo:[0,1] neg_hi:[0,1]
	v_cvt_pk_bf16_f32 v154, v196, v197
	v_lshlrev_b32_e32 v156, 16, v151
	v_and_b32_e32 v157, 0xffff0000, v151
	v_lshlrev_b32_e32 v158, 16, v155
	v_and_b32_e32 v159, 0xffff0000, v155
	v_pk_add_f32 v[156:157], v[156:157], v[158:159]
	v_pk_add_f32 v[156:157], v[20:21], v[156:157]
	v_cvt_pk_bf16_f32 v151, v156, v157
	v_pk_fma_f32 v[198:199], v[156:157], v[156:157], v[198:199]
	v_lshlrev_b32_e32 v158, 16, v151
	v_and_b32_e32 v159, 0xffff0000, v151
	v_pk_add_f32 v[196:197], v[156:157], v[158:159] neg_lo:[0,1] neg_hi:[0,1]
	v_cvt_pk_bf16_f32 v155, v196, v197
	global_store_dwordx4 v210, v[148:151], s[10:11] offset:256
	global_store_dwordx4 v210, v[152:155], s[14:15] offset:256
	v_add_f32_e32 v208, v198, v199
	s_waitcnt vmcnt(10)
	v_lshlrev_b32_e32 v156, 16, v164
	v_and_b32_e32 v157, 0xffff0000, v164
	v_lshlrev_b32_e32 v158, 16, v168
	v_and_b32_e32 v159, 0xffff0000, v168
	v_pk_add_f32 v[156:157], v[156:157], v[158:159]
	v_pk_add_f32 v[156:157], v[14:15], v[156:157]
	v_cvt_pk_bf16_f32 v164, v156, v157
	v_pk_mul_f32 v[198:199], v[156:157], v[156:157]
	v_lshlrev_b32_e32 v158, 16, v164
	v_and_b32_e32 v159, 0xffff0000, v164
	v_pk_add_f32 v[196:197], v[156:157], v[158:159] neg_lo:[0,1] neg_hi:[0,1]
	v_cvt_pk_bf16_f32 v168, v196, v197
	v_lshlrev_b32_e32 v156, 16, v165
	v_and_b32_e32 v157, 0xffff0000, v165
	v_lshlrev_b32_e32 v158, 16, v169
	v_and_b32_e32 v159, 0xffff0000, v169
	v_pk_add_f32 v[156:157], v[156:157], v[158:159]
	v_pk_add_f32 v[156:157], v[16:17], v[156:157]
	v_cvt_pk_bf16_f32 v165, v156, v157
	v_pk_fma_f32 v[198:199], v[156:157], v[156:157], v[198:199]
	v_lshlrev_b32_e32 v158, 16, v165
	v_and_b32_e32 v159, 0xffff0000, v165
	v_pk_add_f32 v[196:197], v[156:157], v[158:159] neg_lo:[0,1] neg_hi:[0,1]
	v_cvt_pk_bf16_f32 v169, v196, v197
	v_lshlrev_b32_e32 v156, 16, v166
	v_and_b32_e32 v157, 0xffff0000, v166
	v_lshlrev_b32_e32 v158, 16, v170
	v_and_b32_e32 v159, 0xffff0000, v170
	v_pk_add_f32 v[156:157], v[156:157], v[158:159]
	v_pk_add_f32 v[156:157], v[10:11], v[156:157]
	v_cvt_pk_bf16_f32 v166, v156, v157
	v_pk_fma_f32 v[198:199], v[156:157], v[156:157], v[198:199]
	v_lshlrev_b32_e32 v158, 16, v166
	v_and_b32_e32 v159, 0xffff0000, v166
	v_pk_add_f32 v[196:197], v[156:157], v[158:159] neg_lo:[0,1] neg_hi:[0,1]
	v_cvt_pk_bf16_f32 v170, v196, v197
	v_lshlrev_b32_e32 v156, 16, v167
	v_and_b32_e32 v157, 0xffff0000, v167
	v_lshlrev_b32_e32 v158, 16, v171
	v_and_b32_e32 v159, 0xffff0000, v171
	v_pk_add_f32 v[156:157], v[156:157], v[158:159]
	v_pk_add_f32 v[156:157], v[12:13], v[156:157]
	v_cvt_pk_bf16_f32 v167, v156, v157
	v_pk_fma_f32 v[198:199], v[156:157], v[156:157], v[198:199]
	v_lshlrev_b32_e32 v158, 16, v167
	v_and_b32_e32 v159, 0xffff0000, v167
	v_pk_add_f32 v[196:197], v[156:157], v[158:159] neg_lo:[0,1] neg_hi:[0,1]
	v_cvt_pk_bf16_f32 v171, v196, v197
	global_store_dwordx4 v211, v[164:167], s[10:11]
	global_store_dwordx4 v211, v[168:171], s[14:15]
	s_waitcnt vmcnt(10)
; __device__ __forceinline__ float bflo(unsigned u) { return __uint_as_float(u << 16); }
;     __device__ __forceinline__ void operator()(const f32x4 (&acc)[2][2][4][2], const Unit& u, int wr, int wc, int fr, int fq) const {
;     ...
;                 for (int bj = 0; bj < 2; ++bj) {
;                     const size_t off = (size_t)row * DM + col0 + bj * HALF;
;                     const u32x4 hh = *(const u32x4*)(HI + off), ll = *(const u32x4*)(LO + off);
;                     float hv[8] = {bflo(hh.x) + bflo(ll.x), bfhi(hh.x) + bfhi(ll.x), bflo(hh.y) + bflo(ll.y), bfhi(hh.y) + bfhi(ll.y),
;                                    bflo(hh.z) + bflo(ll.z), bfhi(hh.z) + bfhi(ll.z), bflo(hh.w) + bflo(ll.w), bfhi(hh.w) + bfhi(ll.w)};
;                     float av[8] = {acc[ai][bj][m][0][0], acc[ai][bj][m][0][1], acc[ai][bj][m][0][2], acc[ai][bj][m][0][3], acc[ai][bj][m][1][0], acc[ai][bj][m][1][1], acc[ai][bj][m][1][2], acc[ai][bj][m][1][3]};
;                     if (GATED) { const u32x4 pp = *(const u32x4*)(PP + off);
;                         const float pv[8] = {bflo(pp.x), bfhi(pp.x), bflo(pp.y), bfhi(pp.y), bflo(pp.z), bfhi(pp.z), bflo(pp.w), bfhi(pp.w)};
; #pragma unroll
;                         for (int e = 0; e < 8; ++e) av[e] = fast_sigmoid(av[e] * rs) * pv[e]; }
;                     else {
; #pragma unroll
;                         for (int e = 0; e < 8; ++e) av[e] *= alpha; }
;                     float lo[8];
; #pragma unroll
;                     for (int e = 0; e < 8; ++e) { hv[e] += av[e]; sq += hv[e] * hv[e]; }
;                     u32x4 wh; wh.x = pk2(hv[0], hv[1]); wh.y = pk2(hv[2], hv[3]); wh.z = pk2(hv[4], hv[5]); wh.w = pk2(hv[6], hv[7]);
;                     lo[0] = hv[0] - bflo(wh.x); lo[1] = hv[1] - bfhi(wh.x); lo[2] = hv[2] - bflo(wh.y); lo[3] = hv[3] - bfhi(wh.y);
;                     lo[4] = hv[4] - bflo(wh.z); lo[5] = hv[5] - bfhi(wh.z); lo[6] = hv[6] - bflo(wh.w); lo[7] = hv[7] - bfhi(wh.w);
;                     u32x4 wl; wl.x = pk2(lo[0], lo[1]); wl.y = pk2(lo[2], lo[3]); wl.z = pk2(lo[4], lo[5]); wl.w = pk2(lo[6], lo[7]);
;                     *(u32x4*)(HO + off) = wh; *(u32x4*)(LO + off) = wl;
;                 }
;                 sq += __shfl_xor(sq, 16); sq += __shfl_xor(sq, 32);
;                 if (fq == 0) ssq_out[(size_t)row * 16 + 4 * u.pn + wc] = sq;
	v_lshlrev_b32_e32 v156, 16, v172
	v_and_b32_e32 v157, 0xffff0000, v172
	v_lshlrev_b32_e32 v158, 16, v176
	v_and_b32_e32 v159, 0xffff0000, v176
	v_pk_add_f32 v[156:157], v[156:157], v[158:159]
	v_pk_add_f32 v[156:157], v[6:7], v[156:157]
	v_cvt_pk_bf16_f32 v172, v156, v157
	v_pk_fma_f32 v[198:199], v[156:157], v[156:157], v[198:199]
	v_lshlrev_b32_e32 v158, 16, v172
	v_and_b32_e32 v159, 0xffff0000, v172
	v_pk_add_f32 v[196:197], v[156:157], v[158:159] neg_lo:[0,1] neg_hi:[0,1]
	v_cvt_pk_bf16_f32 v176, v196, v197
	v_lshlrev_b32_e32 v156, 16, v173
	v_and_b32_e32 v157, 0xffff0000, v173
	v_lshlrev_b32_e32 v158, 16, v177
	v_and_b32_e32 v159, 0xffff0000, v177
	v_pk_add_f32 v[156:157], v[156:157], v[158:159]
	v_pk_add_f32 v[156:157], v[8:9], v[156:157]
	v_cvt_pk_bf16_f32 v173, v156, v157
	v_pk_fma_f32 v[198:199], v[156:157], v[156:157], v[198:199]
	v_lshlrev_b32_e32 v158, 16, v173
	v_and_b32_e32 v159, 0xffff0000, v173
	v_pk_add_f32 v[196:197], v[156:157], v[158:159] neg_lo:[0,1] neg_hi:[0,1]
	v_cvt_pk_bf16_f32 v177, v196, v197
	v_lshlrev_b32_e32 v156, 16, v174
	v_and_b32_e32 v157, 0xffff0000, v174
	v_lshlrev_b32_e32 v158, 16, v178
	v_and_b32_e32 v159, 0xffff0000, v178
	v_pk_add_f32 v[156:157], v[156:157], v[158:159]
	v_pk_add_f32 v[156:157], v[2:3], v[156:157]
	v_cvt_pk_bf16_f32 v174, v156, v157
	v_pk_fma_f32 v[198:199], v[156:157], v[156:157], v[198:199]
	v_lshlrev_b32_e32 v158, 16, v174
	v_and_b32_e32 v159, 0xffff0000, v174
	v_pk_add_f32 v[196:197], v[156:157], v[158:159] neg_lo:[0,1] neg_hi:[0,1]
	v_cvt_pk_bf16_f32 v178, v196, v197
	v_lshlrev_b32_e32 v156, 16, v175
	v_and_b32_e32 v157, 0xffff0000, v175
	v_lshlrev_b32_e32 v158, 16, v179
	v_and_b32_e32 v159, 0xffff0000, v179
	v_pk_add_f32 v[156:157], v[156:157], v[158:159]
	v_pk_add_f32 v[156:157], v[4:5], v[156:157]
	v_cvt_pk_bf16_f32 v175, v156, v157
	v_pk_fma_f32 v[198:199], v[156:157], v[156:157], v[198:199]
	v_lshlrev_b32_e32 v158, 16, v175
	v_and_b32_e32 v159, 0xffff0000, v175
	v_pk_add_f32 v[196:197], v[156:157], v[158:159] neg_lo:[0,1] neg_hi:[0,1]
	v_cvt_pk_bf16_f32 v179, v196, v197
	global_store_dwordx4 v211, v[172:175], s[10:11] offset:256
	global_store_dwordx4 v211, v[176:179], s[14:15] offset:256
	v_add_f32_e32 v209, v198, v199
	v_mov_b32_e32 v140, v200
	s_nop 1
	v_permlane16_swap_b32_e32 v200, v140
	v_mov_b32_e32 v141, v201
	s_nop 1
	v_permlane16_swap_b32_e32 v201, v141
	v_mov_b32_e32 v142, v202
	s_nop 1
	v_permlane16_swap_b32_e32 v202, v142
	v_mov_b32_e32 v143, v203
	s_nop 1
	v_permlane16_swap_b32_e32 v203, v143
	v_mov_b32_e32 v144, v206
	s_nop 1
	v_permlane16_swap_b32_e32 v206, v144
	v_mov_b32_e32 v145, v207
	s_nop 1
	v_permlane16_swap_b32_e32 v207, v145
	v_mov_b32_e32 v146, v208
	s_nop 1
	v_permlane16_swap_b32_e32 v208, v146
	v_mov_b32_e32 v147, v209
	s_nop 1
	v_permlane16_swap_b32_e32 v209, v147
	s_waitcnt lgkmcnt(0)
	v_add_f32_e32 v200, v200, v140
	v_add_f32_e32 v201, v201, v141
	v_add_f32_e32 v202, v202, v142
	v_add_f32_e32 v203, v203, v143
	v_add_f32_e32 v206, v206, v144
	v_add_f32_e32 v207, v207, v145
	v_add_f32_e32 v208, v208, v146
	v_add_f32_e32 v209, v209, v147
	v_mov_b32_e32 v140, v200
	s_nop 1
	v_permlane32_swap_b32_e32 v200, v140
	v_mov_b32_e32 v141, v201
	s_nop 1
	v_permlane32_swap_b32_e32 v201, v141
	v_mov_b32_e32 v142, v202
	s_nop 1
	v_permlane32_swap_b32_e32 v202, v142
	v_mov_b32_e32 v143, v203
	s_nop 1
	v_permlane32_swap_b32_e32 v203, v143
	v_mov_b32_e32 v144, v206
	s_nop 1
	v_permlane32_swap_b32_e32 v206, v144
	v_mov_b32_e32 v145, v207
	s_nop 1
	v_permlane32_swap_b32_e32 v207, v145
	v_mov_b32_e32 v146, v208
	s_nop 1
	v_permlane32_swap_b32_e32 v208, v146
	v_mov_b32_e32 v147, v209
	s_nop 1
	v_permlane32_swap_b32_e32 v209, v147
	s_waitcnt lgkmcnt(0)
	v_add_f32_e32 v200, v200, v140
	v_add_f32_e32 v201, v201, v141
	v_add_f32_e32 v202, v202, v142
	v_add_f32_e32 v203, v203, v143
	v_add_f32_e32 v206, v206, v144
	v_add_f32_e32 v207, v207, v145
	v_add_f32_e32 v208, v208, v146
	v_add_f32_e32 v209, v209, v147
	s_and_saveexec_b64 s[26:27], s[44:45]
	s_cbranch_execz .Lepir_wout_skip
	global_store_dword v216, v200, s[16:17]
	global_store_dword v216, v201, s[16:17] offset:1024
	global_store_dword v216, v202, s[16:17] offset:2048
	global_store_dword v216, v203, s[16:17] offset:3072
	global_store_dword v217, v206, s[16:17]
	global_store_dword v217, v207, s[16:17] offset:1024
	global_store_dword v217, v208, s[16:17] offset:2048
	global_store_dword v217, v209, s[16:17] offset:3072

; __device__ __forceinline__ float bflo(unsigned u) { return __uint_as_float(u << 16); }
;     __device__ __forceinline__ void operator()(const f32x4 (&acc)[2][2][4][2], const Unit& u, int wr, int wc, int fr, int fq) const {
;         const int row0 = u.pm * BM + wr * 64 + fr, col0 = u.pn * BM + wc * 32 + 8 * fq;
; #pragma unroll
;         for (int ai = 0; ai < 2; ++ai)
; #pragma unroll
;             for (int m = 0; m < 4; ++m) {
;                 const int row = row0 + ai * HALF + m * 16;
;                 float rs = 0.f; if (GATED) rs = rsqrtf(row_ssq(ssq_in, 16, 4, row, fq) * (1.f / 1024.f) + EPS);
;                 float sq = 0.f;
; #pragma unroll
;                 for (int bj = 0; bj < 2; ++bj) {
;                     const size_t off = (size_t)row * DM + col0 + bj * HALF;
;                     const u32x4 hh = *(const u32x4*)(HI + off), ll = *(const u32x4*)(LO + off);
;                     float hv[8] = {bflo(hh.x) + bflo(ll.x), bfhi(hh.x) + bfhi(ll.x), bflo(hh.y) + bflo(ll.y), bfhi(hh.y) + bfhi(ll.y),
;                                    bflo(hh.z) + bflo(ll.z), bfhi(hh.z) + bfhi(ll.z), bflo(hh.w) + bflo(ll.w), bfhi(hh.w) + bfhi(ll.w)};
;                     float av[8] = {acc[ai][bj][m][0][0], acc[ai][bj][m][0][1], acc[ai][bj][m][0][2], acc[ai][bj][m][0][3], acc[ai][bj][m][1][0], acc[ai][bj][m][1][1], acc[ai][bj][m][1][2], acc[ai][bj][m][1][3]};
;                     if (GATED) { const u32x4 pp = *(const u32x4*)(PP + off);
;                         const float pv[8] = {bflo(pp.x), bfhi(pp.x), bflo(pp.y), bfhi(pp.y), bflo(pp.z), bfhi(pp.z), bflo(pp.w), bfhi(pp.w)};
; #pragma unroll
;                         for (int e = 0; e < 8; ++e) av[e] = fast_sigmoid(av[e] * rs) * pv[e]; }
;                     else {
; #pragma unroll
;                         for (int e = 0; e < 8; ++e) av[e] *= alpha; }
;                     float lo[8];
; #pragma unroll
;                     for (int e = 0; e < 8; ++e) { hv[e] += av[e]; sq += hv[e] * hv[e]; }
;                     u32x4 wh; wh.x = pk2(hv[0], hv[1]); wh.y = pk2(hv[2], hv[3]); wh.z = pk2(hv[4], hv[5]); wh.w = pk2(hv[6], hv[7]);
;                     lo[0] = hv[0] - bflo(wh.x); lo[1] = hv[1] - bfhi(wh.x); lo[2] = hv[2] - bflo(wh.y); lo[3] = hv[3] - bfhi(wh.y);
;                     lo[4] = hv[4] - bflo(wh.z); lo[5] = hv[5] - bfhi(wh.z); lo[6] = hv[6] - bflo(wh.w); lo[7] = hv[7] - bfhi(wh.w);
.LBB0_1250:
	v_and_b32_e32 v158, 64, v241
	v_xor_b32_e32 v214, 16, v241
	v_add_u32_e32 v158, 64, v158
	v_cmp_lt_i32_e32 vcc, v214, v158
	v_lshl_add_u32 v156, s31, 8, v160
	v_lshl_or_b32 v157, s4, 8, v162
	v_cndmask_b32_e32 v214, v241, v214, vcc
	v_lshlrev_b32_e32 v214, 2, v214
	v_xor_b32_e32 v215, 32, v241
	v_cmp_lt_i32_e32 vcc, v215, v158
	v_readlane_b32 s10, v253, 35
	v_readlane_b32 s11, v253, 36
	v_readlane_b32 s6, v250, 49
	v_readlane_b32 s7, v250, 50
	s_nop 1
	v_cndmask_b32_e32 v215, v241, v215, vcc
	v_lshlrev_b32_e32 v215, 2, v215
	v_lshl_add_u32 v213, v156, 10, v157
	v_lshlrev_b32_e32 v213, 1, v213
	s_lshl_b32 s40, s4, 4
	s_lshl_b32 s50, s25, 2
	s_add_i32 s40, s40, s50
	v_lshlrev_b32_e32 v216, 6, v156
	v_add_u32_e32 v216, s40, v216
	v_add_u32_e32 v217, 0x2000, v216
	s_nop 1
	v_add_u32_e32 v211, 0x8000, v213
	global_load_dwordx4 v[164:167], v211, s[10:11]
	global_load_dwordx4 v[168:171], v211, s[6:7]
	global_load_dwordx4 v[172:175], v211, s[10:11] offset:256
	global_load_dwordx4 v[176:179], v211, s[6:7] offset:256
	v_add_u32_e32 v212, 0x10000, v213
	global_load_dwordx4 v[180:183], v212, s[10:11]
	global_load_dwordx4 v[184:187], v212, s[6:7]
	global_load_dwordx4 v[188:191], v212, s[10:11] offset:256
	global_load_dwordx4 v[192:195], v212, s[6:7] offset:256
	v_add_u32_e32 v210, 0x18000, v213
	global_load_dwordx4 v[140:143], v210, s[10:11]
	global_load_dwordx4 v[144:147], v210, s[6:7]
	global_load_dwordx4 v[148:151], v210, s[10:11] offset:256
	global_load_dwordx4 v[152:155], v210, s[6:7] offset:256
	s_waitcnt vmcnt(12)
	v_lshlrev_b32_e32 v156, 16, v226
	v_and_b32_e32 v157, 0xffff0000, v226
	v_lshlrev_b32_e32 v158, 16, v230
	v_and_b32_e32 v159, 0xffff0000, v230
	v_pk_add_f32 v[156:157], v[156:157], v[158:159]
	v_pk_fma_f32 v[156:157], v[126:127], 0.5, v[156:157] op_sel_hi:[1,0,1]
	v_cvt_pk_bf16_f32 v226, v156, v157
	v_pk_mul_f32 v[198:199], v[156:157], v[156:157]
	v_lshlrev_b32_e32 v158, 16, v226
	v_and_b32_e32 v159, 0xffff0000, v226
	v_pk_add_f32 v[196:197], v[156:157], v[158:159] neg_lo:[0,1] neg_hi:[0,1]
	v_cvt_pk_bf16_f32 v230, v196, v197
	v_lshlrev_b32_e32 v156, 16, v227
	v_and_b32_e32 v157, 0xffff0000, v227
	v_lshlrev_b32_e32 v158, 16, v231
	v_and_b32_e32 v159, 0xffff0000, v231
	v_pk_add_f32 v[156:157], v[156:157], v[158:159]
	v_pk_fma_f32 v[156:157], v[128:129], 0.5, v[156:157] op_sel_hi:[1,0,1]
	v_cvt_pk_bf16_f32 v227, v156, v157
	v_pk_fma_f32 v[198:199], v[156:157], v[156:157], v[198:199]
	v_lshlrev_b32_e32 v158, 16, v227
	v_and_b32_e32 v159, 0xffff0000, v227
	v_pk_add_f32 v[196:197], v[156:157], v[158:159] neg_lo:[0,1] neg_hi:[0,1]
	v_cvt_pk_bf16_f32 v231, v196, v197
	v_lshlrev_b32_e32 v156, 16, v228
	v_and_b32_e32 v157, 0xffff0000, v228
	v_lshlrev_b32_e32 v158, 16, v232
	v_and_b32_e32 v159, 0xffff0000, v232
	v_pk_add_f32 v[156:157], v[156:157], v[158:159]
	v_pk_fma_f32 v[156:157], v[122:123], 0.5, v[156:157] op_sel_hi:[1,0,1]
	v_cvt_pk_bf16_f32 v228, v156, v157
	v_pk_fma_f32 v[198:199], v[156:157], v[156:157], v[198:199]
	v_lshlrev_b32_e32 v158, 16, v228
	v_and_b32_e32 v159, 0xffff0000, v228
	v_pk_add_f32 v[196:197], v[156:157], v[158:159] neg_lo:[0,1] neg_hi:[0,1]
	v_cvt_pk_bf16_f32 v232, v196, v197
	v_lshlrev_b32_e32 v156, 16, v229
	v_and_b32_e32 v157, 0xffff0000, v229
	v_lshlrev_b32_e32 v158, 16, v233
	v_and_b32_e32 v159, 0xffff0000, v233
	v_pk_add_f32 v[156:157], v[156:157], v[158:159]
	v_pk_fma_f32 v[156:157], v[124:125], 0.5, v[156:157] op_sel_hi:[1,0,1]
	v_cvt_pk_bf16_f32 v229, v156, v157
	v_pk_fma_f32 v[198:199], v[156:157], v[156:157], v[198:199]
	v_lshlrev_b32_e32 v158, 16, v229
	v_and_b32_e32 v159, 0xffff0000, v229
	v_pk_add_f32 v[196:197], v[156:157], v[158:159] neg_lo:[0,1] neg_hi:[0,1]
	v_cvt_pk_bf16_f32 v233, v196, v197
	global_store_dwordx4 v213, v[226:229], s[10:11]
	global_store_dwordx4 v213, v[230:233], s[6:7]
	v_lshlrev_b32_e32 v156, 16, v234
	v_and_b32_e32 v157, 0xffff0000, v234
	v_lshlrev_b32_e32 v158, 16, v242
	v_and_b32_e32 v159, 0xffff0000, v242
	v_pk_add_f32 v[156:157], v[156:157], v[158:159]
	v_pk_fma_f32 v[156:157], v[118:119], 0.5, v[156:157] op_sel_hi:[1,0,1]
	v_cvt_pk_bf16_f32 v234, v156, v157
	v_pk_fma_f32 v[198:199], v[156:157], v[156:157], v[198:199]
	v_lshlrev_b32_e32 v158, 16, v234
	v_and_b32_e32 v159, 0xffff0000, v234
	v_pk_add_f32 v[196:197], v[156:157], v[158:159] neg_lo:[0,1] neg_hi:[0,1]
	v_cvt_pk_bf16_f32 v242, v196, v197
	v_lshlrev_b32_e32 v156, 16, v235
	v_and_b32_e32 v157, 0xffff0000, v235
	v_lshlrev_b32_e32 v158, 16, v243
	v_and_b32_e32 v159, 0xffff0000, v243
	v_pk_add_f32 v[156:157], v[156:157], v[158:159]
	v_pk_fma_f32 v[156:157], v[120:121], 0.5, v[156:157] op_sel_hi:[1,0,1]
	v_cvt_pk_bf16_f32 v235, v156, v157
	v_pk_fma_f32 v[198:199], v[156:157], v[156:157], v[198:199]
	v_lshlrev_b32_e32 v158, 16, v235
	v_and_b32_e32 v159, 0xffff0000, v235
	v_pk_add_f32 v[196:197], v[156:157], v[158:159] neg_lo:[0,1] neg_hi:[0,1]
	v_cvt_pk_bf16_f32 v243, v196, v197
	v_lshlrev_b32_e32 v156, 16, v236
	v_and_b32_e32 v157, 0xffff0000, v236
	v_lshlrev_b32_e32 v158, 16, v244
	v_and_b32_e32 v159, 0xffff0000, v244
	v_pk_add_f32 v[156:157], v[156:157], v[158:159]
	v_pk_fma_f32 v[156:157], v[114:115], 0.5, v[156:157] op_sel_hi:[1,0,1]
	v_cvt_pk_bf16_f32 v236, v156, v157
	v_pk_fma_f32 v[198:199], v[156:157], v[156:157], v[198:199]
	v_lshlrev_b32_e32 v158, 16, v236
	v_and_b32_e32 v159, 0xffff0000, v236
	v_pk_add_f32 v[196:197], v[156:157], v[158:159] neg_lo:[0,1] neg_hi:[0,1]
	v_cvt_pk_bf16_f32 v244, v196, v197
	v_lshlrev_b32_e32 v156, 16, v237
	v_and_b32_e32 v157, 0xffff0000, v237
	v_lshlrev_b32_e32 v158, 16, v245
	v_and_b32_e32 v159, 0xffff0000, v245
	v_pk_add_f32 v[156:157], v[156:157], v[158:159]
	v_pk_fma_f32 v[156:157], v[116:117], 0.5, v[156:157] op_sel_hi:[1,0,1]
	v_cvt_pk_bf16_f32 v237, v156, v157
	v_pk_fma_f32 v[198:199], v[156:157], v[156:157], v[198:199]
	v_lshlrev_b32_e32 v158, 16, v237
	v_and_b32_e32 v159, 0xffff0000, v237
	v_pk_add_f32 v[196:197], v[156:157], v[158:159] neg_lo:[0,1] neg_hi:[0,1]
	v_cvt_pk_bf16_f32 v245, v196, v197
	global_store_dwordx4 v213, v[234:237], s[10:11] offset:256
	global_store_dwordx4 v213, v[242:245], s[6:7] offset:256
	v_add_f32_e32 v200, v198, v199
	s_waitcnt vmcnt(14)
; __device__ __forceinline__ unsigned pk2(float lo, float hi) { f32x2_t v = {lo, hi}; bf16x2_t b = __builtin_convertvector(v, bf16x2_t); return __builtin_bit_cast(unsigned, b); }
; __device__ __forceinline__ float bflo(unsigned u) { return __uint_as_float(u << 16); }
;     __device__ __forceinline__ void operator()(const f32x4 (&acc)[2][2][4][2], const Unit& u, int wr, int wc, int fr, int fq) const {
;     ...
;                 for (int bj = 0; bj < 2; ++bj) {
;                     const size_t off = (size_t)row * DM + col0 + bj * HALF;
;                     const u32x4 hh = *(const u32x4*)(HI + off), ll = *(const u32x4*)(LO + off);
;                     float hv[8] = {bflo(hh.x) + bflo(ll.x), bfhi(hh.x) + bfhi(ll.x), bflo(hh.y) + bflo(ll.y), bfhi(hh.y) + bfhi(ll.y),
;                                    bflo(hh.z) + bflo(ll.z), bfhi(hh.z) + bfhi(ll.z), bflo(hh.w) + bflo(ll.w), bfhi(hh.w) + bfhi(ll.w)};
;                     float av[8] = {acc[ai][bj][m][0][0], acc[ai][bj][m][0][1], acc[ai][bj][m][0][2], acc[ai][bj][m][0][3], acc[ai][bj][m][1][0], acc[ai][bj][m][1][1], acc[ai][bj][m][1][2], acc[ai][bj][m][1][3]};
;                     if (GATED) { const u32x4 pp = *(const u32x4*)(PP + off);
;                         const float pv[8] = {bflo(pp.x), bfhi(pp.x), bflo(pp.y), bfhi(pp.y), bflo(pp.z), bfhi(pp.z), bflo(pp.w), bfhi(pp.w)};
; #pragma unroll
;                         for (int e = 0; e < 8; ++e) av[e] = fast_sigmoid(av[e] * rs) * pv[e]; }
;                     else {
; #pragma unroll
;                         for (int e = 0; e < 8; ++e) av[e] *= alpha; }
;                     float lo[8];
; #pragma unroll
;                     for (int e = 0; e < 8; ++e) { hv[e] += av[e]; sq += hv[e] * hv[e]; }
;                     u32x4 wh; wh.x = pk2(hv[0], hv[1]); wh.y = pk2(hv[2], hv[3]); wh.z = pk2(hv[4], hv[5]); wh.w = pk2(hv[6], hv[7]);
;                     lo[0] = hv[0] - bflo(wh.x); lo[1] = hv[1] - bfhi(wh.x); lo[2] = hv[2] - bflo(wh.y); lo[3] = hv[3] - bfhi(wh.y);
;                     lo[4] = hv[4] - bflo(wh.z); lo[5] = hv[5] - bfhi(wh.z); lo[6] = hv[6] - bflo(wh.w); lo[7] = hv[7] - bfhi(wh.w);
;                     u32x4 wl; wl.x = pk2(lo[0], lo[1]); wl.y = pk2(lo[2], lo[3]); wl.z = pk2(lo[4], lo[5]); wl.w = pk2(lo[6], lo[7]);
;                     *(u32x4*)(HO + off) = wh; *(u32x4*)(LO + off) = wl;
;                 }
	v_lshlrev_b32_e32 v156, 16, v164
	v_and_b32_e32 v157, 0xffff0000, v164
	v_lshlrev_b32_e32 v158, 16, v168
	v_and_b32_e32 v159, 0xffff0000, v168
	v_pk_add_f32 v[156:157], v[156:157], v[158:159]
	v_pk_fma_f32 v[156:157], v[110:111], 0.5, v[156:157] op_sel_hi:[1,0,1]
	v_cvt_pk_bf16_f32 v164, v156, v157
	v_pk_mul_f32 v[198:199], v[156:157], v[156:157]
	v_lshlrev_b32_e32 v158, 16, v164
	v_and_b32_e32 v159, 0xffff0000, v164
	v_pk_add_f32 v[196:197], v[156:157], v[158:159] neg_lo:[0,1] neg_hi:[0,1]
	v_cvt_pk_bf16_f32 v168, v196, v197
	v_lshlrev_b32_e32 v156, 16, v165
	v_and_b32_e32 v157, 0xffff0000, v165
	v_lshlrev_b32_e32 v158, 16, v169
	v_and_b32_e32 v159, 0xffff0000, v169
	v_pk_add_f32 v[156:157], v[156:157], v[158:159]
	v_pk_fma_f32 v[156:157], v[112:113], 0.5, v[156:157] op_sel_hi:[1,0,1]
	v_cvt_pk_bf16_f32 v165, v156, v157
	v_pk_fma_f32 v[198:199], v[156:157], v[156:157], v[198:199]
	v_lshlrev_b32_e32 v158, 16, v165
	v_and_b32_e32 v159, 0xffff0000, v165
	v_pk_add_f32 v[196:197], v[156:157], v[158:159] neg_lo:[0,1] neg_hi:[0,1]
	v_cvt_pk_bf16_f32 v169, v196, v197
	v_lshlrev_b32_e32 v156, 16, v166
	v_and_b32_e32 v157, 0xffff0000, v166
	v_lshlrev_b32_e32 v158, 16, v170
	v_and_b32_e32 v159, 0xffff0000, v170
	v_pk_add_f32 v[156:157], v[156:157], v[158:159]
	v_pk_fma_f32 v[156:157], v[106:107], 0.5, v[156:157] op_sel_hi:[1,0,1]
	v_cvt_pk_bf16_f32 v166, v156, v157
	v_pk_fma_f32 v[198:199], v[156:157], v[156:157], v[198:199]
	v_lshlrev_b32_e32 v158, 16, v166
	v_and_b32_e32 v159, 0xffff0000, v166
	v_pk_add_f32 v[196:197], v[156:157], v[158:159] neg_lo:[0,1] neg_hi:[0,1]
	v_cvt_pk_bf16_f32 v170, v196, v197
	v_lshlrev_b32_e32 v156, 16, v167
	v_and_b32_e32 v157, 0xffff0000, v167
	v_lshlrev_b32_e32 v158, 16, v171
	v_and_b32_e32 v159, 0xffff0000, v171
	v_pk_add_f32 v[156:157], v[156:157], v[158:159]
	v_pk_fma_f32 v[156:157], v[108:109], 0.5, v[156:157] op_sel_hi:[1,0,1]
	v_cvt_pk_bf16_f32 v167, v156, v157
	v_pk_fma_f32 v[198:199], v[156:157], v[156:157], v[198:199]
	v_lshlrev_b32_e32 v158, 16, v167
	v_and_b32_e32 v159, 0xffff0000, v167
	v_pk_add_f32 v[196:197], v[156:157], v[158:159] neg_lo:[0,1] neg_hi:[0,1]
	v_cvt_pk_bf16_f32 v171, v196, v197
	global_store_dwordx4 v211, v[164:167], s[10:11]
	global_store_dwordx4 v211, v[168:171], s[6:7]
	s_waitcnt vmcnt(14)
	v_lshlrev_b32_e32 v156, 16, v172
	v_and_b32_e32 v157, 0xffff0000, v172
	v_lshlrev_b32_e32 v158, 16, v176
	v_and_b32_e32 v159, 0xffff0000, v176
	v_pk_add_f32 v[156:157], v[156:157], v[158:159]
	v_pk_fma_f32 v[156:157], v[102:103], 0.5, v[156:157] op_sel_hi:[1,0,1]
	v_cvt_pk_bf16_f32 v172, v156, v157
	v_pk_fma_f32 v[198:199], v[156:157], v[156:157], v[198:199]
	v_lshlrev_b32_e32 v158, 16, v172
	v_and_b32_e32 v159, 0xffff0000, v172
	v_pk_add_f32 v[196:197], v[156:157], v[158:159] neg_lo:[0,1] neg_hi:[0,1]
	v_cvt_pk_bf16_f32 v176, v196, v197
	v_lshlrev_b32_e32 v156, 16, v173
	v_and_b32_e32 v157, 0xffff0000, v173
	v_lshlrev_b32_e32 v158, 16, v177
	v_and_b32_e32 v159, 0xffff0000, v177
	v_pk_add_f32 v[156:157], v[156:157], v[158:159]
	v_pk_fma_f32 v[156:157], v[104:105], 0.5, v[156:157] op_sel_hi:[1,0,1]
	v_cvt_pk_bf16_f32 v173, v156, v157
	v_pk_fma_f32 v[198:199], v[156:157], v[156:157], v[198:199]
	v_lshlrev_b32_e32 v158, 16, v173
	v_and_b32_e32 v159, 0xffff0000, v173
	v_pk_add_f32 v[196:197], v[156:157], v[158:159] neg_lo:[0,1] neg_hi:[0,1]
	v_cvt_pk_bf16_f32 v177, v196, v197
	v_lshlrev_b32_e32 v156, 16, v174
	v_and_b32_e32 v157, 0xffff0000, v174
	v_lshlrev_b32_e32 v158, 16, v178
	v_and_b32_e32 v159, 0xffff0000, v178
	v_pk_add_f32 v[156:157], v[156:157], v[158:159]
	v_pk_fma_f32 v[156:157], v[98:99], 0.5, v[156:157] op_sel_hi:[1,0,1]
	v_cvt_pk_bf16_f32 v174, v156, v157
	v_pk_fma_f32 v[198:199], v[156:157], v[156:157], v[198:199]
	v_lshlrev_b32_e32 v158, 16, v174
	v_and_b32_e32 v159, 0xffff0000, v174
	v_pk_add_f32 v[196:197], v[156:157], v[158:159] neg_lo:[0,1] neg_hi:[0,1]
	v_cvt_pk_bf16_f32 v178, v196, v197
	v_lshlrev_b32_e32 v156, 16, v175
	v_and_b32_e32 v157, 0xffff0000, v175
	v_lshlrev_b32_e32 v158, 16, v179
	v_and_b32_e32 v159, 0xffff0000, v179
	v_pk_add_f32 v[156:157], v[156:157], v[158:159]
	v_pk_fma_f32 v[156:157], v[100:101], 0.5, v[156:157] op_sel_hi:[1,0,1]
	v_cvt_pk_bf16_f32 v175, v156, v157
	v_pk_fma_f32 v[198:199], v[156:157], v[156:157], v[198:199]
	v_lshlrev_b32_e32 v158, 16, v175
	v_and_b32_e32 v159, 0xffff0000, v175
	v_pk_add_f32 v[196:197], v[156:157], v[158:159] neg_lo:[0,1] neg_hi:[0,1]
	v_cvt_pk_bf16_f32 v179, v196, v197
	global_store_dwordx4 v211, v[172:175], s[10:11] offset:256
	global_store_dwordx4 v211, v[176:179], s[6:7] offset:256
	v_add_f32_e32 v201, v198, v199
	s_nop 0
	v_add_u32_e32 v211, 0x40000, v213
	global_load_dwordx4 v[164:167], v211, s[10:11]
	global_load_dwordx4 v[168:171], v211, s[6:7]
	global_load_dwordx4 v[172:175], v211, s[10:11] offset:256
	global_load_dwordx4 v[176:179], v211, s[6:7] offset:256
	s_waitcnt vmcnt(18)
; __device__ __forceinline__ unsigned pk2(float lo, float hi) { f32x2_t v = {lo, hi}; bf16x2_t b = __builtin_convertvector(v, bf16x2_t); return __builtin_bit_cast(unsigned, b); }
; __device__ __forceinline__ float bflo(unsigned u) { return __uint_as_float(u << 16); }
;     __device__ __forceinline__ void operator()(const f32x4 (&acc)[2][2][4][2], const Unit& u, int wr, int wc, int fr, int fq) const {
;     ...
;                 for (int bj = 0; bj < 2; ++bj) {
;                     const size_t off = (size_t)row * DM + col0 + bj * HALF;
;                     const u32x4 hh = *(const u32x4*)(HI + off), ll = *(const u32x4*)(LO + off);
;                     float hv[8] = {bflo(hh.x) + bflo(ll.x), bfhi(hh.x) + bfhi(ll.x), bflo(hh.y) + bflo(ll.y), bfhi(hh.y) + bfhi(ll.y),
;                                    bflo(hh.z) + bflo(ll.z), bfhi(hh.z) + bfhi(ll.z), bflo(hh.w) + bflo(ll.w), bfhi(hh.w) + bfhi(ll.w)};
;                     float av[8] = {acc[ai][bj][m][0][0], acc[ai][bj][m][0][1], acc[ai][bj][m][0][2], acc[ai][bj][m][0][3], acc[ai][bj][m][1][0], acc[ai][bj][m][1][1], acc[ai][bj][m][1][2], acc[ai][bj][m][1][3]};
;                     if (GATED) { const u32x4 pp = *(const u32x4*)(PP + off);
;                         const float pv[8] = {bflo(pp.x), bfhi(pp.x), bflo(pp.y), bfhi(pp.y), bflo(pp.z), bfhi(pp.z), bflo(pp.w), bfhi(pp.w)};
; #pragma unroll
;                         for (int e = 0; e < 8; ++e) av[e] = fast_sigmoid(av[e] * rs) * pv[e]; }
;                     else {
; #pragma unroll
;                         for (int e = 0; e < 8; ++e) av[e] *= alpha; }
;                     float lo[8];
; #pragma unroll
;                     for (int e = 0; e < 8; ++e) { hv[e] += av[e]; sq += hv[e] * hv[e]; }
;                     u32x4 wh; wh.x = pk2(hv[0], hv[1]); wh.y = pk2(hv[2], hv[3]); wh.z = pk2(hv[4], hv[5]); wh.w = pk2(hv[6], hv[7]);
;                     lo[0] = hv[0] - bflo(wh.x); lo[1] = hv[1] - bfhi(wh.x); lo[2] = hv[2] - bflo(wh.y); lo[3] = hv[3] - bfhi(wh.y);
;                     lo[4] = hv[4] - bflo(wh.z); lo[5] = hv[5] - bfhi(wh.z); lo[6] = hv[6] - bflo(wh.w); lo[7] = hv[7] - bfhi(wh.w);
;                     u32x4 wl; wl.x = pk2(lo[0], lo[1]); wl.y = pk2(lo[2], lo[3]); wl.z = pk2(lo[4], lo[5]); wl.w = pk2(lo[6], lo[7]);
;                     *(u32x4*)(HO + off) = wh; *(u32x4*)(LO + off) = wl;
;                 }
	v_lshlrev_b32_e32 v156, 16, v180
	v_and_b32_e32 v157, 0xffff0000, v180
	v_lshlrev_b32_e32 v158, 16, v184
	v_and_b32_e32 v159, 0xffff0000, v184
	v_pk_add_f32 v[156:157], v[156:157], v[158:159]
	v_pk_fma_f32 v[156:157], v[94:95], 0.5, v[156:157] op_sel_hi:[1,0,1]
	v_cvt_pk_bf16_f32 v180, v156, v157
	v_pk_mul_f32 v[198:199], v[156:157], v[156:157]
	v_lshlrev_b32_e32 v158, 16, v180
	v_and_b32_e32 v159, 0xffff0000, v180
	v_pk_add_f32 v[196:197], v[156:157], v[158:159] neg_lo:[0,1] neg_hi:[0,1]
	v_cvt_pk_bf16_f32 v184, v196, v197
	v_lshlrev_b32_e32 v156, 16, v181
	v_and_b32_e32 v157, 0xffff0000, v181
	v_lshlrev_b32_e32 v158, 16, v185
	v_and_b32_e32 v159, 0xffff0000, v185
	v_pk_add_f32 v[156:157], v[156:157], v[158:159]
	v_pk_fma_f32 v[156:157], v[96:97], 0.5, v[156:157] op_sel_hi:[1,0,1]
	v_cvt_pk_bf16_f32 v181, v156, v157
	v_pk_fma_f32 v[198:199], v[156:157], v[156:157], v[198:199]
	v_lshlrev_b32_e32 v158, 16, v181
	v_and_b32_e32 v159, 0xffff0000, v181
	v_pk_add_f32 v[196:197], v[156:157], v[158:159] neg_lo:[0,1] neg_hi:[0,1]
	v_cvt_pk_bf16_f32 v185, v196, v197
	v_lshlrev_b32_e32 v156, 16, v182
	v_and_b32_e32 v157, 0xffff0000, v182
	v_lshlrev_b32_e32 v158, 16, v186
	v_and_b32_e32 v159, 0xffff0000, v186
	v_pk_add_f32 v[156:157], v[156:157], v[158:159]
	v_pk_fma_f32 v[156:157], v[90:91], 0.5, v[156:157] op_sel_hi:[1,0,1]
	v_cvt_pk_bf16_f32 v182, v156, v157
	v_pk_fma_f32 v[198:199], v[156:157], v[156:157], v[198:199]
	v_lshlrev_b32_e32 v158, 16, v182
	v_and_b32_e32 v159, 0xffff0000, v182
	v_pk_add_f32 v[196:197], v[156:157], v[158:159] neg_lo:[0,1] neg_hi:[0,1]
	v_cvt_pk_bf16_f32 v186, v196, v197
	v_lshlrev_b32_e32 v156, 16, v183
	v_and_b32_e32 v157, 0xffff0000, v183
	v_lshlrev_b32_e32 v158, 16, v187
	v_and_b32_e32 v159, 0xffff0000, v187
	v_pk_add_f32 v[156:157], v[156:157], v[158:159]
	v_pk_fma_f32 v[156:157], v[92:93], 0.5, v[156:157] op_sel_hi:[1,0,1]
	v_cvt_pk_bf16_f32 v183, v156, v157
	v_pk_fma_f32 v[198:199], v[156:157], v[156:157], v[198:199]
	v_lshlrev_b32_e32 v158, 16, v183
	v_and_b32_e32 v159, 0xffff0000, v183
	v_pk_add_f32 v[196:197], v[156:157], v[158:159] neg_lo:[0,1] neg_hi:[0,1]
	v_cvt_pk_bf16_f32 v187, v196, v197
	global_store_dwordx4 v212, v[180:183], s[10:11]
	global_store_dwordx4 v212, v[184:187], s[6:7]
	s_waitcnt vmcnt(18)
	v_lshlrev_b32_e32 v156, 16, v188
	v_and_b32_e32 v157, 0xffff0000, v188
	v_lshlrev_b32_e32 v158, 16, v192
	v_and_b32_e32 v159, 0xffff0000, v192
	v_pk_add_f32 v[156:157], v[156:157], v[158:159]
	v_pk_fma_f32 v[156:157], v[86:87], 0.5, v[156:157] op_sel_hi:[1,0,1]
	v_cvt_pk_bf16_f32 v188, v156, v157
	v_pk_fma_f32 v[198:199], v[156:157], v[156:157], v[198:199]
	v_lshlrev_b32_e32 v158, 16, v188
	v_and_b32_e32 v159, 0xffff0000, v188
	v_pk_add_f32 v[196:197], v[156:157], v[158:159] neg_lo:[0,1] neg_hi:[0,1]
	v_cvt_pk_bf16_f32 v192, v196, v197
	v_lshlrev_b32_e32 v156, 16, v189
	v_and_b32_e32 v157, 0xffff0000, v189
	v_lshlrev_b32_e32 v158, 16, v193
	v_and_b32_e32 v159, 0xffff0000, v193
	v_pk_add_f32 v[156:157], v[156:157], v[158:159]
	v_pk_fma_f32 v[156:157], v[88:89], 0.5, v[156:157] op_sel_hi:[1,0,1]
	v_cvt_pk_bf16_f32 v189, v156, v157
	v_pk_fma_f32 v[198:199], v[156:157], v[156:157], v[198:199]
	v_lshlrev_b32_e32 v158, 16, v189
	v_and_b32_e32 v159, 0xffff0000, v189
	v_pk_add_f32 v[196:197], v[156:157], v[158:159] neg_lo:[0,1] neg_hi:[0,1]
	v_cvt_pk_bf16_f32 v193, v196, v197
	v_lshlrev_b32_e32 v156, 16, v190
	v_and_b32_e32 v157, 0xffff0000, v190
	v_lshlrev_b32_e32 v158, 16, v194
	v_and_b32_e32 v159, 0xffff0000, v194
	v_pk_add_f32 v[156:157], v[156:157], v[158:159]
	v_pk_fma_f32 v[156:157], v[82:83], 0.5, v[156:157] op_sel_hi:[1,0,1]
	v_cvt_pk_bf16_f32 v190, v156, v157
	v_pk_fma_f32 v[198:199], v[156:157], v[156:157], v[198:199]
	v_lshlrev_b32_e32 v158, 16, v190
	v_and_b32_e32 v159, 0xffff0000, v190
	v_pk_add_f32 v[196:197], v[156:157], v[158:159] neg_lo:[0,1] neg_hi:[0,1]
	v_cvt_pk_bf16_f32 v194, v196, v197
	v_lshlrev_b32_e32 v156, 16, v191
	v_and_b32_e32 v157, 0xffff0000, v191
	v_lshlrev_b32_e32 v158, 16, v195
	v_and_b32_e32 v159, 0xffff0000, v195
	v_pk_add_f32 v[156:157], v[156:157], v[158:159]
	v_pk_fma_f32 v[156:157], v[84:85], 0.5, v[156:157] op_sel_hi:[1,0,1]
	v_cvt_pk_bf16_f32 v191, v156, v157
	v_pk_fma_f32 v[198:199], v[156:157], v[156:157], v[198:199]
	v_lshlrev_b32_e32 v158, 16, v191
	v_and_b32_e32 v159, 0xffff0000, v191
	v_pk_add_f32 v[196:197], v[156:157], v[158:159] neg_lo:[0,1] neg_hi:[0,1]
	v_cvt_pk_bf16_f32 v195, v196, v197
	global_store_dwordx4 v212, v[188:191], s[10:11] offset:256
	global_store_dwordx4 v212, v[192:195], s[6:7] offset:256
	v_add_f32_e32 v202, v198, v199
	s_nop 0
	v_add_u32_e32 v212, 0x48000, v213
	global_load_dwordx4 v[180:183], v212, s[10:11]
	global_load_dwordx4 v[184:187], v212, s[6:7]
	global_load_dwordx4 v[188:191], v212, s[10:11] offset:256
	global_load_dwordx4 v[192:195], v212, s[6:7] offset:256
	s_waitcnt vmcnt(22)
; __device__ __forceinline__ unsigned pk2(float lo, float hi) { f32x2_t v = {lo, hi}; bf16x2_t b = __builtin_convertvector(v, bf16x2_t); return __builtin_bit_cast(unsigned, b); }
; __device__ __forceinline__ float bflo(unsigned u) { return __uint_as_float(u << 16); }
;     __device__ __forceinline__ void operator()(const f32x4 (&acc)[2][2][4][2], const Unit& u, int wr, int wc, int fr, int fq) const {
;     ...
;                 for (int bj = 0; bj < 2; ++bj) {
;                     const size_t off = (size_t)row * DM + col0 + bj * HALF;
;                     const u32x4 hh = *(const u32x4*)(HI + off), ll = *(const u32x4*)(LO + off);
;                     float hv[8] = {bflo(hh.x) + bflo(ll.x), bfhi(hh.x) + bfhi(ll.x), bflo(hh.y) + bflo(ll.y), bfhi(hh.y) + bfhi(ll.y),
;                                    bflo(hh.z) + bflo(ll.z), bfhi(hh.z) + bfhi(ll.z), bflo(hh.w) + bflo(ll.w), bfhi(hh.w) + bfhi(ll.w)};
;                     float av[8] = {acc[ai][bj][m][0][0], acc[ai][bj][m][0][1], acc[ai][bj][m][0][2], acc[ai][bj][m][0][3], acc[ai][bj][m][1][0], acc[ai][bj][m][1][1], acc[ai][bj][m][1][2], acc[ai][bj][m][1][3]};
;                     if (GATED) { const u32x4 pp = *(const u32x4*)(PP + off);
;                         const float pv[8] = {bflo(pp.x), bfhi(pp.x), bflo(pp.y), bfhi(pp.y), bflo(pp.z), bfhi(pp.z), bflo(pp.w), bfhi(pp.w)};
; #pragma unroll
;                         for (int e = 0; e < 8; ++e) av[e] = fast_sigmoid(av[e] * rs) * pv[e]; }
;                     else {
; #pragma unroll
;                         for (int e = 0; e < 8; ++e) av[e] *= alpha; }
;                     float lo[8];
; #pragma unroll
;                     for (int e = 0; e < 8; ++e) { hv[e] += av[e]; sq += hv[e] * hv[e]; }
;                     u32x4 wh; wh.x = pk2(hv[0], hv[1]); wh.y = pk2(hv[2], hv[3]); wh.z = pk2(hv[4], hv[5]); wh.w = pk2(hv[6], hv[7]);
;                     lo[0] = hv[0] - bflo(wh.x); lo[1] = hv[1] - bfhi(wh.x); lo[2] = hv[2] - bflo(wh.y); lo[3] = hv[3] - bfhi(wh.y);
;                     lo[4] = hv[4] - bflo(wh.z); lo[5] = hv[5] - bfhi(wh.z); lo[6] = hv[6] - bflo(wh.w); lo[7] = hv[7] - bfhi(wh.w);
;                     u32x4 wl; wl.x = pk2(lo[0], lo[1]); wl.y = pk2(lo[2], lo[3]); wl.z = pk2(lo[4], lo[5]); wl.w = pk2(lo[6], lo[7]);
;                     *(u32x4*)(HO + off) = wh; *(u32x4*)(LO + off) = wl;
;                 }
	v_lshlrev_b32_e32 v156, 16, v140
	v_and_b32_e32 v157, 0xffff0000, v140
	v_lshlrev_b32_e32 v158, 16, v144
	v_and_b32_e32 v159, 0xffff0000, v144
	v_pk_add_f32 v[156:157], v[156:157], v[158:159]
	v_pk_fma_f32 v[156:157], v[78:79], 0.5, v[156:157] op_sel_hi:[1,0,1]
	v_cvt_pk_bf16_f32 v140, v156, v157
	v_pk_mul_f32 v[198:199], v[156:157], v[156:157]
	v_lshlrev_b32_e32 v158, 16, v140
	v_and_b32_e32 v159, 0xffff0000, v140
	v_pk_add_f32 v[196:197], v[156:157], v[158:159] neg_lo:[0,1] neg_hi:[0,1]
	v_cvt_pk_bf16_f32 v144, v196, v197
	v_lshlrev_b32_e32 v156, 16, v141
	v_and_b32_e32 v157, 0xffff0000, v141
	v_lshlrev_b32_e32 v158, 16, v145
	v_and_b32_e32 v159, 0xffff0000, v145
	v_pk_add_f32 v[156:157], v[156:157], v[158:159]
	v_pk_fma_f32 v[156:157], v[80:81], 0.5, v[156:157] op_sel_hi:[1,0,1]
	v_cvt_pk_bf16_f32 v141, v156, v157
	v_pk_fma_f32 v[198:199], v[156:157], v[156:157], v[198:199]
	v_lshlrev_b32_e32 v158, 16, v141
	v_and_b32_e32 v159, 0xffff0000, v141
	v_pk_add_f32 v[196:197], v[156:157], v[158:159] neg_lo:[0,1] neg_hi:[0,1]
	v_cvt_pk_bf16_f32 v145, v196, v197
	v_lshlrev_b32_e32 v156, 16, v142
	v_and_b32_e32 v157, 0xffff0000, v142
	v_lshlrev_b32_e32 v158, 16, v146
	v_and_b32_e32 v159, 0xffff0000, v146
	v_pk_add_f32 v[156:157], v[156:157], v[158:159]
	v_pk_fma_f32 v[156:157], v[74:75], 0.5, v[156:157] op_sel_hi:[1,0,1]
	v_cvt_pk_bf16_f32 v142, v156, v157
	v_pk_fma_f32 v[198:199], v[156:157], v[156:157], v[198:199]
	v_lshlrev_b32_e32 v158, 16, v142
	v_and_b32_e32 v159, 0xffff0000, v142
	v_pk_add_f32 v[196:197], v[156:157], v[158:159] neg_lo:[0,1] neg_hi:[0,1]
	v_cvt_pk_bf16_f32 v146, v196, v197
	v_lshlrev_b32_e32 v156, 16, v143
	v_and_b32_e32 v157, 0xffff0000, v143
	v_lshlrev_b32_e32 v158, 16, v147
	v_and_b32_e32 v159, 0xffff0000, v147
	v_pk_add_f32 v[156:157], v[156:157], v[158:159]
	v_pk_fma_f32 v[156:157], v[76:77], 0.5, v[156:157] op_sel_hi:[1,0,1]
	v_cvt_pk_bf16_f32 v143, v156, v157
	v_pk_fma_f32 v[198:199], v[156:157], v[156:157], v[198:199]
	v_lshlrev_b32_e32 v158, 16, v143
	v_and_b32_e32 v159, 0xffff0000, v143
	v_pk_add_f32 v[196:197], v[156:157], v[158:159] neg_lo:[0,1] neg_hi:[0,1]
	v_cvt_pk_bf16_f32 v147, v196, v197
	global_store_dwordx4 v210, v[140:143], s[10:11]
	global_store_dwordx4 v210, v[144:147], s[6:7]
	s_waitcnt vmcnt(22)
	v_lshlrev_b32_e32 v156, 16, v148
	v_and_b32_e32 v157, 0xffff0000, v148
	v_lshlrev_b32_e32 v158, 16, v152
	v_and_b32_e32 v159, 0xffff0000, v152
	v_pk_add_f32 v[156:157], v[156:157], v[158:159]
	v_pk_fma_f32 v[156:157], v[70:71], 0.5, v[156:157] op_sel_hi:[1,0,1]
	v_cvt_pk_bf16_f32 v148, v156, v157
	v_pk_fma_f32 v[198:199], v[156:157], v[156:157], v[198:199]
	v_lshlrev_b32_e32 v158, 16, v148
	v_and_b32_e32 v159, 0xffff0000, v148
	v_pk_add_f32 v[196:197], v[156:157], v[158:159] neg_lo:[0,1] neg_hi:[0,1]
	v_cvt_pk_bf16_f32 v152, v196, v197
	v_lshlrev_b32_e32 v156, 16, v149
	v_and_b32_e32 v157, 0xffff0000, v149
	v_lshlrev_b32_e32 v158, 16, v153
	v_and_b32_e32 v159, 0xffff0000, v153
	v_pk_add_f32 v[156:157], v[156:157], v[158:159]
	v_pk_fma_f32 v[156:157], v[72:73], 0.5, v[156:157] op_sel_hi:[1,0,1]
	v_cvt_pk_bf16_f32 v149, v156, v157
	v_pk_fma_f32 v[198:199], v[156:157], v[156:157], v[198:199]
	v_lshlrev_b32_e32 v158, 16, v149
	v_and_b32_e32 v159, 0xffff0000, v149
	v_pk_add_f32 v[196:197], v[156:157], v[158:159] neg_lo:[0,1] neg_hi:[0,1]
	v_cvt_pk_bf16_f32 v153, v196, v197
	v_lshlrev_b32_e32 v156, 16, v150
	v_and_b32_e32 v157, 0xffff0000, v150
	v_lshlrev_b32_e32 v158, 16, v154
	v_and_b32_e32 v159, 0xffff0000, v154
	v_pk_add_f32 v[156:157], v[156:157], v[158:159]
	v_pk_fma_f32 v[156:157], v[66:67], 0.5, v[156:157] op_sel_hi:[1,0,1]
	v_cvt_pk_bf16_f32 v150, v156, v157
	v_pk_fma_f32 v[198:199], v[156:157], v[156:157], v[198:199]
	v_lshlrev_b32_e32 v158, 16, v150
	v_and_b32_e32 v159, 0xffff0000, v150
	v_pk_add_f32 v[196:197], v[156:157], v[158:159] neg_lo:[0,1] neg_hi:[0,1]
	v_cvt_pk_bf16_f32 v154, v196, v197
	v_lshlrev_b32_e32 v156, 16, v151
	v_and_b32_e32 v157, 0xffff0000, v151
	v_lshlrev_b32_e32 v158, 16, v155
	v_and_b32_e32 v159, 0xffff0000, v155
	v_pk_add_f32 v[156:157], v[156:157], v[158:159]
	v_pk_fma_f32 v[156:157], v[68:69], 0.5, v[156:157] op_sel_hi:[1,0,1]
	v_cvt_pk_bf16_f32 v151, v156, v157
	v_pk_fma_f32 v[198:199], v[156:157], v[156:157], v[198:199]
	v_lshlrev_b32_e32 v158, 16, v151
	v_and_b32_e32 v159, 0xffff0000, v151
	v_pk_add_f32 v[196:197], v[156:157], v[158:159] neg_lo:[0,1] neg_hi:[0,1]
	v_cvt_pk_bf16_f32 v155, v196, v197
	global_store_dwordx4 v210, v[148:151], s[10:11] offset:256
	global_store_dwordx4 v210, v[152:155], s[6:7] offset:256
	v_add_f32_e32 v203, v198, v199
	s_nop 0
	v_add_u32_e32 v210, 0x50000, v213
	global_load_dwordx4 v[140:143], v210, s[10:11]
	global_load_dwordx4 v[144:147], v210, s[6:7]
	global_load_dwordx4 v[148:151], v210, s[10:11] offset:256
	global_load_dwordx4 v[152:155], v210, s[6:7] offset:256
	s_waitcnt vmcnt(18)
; __device__ __forceinline__ unsigned pk2(float lo, float hi) { f32x2_t v = {lo, hi}; bf16x2_t b = __builtin_convertvector(v, bf16x2_t); return __builtin_bit_cast(unsigned, b); }
; __device__ __forceinline__ float bflo(unsigned u) { return __uint_as_float(u << 16); }
;     __device__ __forceinline__ void operator()(const f32x4 (&acc)[2][2][4][2], const Unit& u, int wr, int wc, int fr, int fq) const {
;     ...
;                 for (int bj = 0; bj < 2; ++bj) {
;                     const size_t off = (size_t)row * DM + col0 + bj * HALF;
;                     const u32x4 hh = *(const u32x4*)(HI + off), ll = *(const u32x4*)(LO + off);
;                     float hv[8] = {bflo(hh.x) + bflo(ll.x), bfhi(hh.x) + bfhi(ll.x), bflo(hh.y) + bflo(ll.y), bfhi(hh.y) + bfhi(ll.y),
;                                    bflo(hh.z) + bflo(ll.z), bfhi(hh.z) + bfhi(ll.z), bflo(hh.w) + bflo(ll.w), bfhi(hh.w) + bfhi(ll.w)};
;                     float av[8] = {acc[ai][bj][m][0][0], acc[ai][bj][m][0][1], acc[ai][bj][m][0][2], acc[ai][bj][m][0][3], acc[ai][bj][m][1][0], acc[ai][bj][m][1][1], acc[ai][bj][m][1][2], acc[ai][bj][m][1][3]};
;                     if (GATED) { const u32x4 pp = *(const u32x4*)(PP + off);
;                         const float pv[8] = {bflo(pp.x), bfhi(pp.x), bflo(pp.y), bfhi(pp.y), bflo(pp.z), bfhi(pp.z), bflo(pp.w), bfhi(pp.w)};
; #pragma unroll
;                         for (int e = 0; e < 8; ++e) av[e] = fast_sigmoid(av[e] * rs) * pv[e]; }
;                     else {
; #pragma unroll
;                         for (int e = 0; e < 8; ++e) av[e] *= alpha; }
;                     float lo[8];
; #pragma unroll
;                     for (int e = 0; e < 8; ++e) { hv[e] += av[e]; sq += hv[e] * hv[e]; }
;                     u32x4 wh; wh.x = pk2(hv[0], hv[1]); wh.y = pk2(hv[2], hv[3]); wh.z = pk2(hv[4], hv[5]); wh.w = pk2(hv[6], hv[7]);
;                     lo[0] = hv[0] - bflo(wh.x); lo[1] = hv[1] - bfhi(wh.x); lo[2] = hv[2] - bflo(wh.y); lo[3] = hv[3] - bfhi(wh.y);
;                     lo[4] = hv[4] - bflo(wh.z); lo[5] = hv[5] - bfhi(wh.z); lo[6] = hv[6] - bflo(wh.w); lo[7] = hv[7] - bfhi(wh.w);
;                     u32x4 wl; wl.x = pk2(lo[0], lo[1]); wl.y = pk2(lo[2], lo[3]); wl.z = pk2(lo[4], lo[5]); wl.w = pk2(lo[6], lo[7]);
;                     *(u32x4*)(HO + off) = wh; *(u32x4*)(LO + off) = wl;
;                 }
	v_lshlrev_b32_e32 v156, 16, v164
	v_and_b32_e32 v157, 0xffff0000, v164
	v_lshlrev_b32_e32 v158, 16, v168
	v_and_b32_e32 v159, 0xffff0000, v168
	v_pk_add_f32 v[156:157], v[156:157], v[158:159]
	v_pk_fma_f32 v[156:157], v[62:63], 0.5, v[156:157] op_sel_hi:[1,0,1]
	v_cvt_pk_bf16_f32 v164, v156, v157
	v_pk_mul_f32 v[198:199], v[156:157], v[156:157]
	v_lshlrev_b32_e32 v158, 16, v164
	v_and_b32_e32 v159, 0xffff0000, v164
	v_pk_add_f32 v[196:197], v[156:157], v[158:159] neg_lo:[0,1] neg_hi:[0,1]
	v_cvt_pk_bf16_f32 v168, v196, v197
	v_lshlrev_b32_e32 v156, 16, v165
	v_and_b32_e32 v157, 0xffff0000, v165
	v_lshlrev_b32_e32 v158, 16, v169
	v_and_b32_e32 v159, 0xffff0000, v169
	v_pk_add_f32 v[156:157], v[156:157], v[158:159]
	v_pk_fma_f32 v[156:157], v[64:65], 0.5, v[156:157] op_sel_hi:[1,0,1]
	v_cvt_pk_bf16_f32 v165, v156, v157
	v_pk_fma_f32 v[198:199], v[156:157], v[156:157], v[198:199]
	v_lshlrev_b32_e32 v158, 16, v165
	v_and_b32_e32 v159, 0xffff0000, v165
	v_pk_add_f32 v[196:197], v[156:157], v[158:159] neg_lo:[0,1] neg_hi:[0,1]
	v_cvt_pk_bf16_f32 v169, v196, v197
	v_lshlrev_b32_e32 v156, 16, v166
	v_and_b32_e32 v157, 0xffff0000, v166
	v_lshlrev_b32_e32 v158, 16, v170
	v_and_b32_e32 v159, 0xffff0000, v170
	v_pk_add_f32 v[156:157], v[156:157], v[158:159]
	v_pk_fma_f32 v[156:157], v[58:59], 0.5, v[156:157] op_sel_hi:[1,0,1]
	v_cvt_pk_bf16_f32 v166, v156, v157
	v_pk_fma_f32 v[198:199], v[156:157], v[156:157], v[198:199]
	v_lshlrev_b32_e32 v158, 16, v166
	v_and_b32_e32 v159, 0xffff0000, v166
	v_pk_add_f32 v[196:197], v[156:157], v[158:159] neg_lo:[0,1] neg_hi:[0,1]
	v_cvt_pk_bf16_f32 v170, v196, v197
	v_lshlrev_b32_e32 v156, 16, v167
	v_and_b32_e32 v157, 0xffff0000, v167
	v_lshlrev_b32_e32 v158, 16, v171
	v_and_b32_e32 v159, 0xffff0000, v171
	v_pk_add_f32 v[156:157], v[156:157], v[158:159]
	v_pk_fma_f32 v[156:157], v[60:61], 0.5, v[156:157] op_sel_hi:[1,0,1]
	v_cvt_pk_bf16_f32 v167, v156, v157
	v_pk_fma_f32 v[198:199], v[156:157], v[156:157], v[198:199]
	v_lshlrev_b32_e32 v158, 16, v167
	v_and_b32_e32 v159, 0xffff0000, v167
	v_pk_add_f32 v[196:197], v[156:157], v[158:159] neg_lo:[0,1] neg_hi:[0,1]
	v_cvt_pk_bf16_f32 v171, v196, v197
	global_store_dwordx4 v211, v[164:167], s[10:11]
	global_store_dwordx4 v211, v[168:171], s[6:7]
	s_waitcnt vmcnt(18)
	v_lshlrev_b32_e32 v156, 16, v172
	v_and_b32_e32 v157, 0xffff0000, v172
	v_lshlrev_b32_e32 v158, 16, v176
	v_and_b32_e32 v159, 0xffff0000, v176
	v_pk_add_f32 v[156:157], v[156:157], v[158:159]
	v_pk_fma_f32 v[156:157], v[54:55], 0.5, v[156:157] op_sel_hi:[1,0,1]
	v_cvt_pk_bf16_f32 v172, v156, v157
	v_pk_fma_f32 v[198:199], v[156:157], v[156:157], v[198:199]
	v_lshlrev_b32_e32 v158, 16, v172
	v_and_b32_e32 v159, 0xffff0000, v172
	v_pk_add_f32 v[196:197], v[156:157], v[158:159] neg_lo:[0,1] neg_hi:[0,1]
	v_cvt_pk_bf16_f32 v176, v196, v197
	v_lshlrev_b32_e32 v156, 16, v173
	v_and_b32_e32 v157, 0xffff0000, v173
	v_lshlrev_b32_e32 v158, 16, v177
	v_and_b32_e32 v159, 0xffff0000, v177
	v_pk_add_f32 v[156:157], v[156:157], v[158:159]
	v_pk_fma_f32 v[156:157], v[56:57], 0.5, v[156:157] op_sel_hi:[1,0,1]
	v_cvt_pk_bf16_f32 v173, v156, v157
	v_pk_fma_f32 v[198:199], v[156:157], v[156:157], v[198:199]
	v_lshlrev_b32_e32 v158, 16, v173
	v_and_b32_e32 v159, 0xffff0000, v173
	v_pk_add_f32 v[196:197], v[156:157], v[158:159] neg_lo:[0,1] neg_hi:[0,1]
	v_cvt_pk_bf16_f32 v177, v196, v197
	v_lshlrev_b32_e32 v156, 16, v174
	v_and_b32_e32 v157, 0xffff0000, v174
	v_lshlrev_b32_e32 v158, 16, v178
	v_and_b32_e32 v159, 0xffff0000, v178
	v_pk_add_f32 v[156:157], v[156:157], v[158:159]
	v_pk_fma_f32 v[156:157], v[50:51], 0.5, v[156:157] op_sel_hi:[1,0,1]
	v_cvt_pk_bf16_f32 v174, v156, v157
	v_pk_fma_f32 v[198:199], v[156:157], v[156:157], v[198:199]
	v_lshlrev_b32_e32 v158, 16, v174
	v_and_b32_e32 v159, 0xffff0000, v174
	v_pk_add_f32 v[196:197], v[156:157], v[158:159] neg_lo:[0,1] neg_hi:[0,1]
	v_cvt_pk_bf16_f32 v178, v196, v197
	v_lshlrev_b32_e32 v156, 16, v175
	v_and_b32_e32 v157, 0xffff0000, v175
	v_lshlrev_b32_e32 v158, 16, v179
	v_and_b32_e32 v159, 0xffff0000, v179
	v_pk_add_f32 v[156:157], v[156:157], v[158:159]
	v_pk_fma_f32 v[156:157], v[52:53], 0.5, v[156:157] op_sel_hi:[1,0,1]
	v_cvt_pk_bf16_f32 v175, v156, v157
	v_pk_fma_f32 v[198:199], v[156:157], v[156:157], v[198:199]
	v_lshlrev_b32_e32 v158, 16, v175
	v_and_b32_e32 v159, 0xffff0000, v175
	v_pk_add_f32 v[196:197], v[156:157], v[158:159] neg_lo:[0,1] neg_hi:[0,1]
	v_cvt_pk_bf16_f32 v179, v196, v197
	global_store_dwordx4 v211, v[172:175], s[10:11] offset:256
	global_store_dwordx4 v211, v[176:179], s[6:7] offset:256
	v_add_f32_e32 v206, v198, v199
	s_nop 0
	v_add_u32_e32 v211, 0x58000, v213
	global_load_dwordx4 v[164:167], v211, s[10:11]
	global_load_dwordx4 v[168:171], v211, s[6:7]
	global_load_dwordx4 v[172:175], v211, s[10:11] offset:256
	global_load_dwordx4 v[176:179], v211, s[6:7] offset:256
	s_waitcnt vmcnt(18)
; __device__ __forceinline__ unsigned pk2(float lo, float hi) { f32x2_t v = {lo, hi}; bf16x2_t b = __builtin_convertvector(v, bf16x2_t); return __builtin_bit_cast(unsigned, b); }
; __device__ __forceinline__ float bflo(unsigned u) { return __uint_as_float(u << 16); }
;     __device__ __forceinline__ void operator()(const f32x4 (&acc)[2][2][4][2], const Unit& u, int wr, int wc, int fr, int fq) const {
;     ...
;                 for (int bj = 0; bj < 2; ++bj) {
;                     const size_t off = (size_t)row * DM + col0 + bj * HALF;
;                     const u32x4 hh = *(const u32x4*)(HI + off), ll = *(const u32x4*)(LO + off);
;                     float hv[8] = {bflo(hh.x) + bflo(ll.x), bfhi(hh.x) + bfhi(ll.x), bflo(hh.y) + bflo(ll.y), bfhi(hh.y) + bfhi(ll.y),
;                                    bflo(hh.z) + bflo(ll.z), bfhi(hh.z) + bfhi(ll.z), bflo(hh.w) + bflo(ll.w), bfhi(hh.w) + bfhi(ll.w)};
;                     float av[8] = {acc[ai][bj][m][0][0], acc[ai][bj][m][0][1], acc[ai][bj][m][0][2], acc[ai][bj][m][0][3], acc[ai][bj][m][1][0], acc[ai][bj][m][1][1], acc[ai][bj][m][1][2], acc[ai][bj][m][1][3]};
;                     if (GATED) { const u32x4 pp = *(const u32x4*)(PP + off);
;                         const float pv[8] = {bflo(pp.x), bfhi(pp.x), bflo(pp.y), bfhi(pp.y), bflo(pp.z), bfhi(pp.z), bflo(pp.w), bfhi(pp.w)};
; #pragma unroll
;                         for (int e = 0; e < 8; ++e) av[e] = fast_sigmoid(av[e] * rs) * pv[e]; }
;                     else {
; #pragma unroll
;                         for (int e = 0; e < 8; ++e) av[e] *= alpha; }
;                     float lo[8];
; #pragma unroll
;                     for (int e = 0; e < 8; ++e) { hv[e] += av[e]; sq += hv[e] * hv[e]; }
;                     u32x4 wh; wh.x = pk2(hv[0], hv[1]); wh.y = pk2(hv[2], hv[3]); wh.z = pk2(hv[4], hv[5]); wh.w = pk2(hv[6], hv[7]);
;                     lo[0] = hv[0] - bflo(wh.x); lo[1] = hv[1] - bfhi(wh.x); lo[2] = hv[2] - bflo(wh.y); lo[3] = hv[3] - bfhi(wh.y);
;                     lo[4] = hv[4] - bflo(wh.z); lo[5] = hv[5] - bfhi(wh.z); lo[6] = hv[6] - bflo(wh.w); lo[7] = hv[7] - bfhi(wh.w);
;                     u32x4 wl; wl.x = pk2(lo[0], lo[1]); wl.y = pk2(lo[2], lo[3]); wl.z = pk2(lo[4], lo[5]); wl.w = pk2(lo[6], lo[7]);
;                     *(u32x4*)(HO + off) = wh; *(u32x4*)(LO + off) = wl;
;                 }
	v_lshlrev_b32_e32 v156, 16, v180
	v_and_b32_e32 v157, 0xffff0000, v180
	v_lshlrev_b32_e32 v158, 16, v184
	v_and_b32_e32 v159, 0xffff0000, v184
	v_pk_add_f32 v[156:157], v[156:157], v[158:159]
	v_pk_fma_f32 v[156:157], v[46:47], 0.5, v[156:157] op_sel_hi:[1,0,1]
	v_cvt_pk_bf16_f32 v180, v156, v157
	v_pk_mul_f32 v[198:199], v[156:157], v[156:157]
	v_lshlrev_b32_e32 v158, 16, v180
	v_and_b32_e32 v159, 0xffff0000, v180
	v_pk_add_f32 v[196:197], v[156:157], v[158:159] neg_lo:[0,1] neg_hi:[0,1]
	v_cvt_pk_bf16_f32 v184, v196, v197
	v_lshlrev_b32_e32 v156, 16, v181
	v_and_b32_e32 v157, 0xffff0000, v181
	v_lshlrev_b32_e32 v158, 16, v185
	v_and_b32_e32 v159, 0xffff0000, v185
	v_pk_add_f32 v[156:157], v[156:157], v[158:159]
	v_pk_fma_f32 v[156:157], v[48:49], 0.5, v[156:157] op_sel_hi:[1,0,1]
	v_cvt_pk_bf16_f32 v181, v156, v157
	v_pk_fma_f32 v[198:199], v[156:157], v[156:157], v[198:199]
	v_lshlrev_b32_e32 v158, 16, v181
	v_and_b32_e32 v159, 0xffff0000, v181
	v_pk_add_f32 v[196:197], v[156:157], v[158:159] neg_lo:[0,1] neg_hi:[0,1]
	v_cvt_pk_bf16_f32 v185, v196, v197
	v_lshlrev_b32_e32 v156, 16, v182
	v_and_b32_e32 v157, 0xffff0000, v182
	v_lshlrev_b32_e32 v158, 16, v186
	v_and_b32_e32 v159, 0xffff0000, v186
	v_pk_add_f32 v[156:157], v[156:157], v[158:159]
	v_pk_fma_f32 v[156:157], v[42:43], 0.5, v[156:157] op_sel_hi:[1,0,1]
	v_cvt_pk_bf16_f32 v182, v156, v157
	v_pk_fma_f32 v[198:199], v[156:157], v[156:157], v[198:199]
	v_lshlrev_b32_e32 v158, 16, v182
	v_and_b32_e32 v159, 0xffff0000, v182
	v_pk_add_f32 v[196:197], v[156:157], v[158:159] neg_lo:[0,1] neg_hi:[0,1]
	v_cvt_pk_bf16_f32 v186, v196, v197
	v_lshlrev_b32_e32 v156, 16, v183
	v_and_b32_e32 v157, 0xffff0000, v183
	v_lshlrev_b32_e32 v158, 16, v187
	v_and_b32_e32 v159, 0xffff0000, v187
	v_pk_add_f32 v[156:157], v[156:157], v[158:159]
	v_pk_fma_f32 v[156:157], v[44:45], 0.5, v[156:157] op_sel_hi:[1,0,1]
	v_cvt_pk_bf16_f32 v183, v156, v157
	v_pk_fma_f32 v[198:199], v[156:157], v[156:157], v[198:199]
	v_lshlrev_b32_e32 v158, 16, v183
	v_and_b32_e32 v159, 0xffff0000, v183
	v_pk_add_f32 v[196:197], v[156:157], v[158:159] neg_lo:[0,1] neg_hi:[0,1]
	v_cvt_pk_bf16_f32 v187, v196, v197
	global_store_dwordx4 v212, v[180:183], s[10:11]
	global_store_dwordx4 v212, v[184:187], s[6:7]
	s_waitcnt vmcnt(18)
	v_lshlrev_b32_e32 v156, 16, v188
	v_and_b32_e32 v157, 0xffff0000, v188
	v_lshlrev_b32_e32 v158, 16, v192
	v_and_b32_e32 v159, 0xffff0000, v192
	v_pk_add_f32 v[156:157], v[156:157], v[158:159]
	v_pk_fma_f32 v[156:157], v[38:39], 0.5, v[156:157] op_sel_hi:[1,0,1]
	v_cvt_pk_bf16_f32 v188, v156, v157
	v_pk_fma_f32 v[198:199], v[156:157], v[156:157], v[198:199]
	v_lshlrev_b32_e32 v158, 16, v188
	v_and_b32_e32 v159, 0xffff0000, v188
	v_pk_add_f32 v[196:197], v[156:157], v[158:159] neg_lo:[0,1] neg_hi:[0,1]
	v_cvt_pk_bf16_f32 v192, v196, v197
	v_lshlrev_b32_e32 v156, 16, v189
	v_and_b32_e32 v157, 0xffff0000, v189
	v_lshlrev_b32_e32 v158, 16, v193
	v_and_b32_e32 v159, 0xffff0000, v193
	v_pk_add_f32 v[156:157], v[156:157], v[158:159]
	v_pk_fma_f32 v[156:157], v[40:41], 0.5, v[156:157] op_sel_hi:[1,0,1]
	v_cvt_pk_bf16_f32 v189, v156, v157
	v_pk_fma_f32 v[198:199], v[156:157], v[156:157], v[198:199]
	v_lshlrev_b32_e32 v158, 16, v189
	v_and_b32_e32 v159, 0xffff0000, v189
	v_pk_add_f32 v[196:197], v[156:157], v[158:159] neg_lo:[0,1] neg_hi:[0,1]
	v_cvt_pk_bf16_f32 v193, v196, v197
	v_lshlrev_b32_e32 v156, 16, v190
	v_and_b32_e32 v157, 0xffff0000, v190
	v_lshlrev_b32_e32 v158, 16, v194
	v_and_b32_e32 v159, 0xffff0000, v194
	v_pk_add_f32 v[156:157], v[156:157], v[158:159]
	v_pk_fma_f32 v[156:157], v[34:35], 0.5, v[156:157] op_sel_hi:[1,0,1]
	v_cvt_pk_bf16_f32 v190, v156, v157
	v_pk_fma_f32 v[198:199], v[156:157], v[156:157], v[198:199]
	v_lshlrev_b32_e32 v158, 16, v190
	v_and_b32_e32 v159, 0xffff0000, v190
	v_pk_add_f32 v[196:197], v[156:157], v[158:159] neg_lo:[0,1] neg_hi:[0,1]
	v_cvt_pk_bf16_f32 v194, v196, v197
	v_lshlrev_b32_e32 v156, 16, v191
	v_and_b32_e32 v157, 0xffff0000, v191
	v_lshlrev_b32_e32 v158, 16, v195
	v_and_b32_e32 v159, 0xffff0000, v195
	v_pk_add_f32 v[156:157], v[156:157], v[158:159]
	v_pk_fma_f32 v[156:157], v[36:37], 0.5, v[156:157] op_sel_hi:[1,0,1]
	v_cvt_pk_bf16_f32 v191, v156, v157
	v_pk_fma_f32 v[198:199], v[156:157], v[156:157], v[198:199]
	v_lshlrev_b32_e32 v158, 16, v191
	v_and_b32_e32 v159, 0xffff0000, v191
	v_pk_add_f32 v[196:197], v[156:157], v[158:159] neg_lo:[0,1] neg_hi:[0,1]
	v_cvt_pk_bf16_f32 v195, v196, v197
	global_store_dwordx4 v212, v[188:191], s[10:11] offset:256
	global_store_dwordx4 v212, v[192:195], s[6:7] offset:256
	v_add_f32_e32 v207, v198, v199
	s_waitcnt vmcnt(14)
; __device__ __forceinline__ unsigned pk2(float lo, float hi) { f32x2_t v = {lo, hi}; bf16x2_t b = __builtin_convertvector(v, bf16x2_t); return __builtin_bit_cast(unsigned, b); }
; __device__ __forceinline__ float bflo(unsigned u) { return __uint_as_float(u << 16); }
;     __device__ __forceinline__ void operator()(const f32x4 (&acc)[2][2][4][2], const Unit& u, int wr, int wc, int fr, int fq) const {
;     ...
;                 for (int bj = 0; bj < 2; ++bj) {
;                     const size_t off = (size_t)row * DM + col0 + bj * HALF;
;                     const u32x4 hh = *(const u32x4*)(HI + off), ll = *(const u32x4*)(LO + off);
;                     float hv[8] = {bflo(hh.x) + bflo(ll.x), bfhi(hh.x) + bfhi(ll.x), bflo(hh.y) + bflo(ll.y), bfhi(hh.y) + bfhi(ll.y),
;                                    bflo(hh.z) + bflo(ll.z), bfhi(hh.z) + bfhi(ll.z), bflo(hh.w) + bflo(ll.w), bfhi(hh.w) + bfhi(ll.w)};
;                     float av[8] = {acc[ai][bj][m][0][0], acc[ai][bj][m][0][1], acc[ai][bj][m][0][2], acc[ai][bj][m][0][3], acc[ai][bj][m][1][0], acc[ai][bj][m][1][1], acc[ai][bj][m][1][2], acc[ai][bj][m][1][3]};
;                     if (GATED) { const u32x4 pp = *(const u32x4*)(PP + off);
;                         const float pv[8] = {bflo(pp.x), bfhi(pp.x), bflo(pp.y), bfhi(pp.y), bflo(pp.z), bfhi(pp.z), bflo(pp.w), bfhi(pp.w)};
; #pragma unroll
;                         for (int e = 0; e < 8; ++e) av[e] = fast_sigmoid(av[e] * rs) * pv[e]; }
;                     else {
; #pragma unroll
;                         for (int e = 0; e < 8; ++e) av[e] *= alpha; }
;                     float lo[8];
; #pragma unroll
;                     for (int e = 0; e < 8; ++e) { hv[e] += av[e]; sq += hv[e] * hv[e]; }
;                     u32x4 wh; wh.x = pk2(hv[0], hv[1]); wh.y = pk2(hv[2], hv[3]); wh.z = pk2(hv[4], hv[5]); wh.w = pk2(hv[6], hv[7]);
;                     lo[0] = hv[0] - bflo(wh.x); lo[1] = hv[1] - bfhi(wh.x); lo[2] = hv[2] - bflo(wh.y); lo[3] = hv[3] - bfhi(wh.y);
;                     lo[4] = hv[4] - bflo(wh.z); lo[5] = hv[5] - bfhi(wh.z); lo[6] = hv[6] - bflo(wh.w); lo[7] = hv[7] - bfhi(wh.w);
;                     u32x4 wl; wl.x = pk2(lo[0], lo[1]); wl.y = pk2(lo[2], lo[3]); wl.z = pk2(lo[4], lo[5]); wl.w = pk2(lo[6], lo[7]);
;                     *(u32x4*)(HO + off) = wh; *(u32x4*)(LO + off) = wl;
;                 }
	v_lshlrev_b32_e32 v156, 16, v140
	v_and_b32_e32 v157, 0xffff0000, v140
	v_lshlrev_b32_e32 v158, 16, v144
	v_and_b32_e32 v159, 0xffff0000, v144
	v_pk_add_f32 v[156:157], v[156:157], v[158:159]
	v_pk_fma_f32 v[156:157], v[30:31], 0.5, v[156:157] op_sel_hi:[1,0,1]
	v_cvt_pk_bf16_f32 v140, v156, v157
	v_pk_mul_f32 v[198:199], v[156:157], v[156:157]
	v_lshlrev_b32_e32 v158, 16, v140
	v_and_b32_e32 v159, 0xffff0000, v140
	v_pk_add_f32 v[196:197], v[156:157], v[158:159] neg_lo:[0,1] neg_hi:[0,1]
	v_cvt_pk_bf16_f32 v144, v196, v197
	v_lshlrev_b32_e32 v156, 16, v141
	v_and_b32_e32 v157, 0xffff0000, v141
	v_lshlrev_b32_e32 v158, 16, v145
	v_and_b32_e32 v159, 0xffff0000, v145
	v_pk_add_f32 v[156:157], v[156:157], v[158:159]
	v_pk_fma_f32 v[156:157], v[32:33], 0.5, v[156:157] op_sel_hi:[1,0,1]
	v_cvt_pk_bf16_f32 v141, v156, v157
	v_pk_fma_f32 v[198:199], v[156:157], v[156:157], v[198:199]
	v_lshlrev_b32_e32 v158, 16, v141
	v_and_b32_e32 v159, 0xffff0000, v141
	v_pk_add_f32 v[196:197], v[156:157], v[158:159] neg_lo:[0,1] neg_hi:[0,1]
	v_cvt_pk_bf16_f32 v145, v196, v197
	v_lshlrev_b32_e32 v156, 16, v142
	v_and_b32_e32 v157, 0xffff0000, v142
	v_lshlrev_b32_e32 v158, 16, v146
	v_and_b32_e32 v159, 0xffff0000, v146
	v_pk_add_f32 v[156:157], v[156:157], v[158:159]
	v_pk_fma_f32 v[156:157], v[26:27], 0.5, v[156:157] op_sel_hi:[1,0,1]
	v_cvt_pk_bf16_f32 v142, v156, v157
	v_pk_fma_f32 v[198:199], v[156:157], v[156:157], v[198:199]
	v_lshlrev_b32_e32 v158, 16, v142
	v_and_b32_e32 v159, 0xffff0000, v142
	v_pk_add_f32 v[196:197], v[156:157], v[158:159] neg_lo:[0,1] neg_hi:[0,1]
	v_cvt_pk_bf16_f32 v146, v196, v197
	v_lshlrev_b32_e32 v156, 16, v143
	v_and_b32_e32 v157, 0xffff0000, v143
	v_lshlrev_b32_e32 v158, 16, v147
	v_and_b32_e32 v159, 0xffff0000, v147
	v_pk_add_f32 v[156:157], v[156:157], v[158:159]
	v_pk_fma_f32 v[156:157], v[28:29], 0.5, v[156:157] op_sel_hi:[1,0,1]
	v_cvt_pk_bf16_f32 v143, v156, v157
	v_pk_fma_f32 v[198:199], v[156:157], v[156:157], v[198:199]
	v_lshlrev_b32_e32 v158, 16, v143
	v_and_b32_e32 v159, 0xffff0000, v143
	v_pk_add_f32 v[196:197], v[156:157], v[158:159] neg_lo:[0,1] neg_hi:[0,1]
	v_cvt_pk_bf16_f32 v147, v196, v197
	global_store_dwordx4 v210, v[140:143], s[10:11]
	global_store_dwordx4 v210, v[144:147], s[6:7]
	s_waitcnt vmcnt(14)
	v_lshlrev_b32_e32 v156, 16, v148
	v_and_b32_e32 v157, 0xffff0000, v148
	v_lshlrev_b32_e32 v158, 16, v152
	v_and_b32_e32 v159, 0xffff0000, v152
	v_pk_add_f32 v[156:157], v[156:157], v[158:159]
	v_pk_fma_f32 v[156:157], v[22:23], 0.5, v[156:157] op_sel_hi:[1,0,1]
	v_cvt_pk_bf16_f32 v148, v156, v157
	v_pk_fma_f32 v[198:199], v[156:157], v[156:157], v[198:199]
	v_lshlrev_b32_e32 v158, 16, v148
	v_and_b32_e32 v159, 0xffff0000, v148
	v_pk_add_f32 v[196:197], v[156:157], v[158:159] neg_lo:[0,1] neg_hi:[0,1]
	v_cvt_pk_bf16_f32 v152, v196, v197
	v_lshlrev_b32_e32 v156, 16, v149
	v_and_b32_e32 v157, 0xffff0000, v149
	v_lshlrev_b32_e32 v158, 16, v153
	v_and_b32_e32 v159, 0xffff0000, v153
	v_pk_add_f32 v[156:157], v[156:157], v[158:159]
	v_pk_fma_f32 v[156:157], v[24:25], 0.5, v[156:157] op_sel_hi:[1,0,1]
	v_cvt_pk_bf16_f32 v149, v156, v157
	v_pk_fma_f32 v[198:199], v[156:157], v[156:157], v[198:199]
	v_lshlrev_b32_e32 v158, 16, v149
	v_and_b32_e32 v159, 0xffff0000, v149
	v_pk_add_f32 v[196:197], v[156:157], v[158:159] neg_lo:[0,1] neg_hi:[0,1]
	v_cvt_pk_bf16_f32 v153, v196, v197
	v_lshlrev_b32_e32 v156, 16, v150
	v_and_b32_e32 v157, 0xffff0000, v150
	v_lshlrev_b32_e32 v158, 16, v154
	v_and_b32_e32 v159, 0xffff0000, v154
	v_pk_add_f32 v[156:157], v[156:157], v[158:159]
	v_pk_fma_f32 v[156:157], v[18:19], 0.5, v[156:157] op_sel_hi:[1,0,1]
	v_cvt_pk_bf16_f32 v150, v156, v157
	v_pk_fma_f32 v[198:199], v[156:157], v[156:157], v[198:199]
	v_lshlrev_b32_e32 v158, 16, v150
	v_and_b32_e32 v159, 0xffff0000, v150
	v_pk_add_f32 v[196:197], v[156:157], v[158:159] neg_lo:[0,1] neg_hi:[0,1]
	v_cvt_pk_bf16_f32 v154, v196, v197
	v_lshlrev_b32_e32 v156, 16, v151
	v_and_b32_e32 v157, 0xffff0000, v151
	v_lshlrev_b32_e32 v158, 16, v155
	v_and_b32_e32 v159, 0xffff0000, v155
	v_pk_add_f32 v[156:157], v[156:157], v[158:159]
	v_pk_fma_f32 v[156:157], v[20:21], 0.5, v[156:157] op_sel_hi:[1,0,1]
	v_cvt_pk_bf16_f32 v151, v156, v157
	v_pk_fma_f32 v[198:199], v[156:157], v[156:157], v[198:199]
	v_lshlrev_b32_e32 v158, 16, v151
	v_and_b32_e32 v159, 0xffff0000, v151
	v_pk_add_f32 v[196:197], v[156:157], v[158:159] neg_lo:[0,1] neg_hi:[0,1]
	v_cvt_pk_bf16_f32 v155, v196, v197
	global_store_dwordx4 v210, v[148:151], s[10:11] offset:256
	global_store_dwordx4 v210, v[152:155], s[6:7] offset:256
	v_add_f32_e32 v208, v198, v199
	s_waitcnt vmcnt(10)
; __device__ __forceinline__ float bflo(unsigned u) { return __uint_as_float(u << 16); }
;     __device__ __forceinline__ void operator()(const f32x4 (&acc)[2][2][4][2], const Unit& u, int wr, int wc, int fr, int fq) const {
;     ...
;                 for (int bj = 0; bj < 2; ++bj) {
;                     const size_t off = (size_t)row * DM + col0 + bj * HALF;
;                     const u32x4 hh = *(const u32x4*)(HI + off), ll = *(const u32x4*)(LO + off);
;                     float hv[8] = {bflo(hh.x) + bflo(ll.x), bfhi(hh.x) + bfhi(ll.x), bflo(hh.y) + bflo(ll.y), bfhi(hh.y) + bfhi(ll.y),
;                                    bflo(hh.z) + bflo(ll.z), bfhi(hh.z) + bfhi(ll.z), bflo(hh.w) + bflo(ll.w), bfhi(hh.w) + bfhi(ll.w)};
;                     float av[8] = {acc[ai][bj][m][0][0], acc[ai][bj][m][0][1], acc[ai][bj][m][0][2], acc[ai][bj][m][0][3], acc[ai][bj][m][1][0], acc[ai][bj][m][1][1], acc[ai][bj][m][1][2], acc[ai][bj][m][1][3]};
;                     if (GATED) { const u32x4 pp = *(const u32x4*)(PP + off);
;                         const float pv[8] = {bflo(pp.x), bfhi(pp.x), bflo(pp.y), bfhi(pp.y), bflo(pp.z), bfhi(pp.z), bflo(pp.w), bfhi(pp.w)};
; #pragma unroll
;                         for (int e = 0; e < 8; ++e) av[e] = fast_sigmoid(av[e] * rs) * pv[e]; }
;                     else {
; #pragma unroll
;                         for (int e = 0; e < 8; ++e) av[e] *= alpha; }
;                     float lo[8];
; #pragma unroll
;                     for (int e = 0; e < 8; ++e) { hv[e] += av[e]; sq += hv[e] * hv[e]; }
;                     u32x4 wh; wh.x = pk2(hv[0], hv[1]); wh.y = pk2(hv[2], hv[3]); wh.z = pk2(hv[4], hv[5]); wh.w = pk2(hv[6], hv[7]);
;                     lo[0] = hv[0] - bflo(wh.x); lo[1] = hv[1] - bfhi(wh.x); lo[2] = hv[2] - bflo(wh.y); lo[3] = hv[3] - bfhi(wh.y);
;                     lo[4] = hv[4] - bflo(wh.z); lo[5] = hv[5] - bfhi(wh.z); lo[6] = hv[6] - bflo(wh.w); lo[7] = hv[7] - bfhi(wh.w);
;                     u32x4 wl; wl.x = pk2(lo[0], lo[1]); wl.y = pk2(lo[2], lo[3]); wl.z = pk2(lo[4], lo[5]); wl.w = pk2(lo[6], lo[7]);
;                     *(u32x4*)(HO + off) = wh; *(u32x4*)(LO + off) = wl;
;                 }
;                 sq += __shfl_xor(sq, 16); sq += __shfl_xor(sq, 32);
;                 if (fq == 0) ssq_out[(size_t)row * 16 + 4 * u.pn + wc] = sq;
	v_lshlrev_b32_e32 v156, 16, v164
	v_and_b32_e32 v157, 0xffff0000, v164
	v_lshlrev_b32_e32 v158, 16, v168
	v_and_b32_e32 v159, 0xffff0000, v168
	v_pk_add_f32 v[156:157], v[156:157], v[158:159]
	v_pk_fma_f32 v[156:157], v[14:15], 0.5, v[156:157] op_sel_hi:[1,0,1]
	v_cvt_pk_bf16_f32 v164, v156, v157
	v_pk_mul_f32 v[198:199], v[156:157], v[156:157]
	v_lshlrev_b32_e32 v158, 16, v164
	v_and_b32_e32 v159, 0xffff0000, v164
	v_pk_add_f32 v[196:197], v[156:157], v[158:159] neg_lo:[0,1] neg_hi:[0,1]
	v_cvt_pk_bf16_f32 v168, v196, v197
	v_lshlrev_b32_e32 v156, 16, v165
	v_and_b32_e32 v157, 0xffff0000, v165
	v_lshlrev_b32_e32 v158, 16, v169
	v_and_b32_e32 v159, 0xffff0000, v169
	v_pk_add_f32 v[156:157], v[156:157], v[158:159]
	v_pk_fma_f32 v[156:157], v[16:17], 0.5, v[156:157] op_sel_hi:[1,0,1]
	v_cvt_pk_bf16_f32 v165, v156, v157
	v_pk_fma_f32 v[198:199], v[156:157], v[156:157], v[198:199]
	v_lshlrev_b32_e32 v158, 16, v165
	v_and_b32_e32 v159, 0xffff0000, v165
	v_pk_add_f32 v[196:197], v[156:157], v[158:159] neg_lo:[0,1] neg_hi:[0,1]
	v_cvt_pk_bf16_f32 v169, v196, v197
	v_lshlrev_b32_e32 v156, 16, v166
	v_and_b32_e32 v157, 0xffff0000, v166
	v_lshlrev_b32_e32 v158, 16, v170
	v_and_b32_e32 v159, 0xffff0000, v170
	v_pk_add_f32 v[156:157], v[156:157], v[158:159]
	v_pk_fma_f32 v[156:157], v[10:11], 0.5, v[156:157] op_sel_hi:[1,0,1]
	v_cvt_pk_bf16_f32 v166, v156, v157
	v_pk_fma_f32 v[198:199], v[156:157], v[156:157], v[198:199]
	v_lshlrev_b32_e32 v158, 16, v166
	v_and_b32_e32 v159, 0xffff0000, v166
	v_pk_add_f32 v[196:197], v[156:157], v[158:159] neg_lo:[0,1] neg_hi:[0,1]
	v_cvt_pk_bf16_f32 v170, v196, v197
	v_lshlrev_b32_e32 v156, 16, v167
	v_and_b32_e32 v157, 0xffff0000, v167
	v_lshlrev_b32_e32 v158, 16, v171
	v_and_b32_e32 v159, 0xffff0000, v171
	v_pk_add_f32 v[156:157], v[156:157], v[158:159]
	v_pk_fma_f32 v[156:157], v[12:13], 0.5, v[156:157] op_sel_hi:[1,0,1]
	v_cvt_pk_bf16_f32 v167, v156, v157
	v_pk_fma_f32 v[198:199], v[156:157], v[156:157], v[198:199]
	v_lshlrev_b32_e32 v158, 16, v167
	v_and_b32_e32 v159, 0xffff0000, v167
	v_pk_add_f32 v[196:197], v[156:157], v[158:159] neg_lo:[0,1] neg_hi:[0,1]
	v_cvt_pk_bf16_f32 v171, v196, v197
	global_store_dwordx4 v211, v[164:167], s[10:11]
	global_store_dwordx4 v211, v[168:171], s[6:7]
	s_waitcnt vmcnt(10)
	v_lshlrev_b32_e32 v156, 16, v172
	v_and_b32_e32 v157, 0xffff0000, v172
	v_lshlrev_b32_e32 v158, 16, v176
	v_and_b32_e32 v159, 0xffff0000, v176
	v_pk_add_f32 v[156:157], v[156:157], v[158:159]
	v_pk_fma_f32 v[156:157], v[6:7], 0.5, v[156:157] op_sel_hi:[1,0,1]
	v_cvt_pk_bf16_f32 v172, v156, v157
	v_pk_fma_f32 v[198:199], v[156:157], v[156:157], v[198:199]
	v_lshlrev_b32_e32 v158, 16, v172
	v_and_b32_e32 v159, 0xffff0000, v172
	v_pk_add_f32 v[196:197], v[156:157], v[158:159] neg_lo:[0,1] neg_hi:[0,1]
	v_cvt_pk_bf16_f32 v176, v196, v197
	v_lshlrev_b32_e32 v156, 16, v173
	v_and_b32_e32 v157, 0xffff0000, v173
	v_lshlrev_b32_e32 v158, 16, v177
	v_and_b32_e32 v159, 0xffff0000, v177
	v_pk_add_f32 v[156:157], v[156:157], v[158:159]
	v_pk_fma_f32 v[156:157], v[8:9], 0.5, v[156:157] op_sel_hi:[1,0,1]
	v_cvt_pk_bf16_f32 v173, v156, v157
	v_pk_fma_f32 v[198:199], v[156:157], v[156:157], v[198:199]
	v_lshlrev_b32_e32 v158, 16, v173
	v_and_b32_e32 v159, 0xffff0000, v173
	v_pk_add_f32 v[196:197], v[156:157], v[158:159] neg_lo:[0,1] neg_hi:[0,1]
	v_cvt_pk_bf16_f32 v177, v196, v197
	v_lshlrev_b32_e32 v156, 16, v174
	v_and_b32_e32 v157, 0xffff0000, v174
	v_lshlrev_b32_e32 v158, 16, v178
	v_and_b32_e32 v159, 0xffff0000, v178
	v_pk_add_f32 v[156:157], v[156:157], v[158:159]
	v_pk_fma_f32 v[156:157], v[2:3], 0.5, v[156:157] op_sel_hi:[1,0,1]
	v_cvt_pk_bf16_f32 v174, v156, v157
	v_pk_fma_f32 v[198:199], v[156:157], v[156:157], v[198:199]
	v_lshlrev_b32_e32 v158, 16, v174
	v_and_b32_e32 v159, 0xffff0000, v174
	v_pk_add_f32 v[196:197], v[156:157], v[158:159] neg_lo:[0,1] neg_hi:[0,1]
	v_cvt_pk_bf16_f32 v178, v196, v197
	v_lshlrev_b32_e32 v156, 16, v175
	v_and_b32_e32 v157, 0xffff0000, v175
	v_lshlrev_b32_e32 v158, 16, v179
	v_and_b32_e32 v159, 0xffff0000, v179
	v_pk_add_f32 v[156:157], v[156:157], v[158:159]
	v_pk_fma_f32 v[156:157], v[4:5], 0.5, v[156:157] op_sel_hi:[1,0,1]
	v_cvt_pk_bf16_f32 v175, v156, v157
	v_pk_fma_f32 v[198:199], v[156:157], v[156:157], v[198:199]
	v_lshlrev_b32_e32 v158, 16, v175
	v_and_b32_e32 v159, 0xffff0000, v175
	v_pk_add_f32 v[196:197], v[156:157], v[158:159] neg_lo:[0,1] neg_hi:[0,1]
	v_cvt_pk_bf16_f32 v179, v196, v197
	global_store_dwordx4 v211, v[172:175], s[10:11] offset:256
	global_store_dwordx4 v211, v[176:179], s[6:7] offset:256
	v_add_f32_e32 v209, v198, v199
	v_mov_b32_e32 v140, v200
	s_nop 1
	v_permlane16_swap_b32_e32 v200, v140
	v_mov_b32_e32 v141, v201
	s_nop 1
	v_permlane16_swap_b32_e32 v201, v141
	v_mov_b32_e32 v142, v202
	s_nop 1
	v_permlane16_swap_b32_e32 v202, v142
	v_mov_b32_e32 v143, v203
	s_nop 1
	v_permlane16_swap_b32_e32 v203, v143
	v_mov_b32_e32 v144, v206
	s_nop 1
	v_permlane16_swap_b32_e32 v206, v144
	v_mov_b32_e32 v145, v207
	s_nop 1
	v_permlane16_swap_b32_e32 v207, v145
	v_mov_b32_e32 v146, v208
	s_nop 1
	v_permlane16_swap_b32_e32 v208, v146
	v_mov_b32_e32 v147, v209
	s_nop 1
	v_permlane16_swap_b32_e32 v209, v147
	v_readlane_b32 s50, v250, 39
	v_readlane_b32 s51, v250, 40
	s_waitcnt lgkmcnt(0)
	v_add_f32_e32 v200, v200, v140
	v_add_f32_e32 v201, v201, v141
	v_add_f32_e32 v202, v202, v142
	v_add_f32_e32 v203, v203, v143
	v_add_f32_e32 v206, v206, v144
	v_add_f32_e32 v207, v207, v145
	v_add_f32_e32 v208, v208, v146
	v_add_f32_e32 v209, v209, v147
	v_mov_b32_e32 v140, v200
	s_nop 1
	v_permlane32_swap_b32_e32 v200, v140
	v_mov_b32_e32 v141, v201
	s_nop 1
	v_permlane32_swap_b32_e32 v201, v141
	v_mov_b32_e32 v142, v202
	s_nop 1
	v_permlane32_swap_b32_e32 v202, v142
	v_mov_b32_e32 v143, v203
	s_nop 1
	v_permlane32_swap_b32_e32 v203, v143
	v_mov_b32_e32 v144, v206
	s_nop 1
	v_permlane32_swap_b32_e32 v206, v144
	v_mov_b32_e32 v145, v207
	s_nop 1
	v_permlane32_swap_b32_e32 v207, v145
	v_mov_b32_e32 v146, v208
	s_nop 1
	v_permlane32_swap_b32_e32 v208, v146
	v_mov_b32_e32 v147, v209
	s_nop 1
	v_permlane32_swap_b32_e32 v209, v147
	s_waitcnt lgkmcnt(0)
	v_add_f32_e32 v200, v200, v140
	v_add_f32_e32 v201, v201, v141
	v_add_f32_e32 v202, v202, v142
	v_add_f32_e32 v203, v203, v143
	v_add_f32_e32 v206, v206, v144
	v_add_f32_e32 v207, v207, v145
	v_add_f32_e32 v208, v208, v146
	v_add_f32_e32 v209, v209, v147
	s_and_saveexec_b64 s[12:13], s[42:43]
	s_cbranch_execz .Lepir_f2d_skip
	global_store_dword v216, v200, s[50:51]
	global_store_dword v216, v201, s[50:51] offset:1024
	global_store_dword v216, v202, s[50:51] offset:2048
	global_store_dword v216, v203, s[50:51] offset:3072
	global_store_dword v217, v206, s[50:51]
	global_store_dword v217, v207, s[50:51] offset:1024
	global_store_dword v217, v208, s[50:51] offset:2048
	global_store_dword v217, v209, s[50:51] offset:3072
